# adds: residual-row loads of the x+acc epilogues (xo, ff2, out-proj) issued before the tile's LDS round trip instead of one exposed load per chunk
# speedup vs baseline: 1.0108x; 1.0008x over previous
; #define MFMA(a, b, c) __builtin_amdgcn_mfma_f32_32x32x16_bf16((a), (b), (c), 0, 0, 0)
; template <int TM, int TN>
; DI void gemm_mainloop(const u16* __restrict__ A, long lda, const u16* __restrict__ Bt, long ldb, int K, char* smem,
;                       f32x16 (&acc)[TM][TN]) {
;     ...
;   for (int kt = 0; kt < nk; kt++) {
;     const int buf = kt & 1;
;     const u16* cA = sA + buf * BM * LD + (wm * 32 * TM + r) * LD + h * 8;
;     const u16* cB = sB + buf * BN * LD + (wn * 32 * TN + r) * LD + h * 8;
;     bf16x8 af[TM], bfr[TN];
; #pragma unroll
;     for (int tm = 0; tm < TM; tm++) af[tm] = *(const bf16x8*)(cA + tm * 32 * LD);
; #pragma unroll
;     for (int tn = 0; tn < TN; tn++) bfr[tn] = *(const bf16x8*)(cB + tn * 32 * LD);
;     if (kt + 1 < nk) GEMM_SSTORE(buf ^ 1)
;     __builtin_amdgcn_sched_barrier(0);
;     __builtin_amdgcn_s_setprio(1);
; #pragma unroll
;     for (int tm = 0; tm < TM; tm++)
; #pragma unroll
;       for (int tn = 0; tn < TN; tn++) acc[tm][tn] = MFMA(af[tm], bfr[tn], acc[tm][tn]);
; #pragma unroll
;     for (int tm = 0; tm < TM; tm++) af[tm] = *(const bf16x8*)(cA + tm * 32 * LD + 16);
; #pragma unroll
;     for (int tn = 0; tn < TN; tn++) bfr[tn] = *(const bf16x8*)(cB + tn * 32 * LD + 16);
; #pragma unroll
;     for (int tm = 0; tm < TM; tm++)
; #pragma unroll
;       for (int tn = 0; tn < TN; tn++) acc[tm][tn] = MFMA(af[tm], bfr[tn], acc[tm][tn]);
;     __builtin_amdgcn_sched_group_barrier(0x8, 4, 0);
;     if (kt + 2 < nk) GEMM_GLOAD((kt + 2) * 64)
; #pragma unroll
;     for (int ks = 2; ks < 4; ks++) {
; #pragma unroll
;       for (int tm = 0; tm < TM; tm++) af[tm] = *(const bf16x8*)(cA + tm * 32 * LD + ks * 16);
; #pragma unroll
;       for (int tn = 0; tn < TN; tn++) bfr[tn] = *(const bf16x8*)(cB + tn * 32 * LD + ks * 16);
; #pragma unroll
;       for (int tm = 0; tm < TM; tm++)
; #pragma unroll
;         for (int tn = 0; tn < TN; tn++) acc[tm][tn] = MFMA(af[tm], bfr[tn], acc[tm][tn]);
;     }
;     __builtin_amdgcn_s_setprio(0);
;     __syncthreads();
;   }
.LBB0_1215:
	s_and_b32 s5, s4, 1
	s_mul_i32 s39, s5, 0x4800
	v_add_u32_e32 v109, s39, v102
	v_add_u32_e32 v126, s39, v98
	s_lshl_b32 s5, s5, 7
	ds_read_b128 v[110:113], v109
	ds_read_b128 v[114:117], v109 offset:4608
	ds_read_b128 v[118:121], v126 offset:36864
	ds_read_b128 v[122:125], v126 offset:41472
	s_xor_b32 s5, s5, 0x80
	s_mulk_i32 s5, 0x90
	s_add_i32 s4, s4, 1
	v_add_u32_e32 v127, s5, v108
	s_waitcnt vmcnt(7)
	ds_write_b128 v127, v[70:73]
	s_waitcnt vmcnt(6)
	ds_write_b128 v127, v[74:77] offset:4608
	s_waitcnt vmcnt(5)
	ds_write_b128 v127, v[66:69] offset:9216
	s_waitcnt vmcnt(4)
	ds_write_b128 v127, v[78:81] offset:13824
	s_waitcnt vmcnt(3)
	ds_write_b128 v127, v[82:85] offset:36864
	s_waitcnt vmcnt(2)
	ds_write_b128 v127, v[86:89] offset:41472
	s_waitcnt vmcnt(1)
	ds_write_b128 v127, v[90:93] offset:46080
	s_waitcnt vmcnt(0)
	ds_write_b128 v127, v[94:97] offset:50688
	s_setprio 1
	ds_read_b128 v[66:69], v109 offset:32
	s_waitcnt lgkmcnt(10)
	v_mfma_f32_32x32x16_bf16 v[50:65], v[110:113], v[118:121], v[50:65]
	ds_read_b128 v[70:73], v126 offset:36896
	ds_read_b128 v[74:77], v126 offset:41504
	ds_read_b128 v[86:89], v109 offset:4672
	ds_read_b128 v[78:81], v126 offset:36928
	ds_read_b128 v[82:85], v126 offset:41536
	v_lshl_add_u64 v[90:91], v[106:107], 0, s[16:17]
	ds_read_b128 v[94:97], v126 offset:36960
	s_waitcnt lgkmcnt(14)
	v_mfma_f32_32x32x16_bf16 v[34:49], v[110:113], v[122:125], v[34:49]
	ds_read_b128 v[110:113], v126 offset:41568
	s_waitcnt lgkmcnt(6)
	v_mfma_f32_32x32x16_bf16 v[50:65], v[66:69], v[70:73], v[50:65]
	s_waitcnt lgkmcnt(5)
	v_mfma_f32_32x32x16_bf16 v[34:49], v[66:69], v[74:77], v[34:49]
	ds_read_b128 v[66:69], v109 offset:4640
	v_mfma_f32_32x32x16_bf16 v[18:33], v[114:117], v[118:121], v[18:33]
	v_lshl_add_u64 v[118:119], v[104:105], 0, s[16:17]
	v_mfma_f32_32x32x16_bf16 v[2:17], v[114:117], v[122:125], v[2:17]
	ds_read_b128 v[114:117], v109 offset:4704
	s_waitcnt lgkmcnt(1)
	v_mfma_f32_32x32x16_bf16 v[18:33], v[66:69], v[70:73], v[18:33]
	global_load_dwordx4 v[70:73], v[90:91], off offset:256
	v_mfma_f32_32x32x16_bf16 v[2:17], v[66:69], v[74:77], v[2:17]
	ds_read_b128 v[66:69], v109 offset:64
	v_add_co_u32_e32 v74, vcc, s23, v90
	s_nop 1
	v_addc_co_u32_e32 v75, vcc, 0, v91, vcc
	global_load_dwordx4 v[74:77], v[74:75], off offset:256
	s_waitcnt lgkmcnt(0)
	v_mfma_f32_32x32x16_bf16 v[50:65], v[66:69], v[78:81], v[50:65]
	v_mfma_f32_32x32x16_bf16 v[34:49], v[66:69], v[82:85], v[34:49]
	v_add_co_u32_e32 v66, vcc, s24, v90
	s_nop 1
	v_addc_co_u32_e32 v67, vcc, 0, v91, vcc
	global_load_dwordx4 v[66:69], v[66:67], off offset:256
	v_mfma_f32_32x32x16_bf16 v[18:33], v[86:89], v[78:81], v[18:33]
	v_add_co_u32_e32 v78, vcc, s25, v90
	s_nop 1
	v_addc_co_u32_e32 v79, vcc, 0, v91, vcc
	ds_read_b128 v[90:93], v109 offset:96
	global_load_dwordx4 v[78:81], v[78:79], off offset:256
	v_mfma_f32_32x32x16_bf16 v[2:17], v[86:89], v[82:85], v[2:17]
	v_add_co_u32_e32 v82, vcc, s28, v118
	s_nop 1
	v_addc_co_u32_e32 v83, vcc, 0, v119, vcc
	v_add_co_u32_e32 v86, vcc, s29, v118
	global_load_dwordx4 v[82:85], v[82:83], off offset:256
	s_nop 0
	v_addc_co_u32_e32 v87, vcc, 0, v119, vcc
	v_add_co_u32_e32 v120, vcc, s30, v118
	s_waitcnt lgkmcnt(0)
	v_mfma_f32_32x32x16_bf16 v[50:65], v[90:93], v[94:97], v[50:65]
	v_addc_co_u32_e32 v121, vcc, 0, v119, vcc
	v_add_co_u32_e32 v118, vcc, s31, v118
	global_load_dwordx4 v[86:89], v[86:87], off offset:256
	s_nop 0
	v_addc_co_u32_e32 v119, vcc, 0, v119, vcc
	v_mfma_f32_32x32x16_bf16 v[34:49], v[90:93], v[110:113], v[34:49]
	global_load_dwordx4 v[90:93], v[120:121], off offset:256
	v_mfma_f32_32x32x16_bf16 v[18:33], v[114:117], v[94:97], v[18:33]
	global_load_dwordx4 v[94:97], v[118:119], off offset:256
	v_mfma_f32_32x32x16_bf16 v[2:17], v[114:117], v[110:113], v[2:17]
	s_setprio 0
	s_add_u32 s16, s16, 0x80
	s_addc_u32 s17, s17, 0
	s_cmpk_eq_i32 s16, 0x700
	s_barrier
	s_cbranch_scc0 .LBB0_1215
	ds_read_b128 v[104:107], v102
	ds_read_b128 v[110:113], v102 offset:4608
	ds_read_b128 v[114:117], v98 offset:36864
	ds_read_b128 v[118:121], v98 offset:41472
	s_waitcnt vmcnt(7)
	ds_write_b128 v108, v[70:73] offset:18432
	s_waitcnt vmcnt(6)
	ds_write_b128 v108, v[74:77] offset:23040
	s_waitcnt vmcnt(5)
	ds_write_b128 v108, v[66:69] offset:27648
	s_waitcnt vmcnt(4)
	ds_write_b128 v108, v[78:81] offset:32256
	s_waitcnt vmcnt(3)
	ds_write_b128 v108, v[82:85] offset:55296
	s_waitcnt vmcnt(2)
	ds_write_b128 v108, v[86:89] offset:59904
	s_waitcnt vmcnt(1)
	ds_write_b128 v108, v[90:93] offset:64512
	s_waitcnt vmcnt(0)
	ds_write_b128 v103, v[94:97] offset:32256
	s_setprio 1
	ds_read_b128 v[66:69], v102 offset:32
	s_waitcnt lgkmcnt(10)
	v_mfma_f32_32x32x16_bf16 v[50:65], v[104:107], v[114:117], v[50:65]
	ds_read_b128 v[70:73], v98 offset:36896
	ds_read_b128 v[74:77], v98 offset:41504
	s_waitcnt lgkmcnt(11)
	v_mfma_f32_32x32x16_bf16 v[34:49], v[104:107], v[118:121], v[34:49]
	s_waitcnt lgkmcnt(1)
	v_mfma_f32_32x32x16_bf16 v[50:65], v[66:69], v[70:73], v[50:65]
	s_waitcnt lgkmcnt(0)
	v_mfma_f32_32x32x16_bf16 v[34:49], v[66:69], v[74:77], v[34:49]
	ds_read_b128 v[66:69], v102 offset:4640
	v_mfma_f32_32x32x16_bf16 v[18:33], v[110:113], v[114:117], v[18:33]
	v_mfma_f32_32x32x16_bf16 v[2:17], v[110:113], v[118:121], v[2:17]
	s_waitcnt lgkmcnt(0)
	v_mfma_f32_32x32x16_bf16 v[18:33], v[66:69], v[70:73], v[18:33]
	ds_read_b128 v[70:73], v98 offset:36928
	v_mfma_f32_32x32x16_bf16 v[2:17], v[66:69], v[74:77], v[2:17]
	ds_read_b128 v[66:69], v102 offset:64
	ds_read_b128 v[74:77], v98 offset:41536
	s_waitcnt lgkmcnt(1)
	v_mfma_f32_32x32x16_bf16 v[50:65], v[66:69], v[70:73], v[50:65]
	s_waitcnt lgkmcnt(0)
	v_mfma_f32_32x32x16_bf16 v[34:49], v[66:69], v[74:77], v[34:49]
	ds_read_b128 v[66:69], v102 offset:4672
	s_waitcnt lgkmcnt(0)
	v_mfma_f32_32x32x16_bf16 v[18:33], v[66:69], v[70:73], v[18:33]
	ds_read_b128 v[70:73], v98 offset:36960
	v_mfma_f32_32x32x16_bf16 v[2:17], v[66:69], v[74:77], v[2:17]
	ds_read_b128 v[66:69], v102 offset:96
	ds_read_b128 v[74:77], v98 offset:41568
	s_waitcnt lgkmcnt(1)
	v_mfma_f32_32x32x16_bf16 v[50:65], v[66:69], v[70:73], v[50:65]
	s_waitcnt lgkmcnt(0)
	v_mfma_f32_32x32x16_bf16 v[34:49], v[66:69], v[74:77], v[34:49]
	ds_read_b128 v[66:69], v102 offset:4704
	s_waitcnt lgkmcnt(0)
	v_mfma_f32_32x32x16_bf16 v[2:17], v[66:69], v[74:77], v[2:17]
	v_mfma_f32_32x32x16_bf16 v[18:33], v[66:69], v[70:73], v[18:33]
	s_setprio 0
	s_barrier
; DI int crow(int i, int h) { return (i & 3) + 8 * (i >> 2) + 4 * h; }
; template <int TM, int TN, class Epi>
; DI void gemm_tile(const u16* A, long lda, const u16* Bt, long ldb, int K, int m0, int n0, char* smem, const Epi& epi) {
;     ...
; #pragma unroll
;   for (int tm = 0; tm < TM; tm++)
; #pragma unroll
;     for (int tn = 0; tn < TN; tn++)
; #pragma unroll
;       for (int i = 0; i < 16; i++)
;         Ct[(wm * 32 * TM + tm * 32 + crow(i, h)) * LDC + wn * 32 * TN + tn * 32 + r] = acc[tm][tn][i];
;   __syncthreads();
;   DI void operator()(const float* Ct, int ldc, int m0, int n0, int tid, int bm) const {
;     ...
;       int id = tid + 256 * it; int row = id >> 4, c8 = (id & 15) * 8;
;       int m = m0 + row;
;       const float* c = Ct + row * ldc + c8;
;       float4 a = *(const float4*)c, b = *(const float4*)(c + 4);
;       float x[8];
;       if (srcb != nullptr) {
;         unpack8(*(const uint4*)(srcb + (size_t)m * LDA + n0 + c8), x);
	ds_read_b128 v[66:69], v102 offset:18432
	ds_read_b128 v[70:73], v102 offset:23040
	ds_read_b128 v[74:77], v98 offset:55296
	ds_read_b128 v[78:81], v98 offset:59904
	s_setprio 1
	s_waitcnt lgkmcnt(1)
	v_mfma_f32_32x32x16_bf16 v[50:65], v[66:69], v[74:77], v[50:65]
	s_waitcnt lgkmcnt(0)
	v_mfma_f32_32x32x16_bf16 v[34:49], v[66:69], v[78:81], v[34:49]
	ds_read_b128 v[66:69], v102 offset:18464
	v_mfma_f32_32x32x16_bf16 v[18:33], v[70:73], v[74:77], v[18:33]
	ds_read_b128 v[74:77], v98 offset:59936
	v_mfma_f32_32x32x16_bf16 v[2:17], v[70:73], v[78:81], v[2:17]
	ds_read_b128 v[70:73], v98 offset:55328
	s_waitcnt lgkmcnt(0)
	v_mfma_f32_32x32x16_bf16 v[50:65], v[66:69], v[70:73], v[50:65]
	v_mfma_f32_32x32x16_bf16 v[34:49], v[66:69], v[74:77], v[34:49]
	ds_read_b128 v[66:69], v102 offset:23072
	s_waitcnt lgkmcnt(0)
	v_mfma_f32_32x32x16_bf16 v[18:33], v[66:69], v[70:73], v[18:33]
	ds_read_b128 v[70:73], v98 offset:55360
	v_mfma_f32_32x32x16_bf16 v[2:17], v[66:69], v[74:77], v[2:17]
	ds_read_b128 v[66:69], v102 offset:18496
	ds_read_b128 v[74:77], v98 offset:59968
	s_waitcnt lgkmcnt(1)
	v_mfma_f32_32x32x16_bf16 v[50:65], v[66:69], v[70:73], v[50:65]
	s_waitcnt lgkmcnt(0)
	v_mfma_f32_32x32x16_bf16 v[34:49], v[66:69], v[74:77], v[34:49]
	ds_read_b128 v[66:69], v102 offset:23104
	s_waitcnt lgkmcnt(0)
	v_mfma_f32_32x32x16_bf16 v[18:33], v[66:69], v[70:73], v[18:33]
	ds_read_b128 v[70:73], v98 offset:55392
	v_mfma_f32_32x32x16_bf16 v[2:17], v[66:69], v[74:77], v[2:17]
	ds_read_b128 v[66:69], v102 offset:18528
	ds_read_b128 v[74:77], v98 offset:60000
	s_waitcnt lgkmcnt(1)
	v_mfma_f32_32x32x16_bf16 v[50:65], v[66:69], v[70:73], v[50:65]
	s_waitcnt lgkmcnt(0)
	v_mfma_f32_32x32x16_bf16 v[34:49], v[66:69], v[74:77], v[34:49]
	ds_read_b128 v[66:69], v102 offset:23136
	s_waitcnt lgkmcnt(0)
	v_mfma_f32_32x32x16_bf16 v[2:17], v[66:69], v[74:77], v[2:17]
	v_mfma_f32_32x32x16_bf16 v[18:33], v[66:69], v[70:73], v[18:33]
	s_setprio 0
	v_mov_b32_e32 v66, v0
	s_barrier
	s_mov_b32 s4, 0
	v_lshrrev_b32_e32 v67, 1, v66
	v_and_b32_e32 v67, 0xfffffc0, v67
	v_lshrrev_b32_e32 v68, 3, v66
	v_and_or_b32 v67, v68, 4, v67
	v_and_b32_e32 v68, 0x5f, v66
	v_mul_lo_u32 v67, v67, s36
	v_lshl_add_u32 v67, v68, 2, v67
	ds_write2_b32 v67, v50, v34 offset1:32
	v_add_u32_e32 v34, 0x400, v67
	ds_write2_b32 v34, v52, v36 offset0:8 offset1:40
	ds_write2_b32 v34, v53, v37 offset0:140 offset1:172
	v_add_u32_e32 v34, 0x1000, v67
	ds_write2_b32 v34, v54, v38 offset0:32 offset1:64
	ds_write2_b32 v34, v55, v39 offset0:164 offset1:196
	v_add_u32_e32 v34, 0x1400, v67
	ds_write2_b32 v34, v56, v40 offset0:40 offset1:72
	ds_write2_b32 v34, v57, v41 offset0:172 offset1:204
	v_add_u32_e32 v34, 0x2000, v67
	ds_write2_b32 v34, v58, v42 offset0:64 offset1:96
	ds_write2_b32 v34, v59, v43 offset0:196 offset1:228
	v_add_u32_e32 v34, 0x2400, v67
	ds_write2_b32 v34, v60, v44 offset0:72 offset1:104
	ds_write2_b32 v34, v61, v45 offset0:204 offset1:236
	v_add_u32_e32 v34, 0x3000, v67
	ds_write2_b32 v34, v62, v46 offset0:96 offset1:128
	v_add_u32_e32 v34, 0x3200, v67
	ds_write2_b32 v34, v63, v47 offset0:100 offset1:132
	v_add_u32_e32 v34, 0x3400, v67
	ds_write2_b32 v34, v64, v48 offset0:104 offset1:136
	v_add_u32_e32 v34, 0x3600, v67
	ds_write2_b32 v34, v65, v49 offset0:108 offset1:140
	v_add_u32_e32 v34, 0x4000, v67
	ds_write2_b32 v34, v18, v2 offset0:128 offset1:160
	v_add_u32_e32 v2, 0x4400, v67
	ds_write2_b32 v2, v19, v3 offset0:4 offset1:36
	ds_write2_b32 v2, v20, v4 offset0:136 offset1:168
	v_add_u32_e32 v2, 0x4800, v67
	ds_write2_b32 v2, v21, v5 offset0:12 offset1:44
	v_add_u32_e32 v2, 0x5000, v67
	ds_write2_b32 v2, v22, v6 offset0:160 offset1:192
	v_add_u32_e32 v2, 0x5400, v67
	ds_write2_b32 v2, v23, v7 offset0:36 offset1:68
	ds_write2_b32 v2, v24, v8 offset0:168 offset1:200
	v_add_u32_e32 v2, 0x5800, v67
	ds_write2_b32 v2, v25, v9 offset0:44 offset1:76
	v_add_u32_e32 v2, 0x6000, v67
	ds_write2_b32 v2, v26, v10 offset0:192 offset1:224
	v_add_u32_e32 v2, 0x6400, v67
	ds_write2_b32 v2, v27, v11 offset0:68 offset1:100
	ds_write2_b32 v2, v28, v12 offset0:200 offset1:232
	v_add_u32_e32 v2, 0x6800, v67
	ds_write2_b32 v2, v29, v13 offset0:76 offset1:108
	v_add_u32_e32 v2, 0x7200, v67
	ds_write2_b32 v2, v30, v14 offset0:96 offset1:128
	v_add_u32_e32 v2, 0x7400, v67
	ds_write2_b32 v2, v31, v15 offset0:100 offset1:132
	v_add_u32_e32 v2, 0x7600, v67
	ds_write2_b32 v2, v32, v16 offset0:104 offset1:136
	v_add_u32_e32 v2, 0x7800, v67
	ds_write2_b32 v2, v33, v17 offset0:108 offset1:140
	v_lshlrev_b32_e32 v2, 3, v66
	v_and_b32_e32 v3, 0x78, v2
	v_lshlrev_b32_e32 v98, 1, v3
	v_lshlrev_b32_e32 v2, 2, v3
	v_lshl_add_u64 v[4:5], s[14:15], 0, v[98:99]
	ds_write2_b32 v67, v51, v35 offset0:132 offset1:164
	v_ashrrev_i32_e32 v190, 4, v66
	v_add_u32_e32 v190, s38, v190
	v_mad_i64_i32 v[192:193], vcc, v190, s20, v[4:5]
	global_load_dwordx4 v[150:153], v[192:193], off
	v_add_u32_e32 v191, 16, v190
	v_mad_i64_i32 v[192:193], vcc, v191, s20, v[4:5]
	global_load_dwordx4 v[154:157], v[192:193], off
	v_add_u32_e32 v191, 32, v190
	v_mad_i64_i32 v[192:193], vcc, v191, s20, v[4:5]
	global_load_dwordx4 v[158:161], v[192:193], off
	v_add_u32_e32 v191, 48, v190
	v_mad_i64_i32 v[192:193], vcc, v191, s20, v[4:5]
	global_load_dwordx4 v[162:165], v[192:193], off
	v_add_u32_e32 v191, 64, v190
	v_mad_i64_i32 v[192:193], vcc, v191, s20, v[4:5]
	global_load_dwordx4 v[166:169], v[192:193], off
	v_add_u32_e32 v191, 80, v190
	v_mad_i64_i32 v[192:193], vcc, v191, s20, v[4:5]
	global_load_dwordx4 v[170:173], v[192:193], off
	v_add_u32_e32 v191, 96, v190
	v_mad_i64_i32 v[192:193], vcc, v191, s20, v[4:5]
	global_load_dwordx4 v[174:177], v[192:193], off
	v_add_u32_e32 v191, 112, v190
	v_mad_i64_i32 v[192:193], vcc, v191, s20, v[4:5]
	global_load_dwordx4 v[178:181], v[192:193], off
	s_waitcnt lgkmcnt(0)
	s_barrier
;   DI void operator()(const float* Ct, int ldc, int m0, int n0, int tid, int bm) const {
;     ...
;     for (int it = 0; it < bm / 16; it++) {
;       int id = tid + 256 * it; int row = id >> 4, c8 = (id & 15) * 8;
;       int m = m0 + row;
;       const float* c = Ct + row * ldc + c8;
;       float4 a = *(const float4*)c, b = *(const float4*)(c + 4);
;       float x[8];
;       if (srcb != nullptr) {
;         unpack8(*(const uint4*)(srcb + (size_t)m * LDA + n0 + c8), x);
;       } else {
;         const float* sp = (m < NP ? src0 + (size_t)m * 1024 : src1 + (size_t)(m - NP) * 1024) + n0 + c8;
;         float4 sa = *(const float4*)sp, sb = *(const float4*)(sp + 4);
;         x[0] = sa.x; x[1] = sa.y; x[2] = sa.z; x[3] = sa.w; x[4] = sb.x; x[5] = sb.y; x[6] = sb.z; x[7] = sb.w;
;       }
;       x[0] += a.x; x[1] += a.y; x[2] += a.z; x[3] += a.w; x[4] += b.x; x[5] += b.y; x[6] += b.z; x[7] += b.w;
;       if (dstf != nullptr) {
;         float* o = dstf + (size_t)m * 1024 + n0 + c8;
;         *(float4*)o = make_float4(x[0], x[1], x[2], x[3]); *(float4*)(o + 4) = make_float4(x[4], x[5], x[6], x[7]);
;       } else {
;         *(uint4*)(dstb + (size_t)m * LDA + n0 + c8) = pack8(x);
;       }
.LBB0_1217:
	v_add_u32_e32 v3, s4, v66
	v_ashrrev_i32_e32 v10, 4, v3
	v_add_u32_e32 v6, s38, v10
	v_mad_i64_i32 v[18:19], s[16:17], v6, s20, v[4:5]
	v_add_u32_e32 v11, 0x100, v3
	v_mad_u64_u32 v[14:15], s[16:17], v10, s36, v[2:3]
	v_ashrrev_i32_e32 v26, 4, v11
	ds_read_b128 v[10:13], v14
	ds_read_b128 v[14:17], v14 offset:16
	v_add_u32_e32 v20, s38, v26
	v_mad_i64_i32 v[20:21], s[16:17], v20, s20, v[4:5]
	s_addk_i32 s4, 0x400
	s_cmpk_lg_i32 s4, 0x800
	s_waitcnt vmcnt(7)
	v_mov_b64_e32 v[6:7], v[150:151]
	v_mov_b64_e32 v[8:9], v[152:153]
	v_lshlrev_b32_e32 v22, 16, v6
	v_and_b32_e32 v23, 0xffff0000, v6
	v_lshlrev_b32_e32 v6, 16, v7
	v_and_b32_e32 v7, 0xffff0000, v7
	v_lshlrev_b32_e32 v24, 16, v8
	v_and_b32_e32 v25, 0xffff0000, v8
	v_lshlrev_b32_e32 v8, 16, v9
	v_and_b32_e32 v9, 0xffff0000, v9
	s_waitcnt lgkmcnt(1)
	v_pk_add_f32 v[10:11], v[10:11], v[22:23]
	v_pk_add_f32 v[12:13], v[12:13], v[6:7]
	s_waitcnt lgkmcnt(0)
	v_pk_add_f32 v[14:15], v[14:15], v[24:25]
	v_pk_add_f32 v[16:17], v[16:17], v[8:9]
	v_cvt_pk_bf16_f32 v6, v10, v11
	v_cvt_pk_bf16_f32 v7, v12, v13
	v_cvt_pk_bf16_f32 v8, v14, v15
	v_cvt_pk_bf16_f32 v9, v16, v17
	global_store_dwordx4 v[18:19], v[6:9], off
	v_add_u32_e32 v10, 0x200, v3
	v_mad_u64_u32 v[14:15], s[16:17], v26, s36, v[2:3]
	v_ashrrev_i32_e32 v27, 4, v10
	ds_read_b128 v[10:13], v14
	ds_read_b128 v[14:17], v14 offset:16
	v_add_u32_e32 v18, s38, v27
	v_mad_i64_i32 v[18:19], s[16:17], v18, s20, v[4:5]
	v_add_u32_e32 v3, 0x300, v3
	v_ashrrev_i32_e32 v3, 4, v3
	s_waitcnt vmcnt(7)
	v_mov_b64_e32 v[6:7], v[154:155]
	v_mov_b64_e32 v[8:9], v[156:157]
	v_lshlrev_b32_e32 v22, 16, v6
	v_and_b32_e32 v23, 0xffff0000, v6
	v_lshlrev_b32_e32 v6, 16, v7
	v_and_b32_e32 v7, 0xffff0000, v7
	v_lshlrev_b32_e32 v24, 16, v8
	v_and_b32_e32 v25, 0xffff0000, v8
	v_lshlrev_b32_e32 v8, 16, v9
	v_and_b32_e32 v9, 0xffff0000, v9
	s_waitcnt lgkmcnt(1)
	v_pk_add_f32 v[10:11], v[10:11], v[22:23]
	v_pk_add_f32 v[12:13], v[12:13], v[6:7]
	s_waitcnt lgkmcnt(0)
	v_pk_add_f32 v[14:15], v[14:15], v[24:25]
	v_pk_add_f32 v[16:17], v[16:17], v[8:9]
	v_cvt_pk_bf16_f32 v6, v10, v11
	v_cvt_pk_bf16_f32 v7, v12, v13
	v_cvt_pk_bf16_f32 v8, v14, v15
	v_cvt_pk_bf16_f32 v9, v16, v17
	global_store_dwordx4 v[20:21], v[6:9], off
	v_mad_u64_u32 v[14:15], s[16:17], v27, s36, v[2:3]
	ds_read_b128 v[10:13], v14
	ds_read_b128 v[14:17], v14 offset:16
	v_add_u32_e32 v20, s38, v3
	v_mad_i64_i32 v[20:21], s[16:17], v20, s20, v[4:5]
	s_waitcnt vmcnt(7)
	v_mov_b64_e32 v[6:7], v[158:159]
	v_mov_b64_e32 v[8:9], v[160:161]
	v_lshlrev_b32_e32 v22, 16, v6
	v_and_b32_e32 v23, 0xffff0000, v6
	v_lshlrev_b32_e32 v6, 16, v7
	v_and_b32_e32 v7, 0xffff0000, v7
	v_lshlrev_b32_e32 v24, 16, v8
	v_and_b32_e32 v25, 0xffff0000, v8
	v_lshlrev_b32_e32 v8, 16, v9
	v_and_b32_e32 v9, 0xffff0000, v9
	s_waitcnt lgkmcnt(1)
	v_pk_add_f32 v[10:11], v[10:11], v[22:23]
	v_pk_add_f32 v[12:13], v[12:13], v[6:7]
	s_waitcnt lgkmcnt(0)
	v_pk_add_f32 v[14:15], v[14:15], v[24:25]
	v_pk_add_f32 v[16:17], v[16:17], v[8:9]
	v_cvt_pk_bf16_f32 v6, v10, v11
	v_cvt_pk_bf16_f32 v7, v12, v13
	v_cvt_pk_bf16_f32 v8, v14, v15
	v_cvt_pk_bf16_f32 v9, v16, v17
	global_store_dwordx4 v[18:19], v[6:9], off
	v_mad_u64_u32 v[14:15], s[16:17], v3, s36, v[2:3]
	ds_read_b128 v[10:13], v14
	ds_read_b128 v[14:17], v14 offset:16
	s_waitcnt vmcnt(7)
	v_mov_b64_e32 v[6:7], v[162:163]
	v_mov_b64_e32 v[8:9], v[164:165]
	v_lshlrev_b32_e32 v18, 16, v6
	v_and_b32_e32 v19, 0xffff0000, v6
	v_lshlrev_b32_e32 v6, 16, v7
	v_and_b32_e32 v7, 0xffff0000, v7
	v_lshlrev_b32_e32 v22, 16, v8
	v_and_b32_e32 v23, 0xffff0000, v8
	v_lshlrev_b32_e32 v8, 16, v9
	v_and_b32_e32 v9, 0xffff0000, v9
	s_waitcnt lgkmcnt(1)
	v_pk_add_f32 v[10:11], v[10:11], v[18:19]
	v_pk_add_f32 v[12:13], v[12:13], v[6:7]
	s_waitcnt lgkmcnt(0)
	v_pk_add_f32 v[14:15], v[14:15], v[22:23]
	v_pk_add_f32 v[16:17], v[16:17], v[8:9]
	v_cvt_pk_bf16_f32 v6, v10, v11
	v_cvt_pk_bf16_f32 v7, v12, v13
	v_cvt_pk_bf16_f32 v8, v14, v15
	v_cvt_pk_bf16_f32 v9, v16, v17
	global_store_dwordx4 v[20:21], v[6:9], off
	v_add_u32_e32 v3, s4, v66
	v_ashrrev_i32_e32 v10, 4, v3
	v_add_u32_e32 v6, s38, v10
	v_mad_i64_i32 v[18:19], s[16:17], v6, s20, v[4:5]
	v_add_u32_e32 v11, 0x100, v3
	v_mad_u64_u32 v[14:15], s[16:17], v10, s36, v[2:3]
	v_ashrrev_i32_e32 v26, 4, v11
	ds_read_b128 v[10:13], v14
	ds_read_b128 v[14:17], v14 offset:16
	v_add_u32_e32 v20, s38, v26
	v_mad_i64_i32 v[20:21], s[16:17], v20, s20, v[4:5]
	s_addk_i32 s4, 0x400
	s_cmpk_lg_i32 s4, 0x800
	s_waitcnt vmcnt(7)
	v_mov_b64_e32 v[6:7], v[166:167]
	v_mov_b64_e32 v[8:9], v[168:169]
	v_lshlrev_b32_e32 v22, 16, v6
	v_and_b32_e32 v23, 0xffff0000, v6
	v_lshlrev_b32_e32 v6, 16, v7
	v_and_b32_e32 v7, 0xffff0000, v7
	v_lshlrev_b32_e32 v24, 16, v8
	v_and_b32_e32 v25, 0xffff0000, v8
	v_lshlrev_b32_e32 v8, 16, v9
	v_and_b32_e32 v9, 0xffff0000, v9
	s_waitcnt lgkmcnt(1)
	v_pk_add_f32 v[10:11], v[10:11], v[22:23]
	v_pk_add_f32 v[12:13], v[12:13], v[6:7]
	s_waitcnt lgkmcnt(0)
	v_pk_add_f32 v[14:15], v[14:15], v[24:25]
	v_pk_add_f32 v[16:17], v[16:17], v[8:9]
	v_cvt_pk_bf16_f32 v6, v10, v11
	v_cvt_pk_bf16_f32 v7, v12, v13
	v_cvt_pk_bf16_f32 v8, v14, v15
	v_cvt_pk_bf16_f32 v9, v16, v17
	global_store_dwordx4 v[18:19], v[6:9], off
	v_add_u32_e32 v10, 0x200, v3
	v_mad_u64_u32 v[14:15], s[16:17], v26, s36, v[2:3]
	v_ashrrev_i32_e32 v27, 4, v10
	ds_read_b128 v[10:13], v14
	ds_read_b128 v[14:17], v14 offset:16
	v_add_u32_e32 v18, s38, v27
	v_mad_i64_i32 v[18:19], s[16:17], v18, s20, v[4:5]
	v_add_u32_e32 v3, 0x300, v3
	v_ashrrev_i32_e32 v3, 4, v3
	s_waitcnt vmcnt(7)
; template <int TM, int TN>
; DI void gemm_mainloop(const u16* __restrict__ A, long lda, const u16* __restrict__ Bt, long ldb, int K, char* smem,
;                       f32x16 (&acc)[TM][TN]) {
;     ...
;   const int nk = K / 64;
;   const int lrow = tid >> 3, lch = (tid & 7) * 8;
;   const u16* gA = A + (long)lrow * lda + lch;
;   const u16* gB = Bt + (long)lrow * ldb + lch;
;   const int soff = lrow * LD + lch;
;     ...
;   GEMM_GLOAD(0)
;   __syncthreads();
;   GEMM_SSTORE(0)
;   if (nk > 1) GEMM_GLOAD(64)
;   __syncthreads();
;   DI void operator()(const float* Ct, int ldc, int m0, int n0, int tid, int bm) const {
;     ...
;     for (int it = 0; it < bm / 16; it++) {
;       int id = tid + 256 * it; int row = id >> 4, c8 = (id & 15) * 8;
;       int m = m0 + row;
;       const float* c = Ct + row * ldc + c8;
;       float4 a = *(const float4*)c, b = *(const float4*)(c + 4);
;       float x[8];
;       if (srcb != nullptr) {
;         unpack8(*(const uint4*)(srcb + (size_t)m * LDA + n0 + c8), x);
;       } else {
;         const float* sp = (m < NP ? src0 + (size_t)m * 1024 : src1 + (size_t)(m - NP) * 1024) + n0 + c8;
;         float4 sa = *(const float4*)sp, sb = *(const float4*)(sp + 4);
;         x[0] = sa.x; x[1] = sa.y; x[2] = sa.z; x[3] = sa.w; x[4] = sb.x; x[5] = sb.y; x[6] = sb.z; x[7] = sb.w;
;       }
;       x[0] += a.x; x[1] += a.y; x[2] += a.z; x[3] += a.w; x[4] += b.x; x[5] += b.y; x[6] += b.z; x[7] += b.w;
;       if (dstf != nullptr) {
;         float* o = dstf + (size_t)m * 1024 + n0 + c8;
;         *(float4*)o = make_float4(x[0], x[1], x[2], x[3]); *(float4*)(o + 4) = make_float4(x[4], x[5], x[6], x[7]);
;       } else {
;         *(uint4*)(dstb + (size_t)m * LDA + n0 + c8) = pack8(x);
;       }
	v_mov_b64_e32 v[6:7], v[170:171]
	v_mov_b64_e32 v[8:9], v[172:173]
	v_lshlrev_b32_e32 v22, 16, v6
	v_and_b32_e32 v23, 0xffff0000, v6
	v_lshlrev_b32_e32 v6, 16, v7
	v_and_b32_e32 v7, 0xffff0000, v7
	v_lshlrev_b32_e32 v24, 16, v8
	v_and_b32_e32 v25, 0xffff0000, v8
	v_lshlrev_b32_e32 v8, 16, v9
	v_and_b32_e32 v9, 0xffff0000, v9
	s_waitcnt lgkmcnt(1)
	v_pk_add_f32 v[10:11], v[10:11], v[22:23]
	v_pk_add_f32 v[12:13], v[12:13], v[6:7]
	s_waitcnt lgkmcnt(0)
	v_pk_add_f32 v[14:15], v[14:15], v[24:25]
	v_pk_add_f32 v[16:17], v[16:17], v[8:9]
	v_cvt_pk_bf16_f32 v6, v10, v11
	v_cvt_pk_bf16_f32 v7, v12, v13
	v_cvt_pk_bf16_f32 v8, v14, v15
	v_cvt_pk_bf16_f32 v9, v16, v17
	global_store_dwordx4 v[20:21], v[6:9], off
	v_mad_u64_u32 v[14:15], s[16:17], v27, s36, v[2:3]
	ds_read_b128 v[10:13], v14
	ds_read_b128 v[14:17], v14 offset:16
	v_add_u32_e32 v20, s38, v3
	v_mad_i64_i32 v[20:21], s[16:17], v20, s20, v[4:5]
	s_waitcnt vmcnt(7)
	v_mov_b64_e32 v[6:7], v[174:175]
	v_mov_b64_e32 v[8:9], v[176:177]
	v_lshlrev_b32_e32 v22, 16, v6
	v_and_b32_e32 v23, 0xffff0000, v6
	v_lshlrev_b32_e32 v6, 16, v7
	v_and_b32_e32 v7, 0xffff0000, v7
	v_lshlrev_b32_e32 v24, 16, v8
	v_and_b32_e32 v25, 0xffff0000, v8
	v_lshlrev_b32_e32 v8, 16, v9
	v_and_b32_e32 v9, 0xffff0000, v9
	s_waitcnt lgkmcnt(1)
	v_pk_add_f32 v[10:11], v[10:11], v[22:23]
	v_pk_add_f32 v[12:13], v[12:13], v[6:7]
	s_waitcnt lgkmcnt(0)
	v_pk_add_f32 v[14:15], v[14:15], v[24:25]
	v_pk_add_f32 v[16:17], v[16:17], v[8:9]
	v_cvt_pk_bf16_f32 v6, v10, v11
	v_cvt_pk_bf16_f32 v7, v12, v13
	v_cvt_pk_bf16_f32 v8, v14, v15
	v_cvt_pk_bf16_f32 v9, v16, v17
	global_store_dwordx4 v[18:19], v[6:9], off
	v_mad_u64_u32 v[14:15], s[16:17], v3, s36, v[2:3]
	ds_read_b128 v[10:13], v14
	ds_read_b128 v[14:17], v14 offset:16
	s_waitcnt vmcnt(7)
	v_mov_b64_e32 v[6:7], v[178:179]
	v_mov_b64_e32 v[8:9], v[180:181]
	v_lshlrev_b32_e32 v18, 16, v6
	v_and_b32_e32 v19, 0xffff0000, v6
	v_lshlrev_b32_e32 v6, 16, v7
	v_and_b32_e32 v7, 0xffff0000, v7
	v_lshlrev_b32_e32 v22, 16, v8
	v_and_b32_e32 v23, 0xffff0000, v8
	v_lshlrev_b32_e32 v8, 16, v9
	v_and_b32_e32 v9, 0xffff0000, v9
	s_waitcnt lgkmcnt(1)
	v_pk_add_f32 v[10:11], v[10:11], v[18:19]
	v_pk_add_f32 v[12:13], v[12:13], v[6:7]
	s_waitcnt lgkmcnt(0)
	v_pk_add_f32 v[14:15], v[14:15], v[22:23]
	v_pk_add_f32 v[16:17], v[16:17], v[8:9]
	v_cvt_pk_bf16_f32 v6, v10, v11
	v_cvt_pk_bf16_f32 v7, v12, v13
	v_cvt_pk_bf16_f32 v8, v14, v15
	v_cvt_pk_bf16_f32 v9, v16, v17
	global_store_dwordx4 v[20:21], v[6:9], off
	s_add_i32 s4, s37, 8
	s_addk_i32 s21, 0x2000
	s_cmp_lt_u32 s37, 24
	s_mov_b32 s37, s4
	s_barrier
	s_cbranch_scc1 .LBB0_1214
	s_lshl_b32 s4, s79, 6
	s_add_i32 s4, s80, s4
	s_cmpk_gt_i32 s4, 0xff
	s_cbranch_scc1 .LBB0_1221
	s_lshl_b32 s4, s4, 3
	s_lshl_b32 s5, s80, 6
	s_and_b32 s4, s4, 0xffffff80
	s_and_b32 s10, s5, 64
	s_or_b32 s11, s4, s10
	s_add_i32 s11, s11, 0x8000
	s_and_b32 s14, s5, 0x380
	s_mul_i32 s4, s11, 0x880
	s_mul_hi_i32 s5, s11, 0x880
	s_add_u32 s4, s8, s4
	v_mov_b32_e32 v1, v0
	s_addc_u32 s5, s9, s5
	s_mul_i32 s8, s14, 0x880
	s_movk_i32 s10, 0x880
	v_lshlrev_b32_e32 v2, 3, v1
	s_add_u32 s8, s3, s8
	v_ashrrev_i32_e32 v36, 3, v1
	v_and_b32_e32 v37, 56, v2
	v_mov_b64_e32 v[2:3], s[4:5]
	s_addc_u32 s9, s18, 0
	v_mad_i64_i32 v[2:3], s[4:5], v36, s10, v[2:3]
	v_lshlrev_b32_e32 v34, 1, v37
	v_mov_b32_e32 v35, 0
	v_lshl_add_u64 v[40:41], v[2:3], 0, v[34:35]
	v_mov_b64_e32 v[2:3], s[8:9]
	s_mov_b32 s3, 0x11000
	v_mad_i64_i32 v[10:11], s[4:5], v36, s10, v[2:3]
	v_add_co_u32_e32 v38, vcc, s3, v40
	v_lshl_add_u64 v[42:43], v[10:11], 0, v[34:35]
	s_nop 0
	v_addc_co_u32_e32 v39, vcc, 0, v41, vcc
	v_add_co_u32_e32 v44, vcc, s3, v42
	s_mov_b32 s3, 0x22000
	s_nop 0
	v_addc_co_u32_e32 v45, vcc, 0, v43, vcc
	v_add_co_u32_e32 v48, vcc, s3, v42
	s_mov_b32 s3, 0x33000
	s_nop 0
	v_addc_co_u32_e32 v49, vcc, 0, v43, vcc
	v_add_co_u32_e32 v46, vcc, s3, v42
	global_load_dwordx4 v[2:5], v[40:41], off
	s_nop 0
	v_addc_co_u32_e32 v47, vcc, 0, v43, vcc
	global_load_dwordx4 v[6:9], v[38:39], off
	global_load_dwordx4 v[10:13], v[42:43], off
	global_load_dwordx4 v[14:17], v[44:45], off
	global_load_dwordx4 v[18:21], v[48:49], off
	global_load_dwordx4 v[22:25], v[46:47], off
	s_barrier
	global_load_dwordx4 v[26:29], v[40:41], off offset:128
	global_load_dwordx4 v[30:33], v[38:39], off offset:128
	global_load_dwordx4 v[50:53], v[42:43], off offset:128
	global_load_dwordx4 v[54:57], v[44:45], off offset:128
	global_load_dwordx4 v[58:61], v[48:49], off offset:128
	global_load_dwordx4 v[62:65], v[46:47], off offset:128
	s_movk_i32 s4, 0x48
	s_mov_b32 s3, 0xfffffe0
	v_and_b32_e32 v34, 31, v1
	v_lshrrev_b32_e32 v66, 2, v1
	v_lshrrev_b32_e32 v67, 1, v1
	s_movk_i32 s8, 0x90
	v_and_b32_e32 v1, 0x5f, v1
	v_mul_lo_u32 v36, v36, s4
	v_and_or_b32 v68, v66, s3, v34
	v_and_b32_e32 v66, 16, v67
	v_add_lshl_u32 v34, v36, v37, 1
	v_mad_u64_u32 v[36:37], s[4:5], v68, s8, v[66:67]
	v_mad_u32_u24 v1, v1, s8, v66
	s_mov_b32 s9, 0
	s_waitcnt vmcnt(11)
	ds_write_b128 v34, v[2:5]
	s_waitcnt vmcnt(10)
	ds_write_b128 v34, v[6:9] offset:4608
	s_waitcnt vmcnt(9)
	ds_write_b128 v34, v[10:13] offset:18432
	s_waitcnt vmcnt(8)
	ds_write_b128 v34, v[14:17] offset:23040
	s_waitcnt vmcnt(7)
	ds_write_b128 v34, v[18:21] offset:27648
	s_waitcnt vmcnt(6)
	ds_write_b128 v34, v[22:25] offset:32256
	s_waitcnt lgkmcnt(0)
	s_barrier
; #define MFMA(a, b, c) __builtin_amdgcn_mfma_f32_32x32x16_bf16((a), (b), (c), 0, 0, 0)
; template <int TM, int TN>
; DI void gemm_mainloop(const u16* __restrict__ A, long lda, const u16* __restrict__ Bt, long ldb, int K, char* smem,
;                       f32x16 (&acc)[TM][TN]) {
;     ...
;   for (int kt = 0; kt < nk; kt++) {
;     const int buf = kt & 1;
;     const u16* cA = sA + buf * BM * LD + (wm * 32 * TM + r) * LD + h * 8;
;     const u16* cB = sB + buf * BN * LD + (wn * 32 * TN + r) * LD + h * 8;
;     bf16x8 af[TM], bfr[TN];
; #pragma unroll
;     for (int tm = 0; tm < TM; tm++) af[tm] = *(const bf16x8*)(cA + tm * 32 * LD);
; #pragma unroll
;     for (int tn = 0; tn < TN; tn++) bfr[tn] = *(const bf16x8*)(cB + tn * 32 * LD);
;     if (kt + 1 < nk) GEMM_SSTORE(buf ^ 1)
;     __builtin_amdgcn_sched_barrier(0);
;     __builtin_amdgcn_s_setprio(1);
; #pragma unroll
;     for (int tm = 0; tm < TM; tm++)
; #pragma unroll
;       for (int tn = 0; tn < TN; tn++) acc[tm][tn] = MFMA(af[tm], bfr[tn], acc[tm][tn]);
; #pragma unroll
;     for (int tm = 0; tm < TM; tm++) af[tm] = *(const bf16x8*)(cA + tm * 32 * LD + 16);
; #pragma unroll
;     for (int tn = 0; tn < TN; tn++) bfr[tn] = *(const bf16x8*)(cB + tn * 32 * LD + 16);
; #pragma unroll
;     for (int tm = 0; tm < TM; tm++)
; #pragma unroll
;       for (int tn = 0; tn < TN; tn++) acc[tm][tn] = MFMA(af[tm], bfr[tn], acc[tm][tn]);
;     __builtin_amdgcn_sched_group_barrier(0x8, 4, 0);
;     if (kt + 2 < nk) GEMM_GLOAD((kt + 2) * 64)
; #pragma unroll
;     for (int ks = 2; ks < 4; ks++) {
; #pragma unroll
;       for (int tm = 0; tm < TM; tm++) af[tm] = *(const bf16x8*)(cA + tm * 32 * LD + ks * 16);
; #pragma unroll
;       for (int tn = 0; tn < TN; tn++) bfr[tn] = *(const bf16x8*)(cB + tn * 32 * LD + ks * 16);
; #pragma unroll
;       for (int tm = 0; tm < TM; tm++)
; #pragma unroll
;         for (int tn = 0; tn < TN; tn++) acc[tm][tn] = MFMA(af[tm], bfr[tn], acc[tm][tn]);
;     }
;     __builtin_amdgcn_s_setprio(0);
;     __syncthreads();
;   }
	ds_read_b128 v[18:21], v36
	ds_read_b128 v[2:5], v1 offset:18432
	ds_read_b128 v[22:25], v1 offset:23040
	s_waitcnt vmcnt(5)
	ds_write_b128 v34, v[26:29] offset:9216
	s_waitcnt vmcnt(4)
	ds_write_b128 v34, v[30:33] offset:13824
	s_waitcnt vmcnt(3)
	ds_write_b128 v34, v[50:53] offset:36864
	s_waitcnt vmcnt(2)
	ds_write_b128 v34, v[54:57] offset:41472
	s_waitcnt vmcnt(1)
	ds_write_b128 v34, v[58:61] offset:46080
	s_waitcnt vmcnt(0)
	ds_write_b128 v34, v[62:65] offset:50688
	s_setprio 1
	ds_read_b128 v[50:53], v36 offset:32
	s_waitcnt lgkmcnt(8)
	v_mfma_f32_32x32x16_bf16 v[2:17], v[18:21], v[2:5], 0
	ds_read_b128 v[54:57], v1 offset:18464
	ds_read_b128 v[58:61], v1 offset:18528
	global_load_dwordx4 v[62:65], v[38:39], off offset:256
	global_load_dwordx4 v[66:69], v[42:43], off offset:256
	global_load_dwordx4 v[70:73], v[44:45], off offset:256
	global_load_dwordx4 v[74:77], v[48:49], off offset:256
	global_load_dwordx4 v[140:143], v[40:41], off offset:256
	global_load_dwordx4 v[144:147], v[46:47], off offset:256
	ds_read_b128 v[78:81], v1 offset:23136
	s_waitcnt lgkmcnt(10)
	v_mfma_f32_32x32x16_bf16 v[18:33], v[18:21], v[22:25], 0
	s_waitcnt lgkmcnt(2)
	v_mfma_f32_32x32x16_bf16 v[2:17], v[50:53], v[54:57], v[2:17]
	ds_read_b128 v[54:57], v1 offset:23072
	s_waitcnt lgkmcnt(0)
	v_mfma_f32_32x32x16_bf16 v[18:33], v[50:53], v[54:57], v[18:33]
	ds_read_b128 v[50:53], v36 offset:64
	ds_read_b128 v[54:57], v1 offset:18496
	s_waitcnt lgkmcnt(0)
	v_mfma_f32_32x32x16_bf16 v[2:17], v[50:53], v[54:57], v[2:17]
	ds_read_b128 v[54:57], v1 offset:23104
	s_waitcnt lgkmcnt(0)
	v_mfma_f32_32x32x16_bf16 v[18:33], v[50:53], v[54:57], v[18:33]
	ds_read_b128 v[50:53], v36 offset:96
	s_waitcnt lgkmcnt(0)
	v_mfma_f32_32x32x16_bf16 v[2:17], v[50:53], v[58:61], v[2:17]
	v_mfma_f32_32x32x16_bf16 v[18:33], v[50:53], v[78:81], v[18:33]
	s_setprio 0
	s_barrier
	ds_read_b128 v[50:53], v36 offset:9216
	ds_read_b128 v[78:81], v1 offset:36864
	ds_read_b128 v[82:85], v1 offset:41472
	s_waitcnt vmcnt(1)
	ds_write_b128 v34, v[140:143]
	ds_write_b128 v34, v[62:65] offset:4608
	ds_write_b128 v34, v[66:69] offset:18432
	ds_write_b128 v34, v[70:73] offset:23040
	ds_write_b128 v34, v[74:77] offset:27648
	s_waitcnt vmcnt(0)
	ds_write_b128 v34, v[144:147] offset:32256
	s_setprio 1
	s_waitcnt lgkmcnt(7)
	v_mfma_f32_32x32x16_bf16 v[2:17], v[50:53], v[78:81], v[2:17]
	ds_read_b128 v[54:57], v1 offset:36896
	ds_read_b128 v[58:61], v1 offset:36960
	global_load_dwordx4 v[62:65], v[38:39], off offset:384
	global_load_dwordx4 v[66:69], v[42:43], off offset:384
	global_load_dwordx4 v[70:73], v[44:45], off offset:384
	global_load_dwordx4 v[74:77], v[48:49], off offset:384
	global_load_dwordx4 v[140:143], v[40:41], off offset:384
	global_load_dwordx4 v[144:147], v[46:47], off offset:384
	ds_read_b128 v[78:81], v1 offset:41568
	s_waitcnt lgkmcnt(9)
	v_mfma_f32_32x32x16_bf16 v[18:33], v[50:53], v[82:85], v[18:33]
	ds_read_b128 v[50:53], v36 offset:9248
	s_waitcnt lgkmcnt(0)
	v_mfma_f32_32x32x16_bf16 v[2:17], v[50:53], v[54:57], v[2:17]
	ds_read_b128 v[54:57], v1 offset:41504
	s_waitcnt lgkmcnt(0)
	v_mfma_f32_32x32x16_bf16 v[18:33], v[50:53], v[54:57], v[18:33]
	ds_read_b128 v[50:53], v36 offset:9280
	ds_read_b128 v[54:57], v1 offset:36928
	s_waitcnt lgkmcnt(0)
	v_mfma_f32_32x32x16_bf16 v[2:17], v[50:53], v[54:57], v[2:17]
	ds_read_b128 v[54:57], v1 offset:41536
	s_waitcnt lgkmcnt(0)
	v_mfma_f32_32x32x16_bf16 v[18:33], v[50:53], v[54:57], v[18:33]
	ds_read_b128 v[50:53], v36 offset:9312
	s_waitcnt lgkmcnt(0)
	v_mfma_f32_32x32x16_bf16 v[2:17], v[50:53], v[58:61], v[2:17]
	v_mfma_f32_32x32x16_bf16 v[18:33], v[50:53], v[78:81], v[18:33]
	s_setprio 0
	s_barrier
	ds_read_b128 v[50:53], v36
	ds_read_b128 v[78:81], v1 offset:18432
	ds_read_b128 v[82:85], v1 offset:23040
	s_waitcnt vmcnt(1)
	ds_write_b128 v34, v[140:143] offset:9216
	ds_write_b128 v34, v[62:65] offset:13824
	ds_write_b128 v34, v[66:69] offset:36864
	ds_write_b128 v34, v[70:73] offset:41472
	ds_write_b128 v34, v[74:77] offset:46080
	s_waitcnt vmcnt(0)
	ds_write_b128 v34, v[144:147] offset:50688
	s_setprio 1
	s_waitcnt lgkmcnt(7)
	v_mfma_f32_32x32x16_bf16 v[2:17], v[50:53], v[78:81], v[2:17]
	ds_read_b128 v[54:57], v1 offset:18464
	ds_read_b128 v[58:61], v1 offset:18528
	global_load_dwordx4 v[62:65], v[38:39], off offset:512
	global_load_dwordx4 v[66:69], v[42:43], off offset:512
	global_load_dwordx4 v[70:73], v[44:45], off offset:512
	global_load_dwordx4 v[74:77], v[48:49], off offset:512
	global_load_dwordx4 v[140:143], v[40:41], off offset:512
	global_load_dwordx4 v[144:147], v[46:47], off offset:512
	ds_read_b128 v[78:81], v1 offset:23136
	s_waitcnt lgkmcnt(9)
	v_mfma_f32_32x32x16_bf16 v[18:33], v[50:53], v[82:85], v[18:33]
	ds_read_b128 v[50:53], v36 offset:32
	s_waitcnt lgkmcnt(0)
	v_mfma_f32_32x32x16_bf16 v[2:17], v[50:53], v[54:57], v[2:17]
	ds_read_b128 v[54:57], v1 offset:23072
	s_waitcnt lgkmcnt(0)
	v_mfma_f32_32x32x16_bf16 v[18:33], v[50:53], v[54:57], v[18:33]
	ds_read_b128 v[50:53], v36 offset:64
	ds_read_b128 v[54:57], v1 offset:18496
	s_waitcnt lgkmcnt(0)
	v_mfma_f32_32x32x16_bf16 v[2:17], v[50:53], v[54:57], v[2:17]
	ds_read_b128 v[54:57], v1 offset:23104
	s_waitcnt lgkmcnt(0)
	v_mfma_f32_32x32x16_bf16 v[18:33], v[50:53], v[54:57], v[18:33]
	ds_read_b128 v[50:53], v36 offset:96
	s_waitcnt lgkmcnt(0)
	v_mfma_f32_32x32x16_bf16 v[2:17], v[50:53], v[58:61], v[2:17]
	v_mfma_f32_32x32x16_bf16 v[18:33], v[50:53], v[78:81], v[18:33]
	s_setprio 0
	s_barrier
; #define MFMA(a, b, c) __builtin_amdgcn_mfma_f32_32x32x16_bf16((a), (b), (c), 0, 0, 0)
; template <int TM, int TN>
; DI void gemm_mainloop(const u16* __restrict__ A, long lda, const u16* __restrict__ Bt, long ldb, int K, char* smem,
;                       f32x16 (&acc)[TM][TN]) {
;     ...
;   for (int kt = 0; kt < nk; kt++) {
;     const int buf = kt & 1;
;     const u16* cA = sA + buf * BM * LD + (wm * 32 * TM + r) * LD + h * 8;
;     const u16* cB = sB + buf * BN * LD + (wn * 32 * TN + r) * LD + h * 8;
;     bf16x8 af[TM], bfr[TN];
; #pragma unroll
;     for (int tm = 0; tm < TM; tm++) af[tm] = *(const bf16x8*)(cA + tm * 32 * LD);
; #pragma unroll
;     for (int tn = 0; tn < TN; tn++) bfr[tn] = *(const bf16x8*)(cB + tn * 32 * LD);
;     if (kt + 1 < nk) GEMM_SSTORE(buf ^ 1)
;     __builtin_amdgcn_sched_barrier(0);
;     __builtin_amdgcn_s_setprio(1);
; #pragma unroll
;     for (int tm = 0; tm < TM; tm++)
; #pragma unroll
;       for (int tn = 0; tn < TN; tn++) acc[tm][tn] = MFMA(af[tm], bfr[tn], acc[tm][tn]);
; #pragma unroll
;     for (int tm = 0; tm < TM; tm++) af[tm] = *(const bf16x8*)(cA + tm * 32 * LD + 16);
; #pragma unroll
;     for (int tn = 0; tn < TN; tn++) bfr[tn] = *(const bf16x8*)(cB + tn * 32 * LD + 16);
; #pragma unroll
;     for (int tm = 0; tm < TM; tm++)
; #pragma unroll
;       for (int tn = 0; tn < TN; tn++) acc[tm][tn] = MFMA(af[tm], bfr[tn], acc[tm][tn]);
;     __builtin_amdgcn_sched_group_barrier(0x8, 4, 0);
;     if (kt + 2 < nk) GEMM_GLOAD((kt + 2) * 64)
; #pragma unroll
;     for (int ks = 2; ks < 4; ks++) {
; #pragma unroll
;       for (int tm = 0; tm < TM; tm++) af[tm] = *(const bf16x8*)(cA + tm * 32 * LD + ks * 16);
; #pragma unroll
;       for (int tn = 0; tn < TN; tn++) bfr[tn] = *(const bf16x8*)(cB + tn * 32 * LD + ks * 16);
; #pragma unroll
;       for (int tm = 0; tm < TM; tm++)
; #pragma unroll
;         for (int tn = 0; tn < TN; tn++) acc[tm][tn] = MFMA(af[tm], bfr[tn], acc[tm][tn]);
;     }
;     __builtin_amdgcn_s_setprio(0);
;     __syncthreads();
;   }
	ds_read_b128 v[50:53], v36 offset:9216
	ds_read_b128 v[78:81], v1 offset:36864
	ds_read_b128 v[82:85], v1 offset:41472
	s_waitcnt vmcnt(1)
	ds_write_b128 v34, v[140:143]
	ds_write_b128 v34, v[62:65] offset:4608
	ds_write_b128 v34, v[66:69] offset:18432
	ds_write_b128 v34, v[70:73] offset:23040
	ds_write_b128 v34, v[74:77] offset:27648
	s_waitcnt vmcnt(0)
	ds_write_b128 v34, v[144:147] offset:32256
	s_setprio 1
	s_waitcnt lgkmcnt(7)
	v_mfma_f32_32x32x16_bf16 v[2:17], v[50:53], v[78:81], v[2:17]
	ds_read_b128 v[54:57], v1 offset:36896
	ds_read_b128 v[58:61], v1 offset:36960
	global_load_dwordx4 v[62:65], v[38:39], off offset:640
	global_load_dwordx4 v[66:69], v[42:43], off offset:640
	global_load_dwordx4 v[70:73], v[44:45], off offset:640
	global_load_dwordx4 v[74:77], v[48:49], off offset:640
	global_load_dwordx4 v[140:143], v[40:41], off offset:640
	global_load_dwordx4 v[144:147], v[46:47], off offset:640
	ds_read_b128 v[78:81], v1 offset:41568
	s_waitcnt lgkmcnt(9)
	v_mfma_f32_32x32x16_bf16 v[18:33], v[50:53], v[82:85], v[18:33]
	ds_read_b128 v[50:53], v36 offset:9248
	s_waitcnt lgkmcnt(0)
	v_mfma_f32_32x32x16_bf16 v[2:17], v[50:53], v[54:57], v[2:17]
	ds_read_b128 v[54:57], v1 offset:41504
	s_waitcnt lgkmcnt(0)
	v_mfma_f32_32x32x16_bf16 v[18:33], v[50:53], v[54:57], v[18:33]
	ds_read_b128 v[50:53], v36 offset:9280
	ds_read_b128 v[54:57], v1 offset:36928
	s_waitcnt lgkmcnt(0)
	v_mfma_f32_32x32x16_bf16 v[2:17], v[50:53], v[54:57], v[2:17]
	ds_read_b128 v[54:57], v1 offset:41536
	s_waitcnt lgkmcnt(0)
	v_mfma_f32_32x32x16_bf16 v[18:33], v[50:53], v[54:57], v[18:33]
	ds_read_b128 v[50:53], v36 offset:9312
	s_waitcnt lgkmcnt(0)
	v_mfma_f32_32x32x16_bf16 v[2:17], v[50:53], v[58:61], v[2:17]
	v_mfma_f32_32x32x16_bf16 v[18:33], v[50:53], v[78:81], v[18:33]
	s_setprio 0
	s_barrier
	ds_read_b128 v[50:53], v36
	ds_read_b128 v[78:81], v1 offset:18432
	ds_read_b128 v[82:85], v1 offset:23040
	s_waitcnt vmcnt(1)
	ds_write_b128 v34, v[140:143] offset:9216
	ds_write_b128 v34, v[62:65] offset:13824
	ds_write_b128 v34, v[66:69] offset:36864
	ds_write_b128 v34, v[70:73] offset:41472
	ds_write_b128 v34, v[74:77] offset:46080
	s_waitcnt vmcnt(0)
	ds_write_b128 v34, v[144:147] offset:50688
	s_setprio 1
	s_waitcnt lgkmcnt(7)
	v_mfma_f32_32x32x16_bf16 v[2:17], v[50:53], v[78:81], v[2:17]
	ds_read_b128 v[54:57], v1 offset:18464
	ds_read_b128 v[58:61], v1 offset:18528
	global_load_dwordx4 v[62:65], v[38:39], off offset:768
	global_load_dwordx4 v[66:69], v[42:43], off offset:768
	global_load_dwordx4 v[70:73], v[44:45], off offset:768
	global_load_dwordx4 v[74:77], v[48:49], off offset:768
	global_load_dwordx4 v[140:143], v[40:41], off offset:768
	global_load_dwordx4 v[144:147], v[46:47], off offset:768
	ds_read_b128 v[78:81], v1 offset:23136
	s_waitcnt lgkmcnt(9)
	v_mfma_f32_32x32x16_bf16 v[18:33], v[50:53], v[82:85], v[18:33]
	ds_read_b128 v[50:53], v36 offset:32
	s_waitcnt lgkmcnt(0)
	v_mfma_f32_32x32x16_bf16 v[2:17], v[50:53], v[54:57], v[2:17]
	ds_read_b128 v[54:57], v1 offset:23072
	s_waitcnt lgkmcnt(0)
	v_mfma_f32_32x32x16_bf16 v[18:33], v[50:53], v[54:57], v[18:33]
	ds_read_b128 v[50:53], v36 offset:64
	ds_read_b128 v[54:57], v1 offset:18496
	s_waitcnt lgkmcnt(0)
	v_mfma_f32_32x32x16_bf16 v[2:17], v[50:53], v[54:57], v[2:17]
	ds_read_b128 v[54:57], v1 offset:23104
	s_waitcnt lgkmcnt(0)
	v_mfma_f32_32x32x16_bf16 v[18:33], v[50:53], v[54:57], v[18:33]
	ds_read_b128 v[50:53], v36 offset:96
	s_waitcnt lgkmcnt(0)
	v_mfma_f32_32x32x16_bf16 v[2:17], v[50:53], v[58:61], v[2:17]
	v_mfma_f32_32x32x16_bf16 v[18:33], v[50:53], v[78:81], v[18:33]
	s_setprio 0
	s_barrier
	ds_read_b128 v[50:53], v36 offset:9216
	ds_read_b128 v[78:81], v1 offset:36864
	ds_read_b128 v[82:85], v1 offset:41472
	s_waitcnt vmcnt(1)
	ds_write_b128 v34, v[140:143]
	ds_write_b128 v34, v[62:65] offset:4608
	ds_write_b128 v34, v[66:69] offset:18432
	ds_write_b128 v34, v[70:73] offset:23040
	ds_write_b128 v34, v[74:77] offset:27648
	s_waitcnt vmcnt(0)
	ds_write_b128 v34, v[144:147] offset:32256
	s_setprio 1
	s_waitcnt lgkmcnt(7)
	v_mfma_f32_32x32x16_bf16 v[2:17], v[50:53], v[78:81], v[2:17]
	ds_read_b128 v[54:57], v1 offset:36896
	ds_read_b128 v[58:61], v1 offset:36960
	global_load_dwordx4 v[62:65], v[38:39], off offset:896
	global_load_dwordx4 v[66:69], v[42:43], off offset:896
	global_load_dwordx4 v[70:73], v[44:45], off offset:896
	global_load_dwordx4 v[74:77], v[48:49], off offset:896
	global_load_dwordx4 v[140:143], v[40:41], off offset:896
	global_load_dwordx4 v[144:147], v[46:47], off offset:896
	ds_read_b128 v[78:81], v1 offset:41568
	s_waitcnt lgkmcnt(9)
	v_mfma_f32_32x32x16_bf16 v[18:33], v[50:53], v[82:85], v[18:33]
	ds_read_b128 v[50:53], v36 offset:9248
	s_waitcnt lgkmcnt(0)
	v_mfma_f32_32x32x16_bf16 v[2:17], v[50:53], v[54:57], v[2:17]
	ds_read_b128 v[54:57], v1 offset:41504
	s_waitcnt lgkmcnt(0)
	v_mfma_f32_32x32x16_bf16 v[18:33], v[50:53], v[54:57], v[18:33]
	ds_read_b128 v[50:53], v36 offset:9280
	ds_read_b128 v[54:57], v1 offset:36928
	s_waitcnt lgkmcnt(0)
	v_mfma_f32_32x32x16_bf16 v[2:17], v[50:53], v[54:57], v[2:17]
	ds_read_b128 v[54:57], v1 offset:41536
	s_waitcnt lgkmcnt(0)
	v_mfma_f32_32x32x16_bf16 v[18:33], v[50:53], v[54:57], v[18:33]
	ds_read_b128 v[50:53], v36 offset:9312
	s_waitcnt lgkmcnt(0)
	v_mfma_f32_32x32x16_bf16 v[2:17], v[50:53], v[58:61], v[2:17]
	v_mfma_f32_32x32x16_bf16 v[18:33], v[50:53], v[78:81], v[18:33]
	s_setprio 0
	s_barrier
; #define MFMA(a, b, c) __builtin_amdgcn_mfma_f32_32x32x16_bf16((a), (b), (c), 0, 0, 0)
; template <int TM, int TN>
; DI void gemm_mainloop(const u16* __restrict__ A, long lda, const u16* __restrict__ Bt, long ldb, int K, char* smem,
;                       f32x16 (&acc)[TM][TN]) {
;     ...
;   for (int kt = 0; kt < nk; kt++) {
;     const int buf = kt & 1;
;     const u16* cA = sA + buf * BM * LD + (wm * 32 * TM + r) * LD + h * 8;
;     const u16* cB = sB + buf * BN * LD + (wn * 32 * TN + r) * LD + h * 8;
;     bf16x8 af[TM], bfr[TN];
; #pragma unroll
;     for (int tm = 0; tm < TM; tm++) af[tm] = *(const bf16x8*)(cA + tm * 32 * LD);
; #pragma unroll
;     for (int tn = 0; tn < TN; tn++) bfr[tn] = *(const bf16x8*)(cB + tn * 32 * LD);
;     if (kt + 1 < nk) GEMM_SSTORE(buf ^ 1)
;     __builtin_amdgcn_sched_barrier(0);
;     __builtin_amdgcn_s_setprio(1);
; #pragma unroll
;     for (int tm = 0; tm < TM; tm++)
; #pragma unroll
;       for (int tn = 0; tn < TN; tn++) acc[tm][tn] = MFMA(af[tm], bfr[tn], acc[tm][tn]);
; #pragma unroll
;     for (int tm = 0; tm < TM; tm++) af[tm] = *(const bf16x8*)(cA + tm * 32 * LD + 16);
; #pragma unroll
;     for (int tn = 0; tn < TN; tn++) bfr[tn] = *(const bf16x8*)(cB + tn * 32 * LD + 16);
; #pragma unroll
;     for (int tm = 0; tm < TM; tm++)
; #pragma unroll
;       for (int tn = 0; tn < TN; tn++) acc[tm][tn] = MFMA(af[tm], bfr[tn], acc[tm][tn]);
;     __builtin_amdgcn_sched_group_barrier(0x8, 4, 0);
;     if (kt + 2 < nk) GEMM_GLOAD((kt + 2) * 64)
; #pragma unroll
;     for (int ks = 2; ks < 4; ks++) {
; #pragma unroll
;       for (int tm = 0; tm < TM; tm++) af[tm] = *(const bf16x8*)(cA + tm * 32 * LD + ks * 16);
; #pragma unroll
;       for (int tn = 0; tn < TN; tn++) bfr[tn] = *(const bf16x8*)(cB + tn * 32 * LD + ks * 16);
; #pragma unroll
;       for (int tm = 0; tm < TM; tm++)
; #pragma unroll
;         for (int tn = 0; tn < TN; tn++) acc[tm][tn] = MFMA(af[tm], bfr[tn], acc[tm][tn]);
;     }
;     __builtin_amdgcn_s_setprio(0);
;     __syncthreads();
;   }
	ds_read_b128 v[50:53], v36
	ds_read_b128 v[78:81], v1 offset:18432
	ds_read_b128 v[82:85], v1 offset:23040
	s_waitcnt vmcnt(1)
	ds_write_b128 v34, v[140:143] offset:9216
	ds_write_b128 v34, v[62:65] offset:13824
	ds_write_b128 v34, v[66:69] offset:36864
	ds_write_b128 v34, v[70:73] offset:41472
	ds_write_b128 v34, v[74:77] offset:46080
	s_waitcnt vmcnt(0)
	ds_write_b128 v34, v[144:147] offset:50688
	s_setprio 1
	s_waitcnt lgkmcnt(7)
	v_mfma_f32_32x32x16_bf16 v[2:17], v[50:53], v[78:81], v[2:17]
	ds_read_b128 v[54:57], v1 offset:18464
	ds_read_b128 v[58:61], v1 offset:18528
	global_load_dwordx4 v[62:65], v[38:39], off offset:1024
	global_load_dwordx4 v[66:69], v[42:43], off offset:1024
	global_load_dwordx4 v[70:73], v[44:45], off offset:1024
	global_load_dwordx4 v[74:77], v[48:49], off offset:1024
	global_load_dwordx4 v[140:143], v[40:41], off offset:1024
	global_load_dwordx4 v[144:147], v[46:47], off offset:1024
	ds_read_b128 v[78:81], v1 offset:23136
	s_waitcnt lgkmcnt(9)
	v_mfma_f32_32x32x16_bf16 v[18:33], v[50:53], v[82:85], v[18:33]
	ds_read_b128 v[50:53], v36 offset:32
	s_waitcnt lgkmcnt(0)
	v_mfma_f32_32x32x16_bf16 v[2:17], v[50:53], v[54:57], v[2:17]
	ds_read_b128 v[54:57], v1 offset:23072
	s_waitcnt lgkmcnt(0)
	v_mfma_f32_32x32x16_bf16 v[18:33], v[50:53], v[54:57], v[18:33]
	ds_read_b128 v[50:53], v36 offset:64
	ds_read_b128 v[54:57], v1 offset:18496
	s_waitcnt lgkmcnt(0)
	v_mfma_f32_32x32x16_bf16 v[2:17], v[50:53], v[54:57], v[2:17]
	ds_read_b128 v[54:57], v1 offset:23104
	s_waitcnt lgkmcnt(0)
	v_mfma_f32_32x32x16_bf16 v[18:33], v[50:53], v[54:57], v[18:33]
	ds_read_b128 v[50:53], v36 offset:96
	s_waitcnt lgkmcnt(0)
	v_mfma_f32_32x32x16_bf16 v[2:17], v[50:53], v[58:61], v[2:17]
	v_mfma_f32_32x32x16_bf16 v[18:33], v[50:53], v[78:81], v[18:33]
	s_setprio 0
	s_barrier
	ds_read_b128 v[50:53], v36 offset:9216
	ds_read_b128 v[78:81], v1 offset:36864
	ds_read_b128 v[82:85], v1 offset:41472
	s_waitcnt vmcnt(1)
	ds_write_b128 v34, v[140:143]
	ds_write_b128 v34, v[62:65] offset:4608
	ds_write_b128 v34, v[66:69] offset:18432
	ds_write_b128 v34, v[70:73] offset:23040
	ds_write_b128 v34, v[74:77] offset:27648
	s_waitcnt vmcnt(0)
	ds_write_b128 v34, v[144:147] offset:32256
	s_setprio 1
	s_waitcnt lgkmcnt(7)
	v_mfma_f32_32x32x16_bf16 v[2:17], v[50:53], v[78:81], v[2:17]
	ds_read_b128 v[54:57], v1 offset:36896
	ds_read_b128 v[58:61], v1 offset:36960
	global_load_dwordx4 v[62:65], v[38:39], off offset:1152
	global_load_dwordx4 v[66:69], v[42:43], off offset:1152
	global_load_dwordx4 v[70:73], v[44:45], off offset:1152
	global_load_dwordx4 v[74:77], v[48:49], off offset:1152
	global_load_dwordx4 v[140:143], v[40:41], off offset:1152
	global_load_dwordx4 v[144:147], v[46:47], off offset:1152
	ds_read_b128 v[78:81], v1 offset:41568
	s_waitcnt lgkmcnt(9)
	v_mfma_f32_32x32x16_bf16 v[18:33], v[50:53], v[82:85], v[18:33]
	ds_read_b128 v[50:53], v36 offset:9248
	s_waitcnt lgkmcnt(0)
	v_mfma_f32_32x32x16_bf16 v[2:17], v[50:53], v[54:57], v[2:17]
	ds_read_b128 v[54:57], v1 offset:41504
	s_waitcnt lgkmcnt(0)
	v_mfma_f32_32x32x16_bf16 v[18:33], v[50:53], v[54:57], v[18:33]
	ds_read_b128 v[50:53], v36 offset:9280
	ds_read_b128 v[54:57], v1 offset:36928
	s_waitcnt lgkmcnt(0)
	v_mfma_f32_32x32x16_bf16 v[2:17], v[50:53], v[54:57], v[2:17]
	ds_read_b128 v[54:57], v1 offset:41536
	s_waitcnt lgkmcnt(0)
	v_mfma_f32_32x32x16_bf16 v[18:33], v[50:53], v[54:57], v[18:33]
	ds_read_b128 v[50:53], v36 offset:9312
	s_waitcnt lgkmcnt(0)
	v_mfma_f32_32x32x16_bf16 v[2:17], v[50:53], v[58:61], v[2:17]
	v_mfma_f32_32x32x16_bf16 v[18:33], v[50:53], v[78:81], v[18:33]
	s_setprio 0
	s_barrier
	ds_read_b128 v[50:53], v36
	ds_read_b128 v[78:81], v1 offset:18432
	ds_read_b128 v[82:85], v1 offset:23040
	s_waitcnt vmcnt(1)
	ds_write_b128 v34, v[140:143] offset:9216
	ds_write_b128 v34, v[62:65] offset:13824
	ds_write_b128 v34, v[66:69] offset:36864
	ds_write_b128 v34, v[70:73] offset:41472
	ds_write_b128 v34, v[74:77] offset:46080
	s_waitcnt vmcnt(0)
	ds_write_b128 v34, v[144:147] offset:50688
	s_setprio 1
	s_waitcnt lgkmcnt(7)
	v_mfma_f32_32x32x16_bf16 v[2:17], v[50:53], v[78:81], v[2:17]
	ds_read_b128 v[54:57], v1 offset:18464
	ds_read_b128 v[58:61], v1 offset:18528
	global_load_dwordx4 v[62:65], v[38:39], off offset:1280
	global_load_dwordx4 v[66:69], v[42:43], off offset:1280
	global_load_dwordx4 v[70:73], v[44:45], off offset:1280
	global_load_dwordx4 v[74:77], v[48:49], off offset:1280
	global_load_dwordx4 v[140:143], v[40:41], off offset:1280
	global_load_dwordx4 v[144:147], v[46:47], off offset:1280
	ds_read_b128 v[78:81], v1 offset:23136
	s_waitcnt lgkmcnt(9)
	v_mfma_f32_32x32x16_bf16 v[18:33], v[50:53], v[82:85], v[18:33]
	ds_read_b128 v[50:53], v36 offset:32
	s_waitcnt lgkmcnt(0)
	v_mfma_f32_32x32x16_bf16 v[2:17], v[50:53], v[54:57], v[2:17]
	ds_read_b128 v[54:57], v1 offset:23072
	s_waitcnt lgkmcnt(0)
	v_mfma_f32_32x32x16_bf16 v[18:33], v[50:53], v[54:57], v[18:33]
	ds_read_b128 v[50:53], v36 offset:64
	ds_read_b128 v[54:57], v1 offset:18496
	s_waitcnt lgkmcnt(0)
	v_mfma_f32_32x32x16_bf16 v[2:17], v[50:53], v[54:57], v[2:17]
	ds_read_b128 v[54:57], v1 offset:23104
	s_waitcnt lgkmcnt(0)
	v_mfma_f32_32x32x16_bf16 v[18:33], v[50:53], v[54:57], v[18:33]
	ds_read_b128 v[50:53], v36 offset:96
	s_waitcnt lgkmcnt(0)
	v_mfma_f32_32x32x16_bf16 v[2:17], v[50:53], v[58:61], v[2:17]
	v_mfma_f32_32x32x16_bf16 v[18:33], v[50:53], v[78:81], v[18:33]
	s_setprio 0
	s_barrier
; #define MFMA(a, b, c) __builtin_amdgcn_mfma_f32_32x32x16_bf16((a), (b), (c), 0, 0, 0)
; template <int TM, int TN>
; DI void gemm_mainloop(const u16* __restrict__ A, long lda, const u16* __restrict__ Bt, long ldb, int K, char* smem,
;                       f32x16 (&acc)[TM][TN]) {
;     ...
;   for (int kt = 0; kt < nk; kt++) {
;     const int buf = kt & 1;
;     const u16* cA = sA + buf * BM * LD + (wm * 32 * TM + r) * LD + h * 8;
;     const u16* cB = sB + buf * BN * LD + (wn * 32 * TN + r) * LD + h * 8;
;     bf16x8 af[TM], bfr[TN];
; #pragma unroll
;     for (int tm = 0; tm < TM; tm++) af[tm] = *(const bf16x8*)(cA + tm * 32 * LD);
; #pragma unroll
;     for (int tn = 0; tn < TN; tn++) bfr[tn] = *(const bf16x8*)(cB + tn * 32 * LD);
;     if (kt + 1 < nk) GEMM_SSTORE(buf ^ 1)
;     __builtin_amdgcn_sched_barrier(0);
;     __builtin_amdgcn_s_setprio(1);
; #pragma unroll
;     for (int tm = 0; tm < TM; tm++)
; #pragma unroll
;       for (int tn = 0; tn < TN; tn++) acc[tm][tn] = MFMA(af[tm], bfr[tn], acc[tm][tn]);
; #pragma unroll
;     for (int tm = 0; tm < TM; tm++) af[tm] = *(const bf16x8*)(cA + tm * 32 * LD + 16);
; #pragma unroll
;     for (int tn = 0; tn < TN; tn++) bfr[tn] = *(const bf16x8*)(cB + tn * 32 * LD + 16);
; #pragma unroll
;     for (int tm = 0; tm < TM; tm++)
; #pragma unroll
;       for (int tn = 0; tn < TN; tn++) acc[tm][tn] = MFMA(af[tm], bfr[tn], acc[tm][tn]);
;     __builtin_amdgcn_sched_group_barrier(0x8, 4, 0);
;     if (kt + 2 < nk) GEMM_GLOAD((kt + 2) * 64)
; #pragma unroll
;     for (int ks = 2; ks < 4; ks++) {
; #pragma unroll
;       for (int tm = 0; tm < TM; tm++) af[tm] = *(const bf16x8*)(cA + tm * 32 * LD + ks * 16);
; #pragma unroll
;       for (int tn = 0; tn < TN; tn++) bfr[tn] = *(const bf16x8*)(cB + tn * 32 * LD + ks * 16);
; #pragma unroll
;       for (int tm = 0; tm < TM; tm++)
; #pragma unroll
;         for (int tn = 0; tn < TN; tn++) acc[tm][tn] = MFMA(af[tm], bfr[tn], acc[tm][tn]);
;     }
;     __builtin_amdgcn_s_setprio(0);
;     __syncthreads();
;   }
	ds_read_b128 v[50:53], v36 offset:9216
	ds_read_b128 v[78:81], v1 offset:36864
	ds_read_b128 v[82:85], v1 offset:41472
	s_waitcnt vmcnt(1)
	ds_write_b128 v34, v[140:143]
	ds_write_b128 v34, v[62:65] offset:4608
	ds_write_b128 v34, v[66:69] offset:18432
	ds_write_b128 v34, v[70:73] offset:23040
	ds_write_b128 v34, v[74:77] offset:27648
	s_waitcnt vmcnt(0)
	ds_write_b128 v34, v[144:147] offset:32256
	s_setprio 1
	s_waitcnt lgkmcnt(7)
	v_mfma_f32_32x32x16_bf16 v[2:17], v[50:53], v[78:81], v[2:17]
	ds_read_b128 v[54:57], v1 offset:36896
	ds_read_b128 v[58:61], v1 offset:36960
	global_load_dwordx4 v[62:65], v[38:39], off offset:1408
	global_load_dwordx4 v[66:69], v[42:43], off offset:1408
	global_load_dwordx4 v[70:73], v[44:45], off offset:1408
	global_load_dwordx4 v[74:77], v[48:49], off offset:1408
	global_load_dwordx4 v[140:143], v[40:41], off offset:1408
	global_load_dwordx4 v[144:147], v[46:47], off offset:1408
	ds_read_b128 v[78:81], v1 offset:41568
	s_waitcnt lgkmcnt(9)
	v_mfma_f32_32x32x16_bf16 v[18:33], v[50:53], v[82:85], v[18:33]
	ds_read_b128 v[50:53], v36 offset:9248
	s_waitcnt lgkmcnt(0)
	v_mfma_f32_32x32x16_bf16 v[2:17], v[50:53], v[54:57], v[2:17]
	ds_read_b128 v[54:57], v1 offset:41504
	s_waitcnt lgkmcnt(0)
	v_mfma_f32_32x32x16_bf16 v[18:33], v[50:53], v[54:57], v[18:33]
	ds_read_b128 v[50:53], v36 offset:9280
	ds_read_b128 v[54:57], v1 offset:36928
	s_waitcnt lgkmcnt(0)
	v_mfma_f32_32x32x16_bf16 v[2:17], v[50:53], v[54:57], v[2:17]
	ds_read_b128 v[54:57], v1 offset:41536
	s_waitcnt lgkmcnt(0)
	v_mfma_f32_32x32x16_bf16 v[18:33], v[50:53], v[54:57], v[18:33]
	ds_read_b128 v[50:53], v36 offset:9312
	s_waitcnt lgkmcnt(0)
	v_mfma_f32_32x32x16_bf16 v[2:17], v[50:53], v[58:61], v[2:17]
	v_mfma_f32_32x32x16_bf16 v[18:33], v[50:53], v[78:81], v[18:33]
	s_setprio 0
	s_barrier
	ds_read_b128 v[50:53], v36
	ds_read_b128 v[78:81], v1 offset:18432
	ds_read_b128 v[82:85], v1 offset:23040
	s_waitcnt vmcnt(1)
	ds_write_b128 v34, v[140:143] offset:9216
	ds_write_b128 v34, v[62:65] offset:13824
	ds_write_b128 v34, v[66:69] offset:36864
	ds_write_b128 v34, v[70:73] offset:41472
	ds_write_b128 v34, v[74:77] offset:46080
	s_waitcnt vmcnt(0)
	ds_write_b128 v34, v[144:147] offset:50688
	s_setprio 1
	s_waitcnt lgkmcnt(7)
	v_mfma_f32_32x32x16_bf16 v[2:17], v[50:53], v[78:81], v[2:17]
	ds_read_b128 v[54:57], v1 offset:18464
	ds_read_b128 v[58:61], v1 offset:18528
	global_load_dwordx4 v[62:65], v[38:39], off offset:1536
	global_load_dwordx4 v[66:69], v[42:43], off offset:1536
	global_load_dwordx4 v[70:73], v[44:45], off offset:1536
	global_load_dwordx4 v[74:77], v[48:49], off offset:1536
	global_load_dwordx4 v[140:143], v[40:41], off offset:1536
	global_load_dwordx4 v[144:147], v[46:47], off offset:1536
	ds_read_b128 v[78:81], v1 offset:23136
	s_waitcnt lgkmcnt(9)
	v_mfma_f32_32x32x16_bf16 v[18:33], v[50:53], v[82:85], v[18:33]
	ds_read_b128 v[50:53], v36 offset:32
	s_waitcnt lgkmcnt(0)
	v_mfma_f32_32x32x16_bf16 v[2:17], v[50:53], v[54:57], v[2:17]
	ds_read_b128 v[54:57], v1 offset:23072
	s_waitcnt lgkmcnt(0)
	v_mfma_f32_32x32x16_bf16 v[18:33], v[50:53], v[54:57], v[18:33]
	ds_read_b128 v[50:53], v36 offset:64
	ds_read_b128 v[54:57], v1 offset:18496
	s_waitcnt lgkmcnt(0)
	v_mfma_f32_32x32x16_bf16 v[2:17], v[50:53], v[54:57], v[2:17]
	ds_read_b128 v[54:57], v1 offset:23104
	s_waitcnt lgkmcnt(0)
	v_mfma_f32_32x32x16_bf16 v[18:33], v[50:53], v[54:57], v[18:33]
	ds_read_b128 v[50:53], v36 offset:96
	s_waitcnt lgkmcnt(0)
	v_mfma_f32_32x32x16_bf16 v[2:17], v[50:53], v[58:61], v[2:17]
	v_mfma_f32_32x32x16_bf16 v[18:33], v[50:53], v[78:81], v[18:33]
	s_setprio 0
	s_barrier
	ds_read_b128 v[50:53], v36 offset:9216
	ds_read_b128 v[78:81], v1 offset:36864
	ds_read_b128 v[82:85], v1 offset:41472
	s_waitcnt vmcnt(1)
	ds_write_b128 v34, v[140:143]
	ds_write_b128 v34, v[62:65] offset:4608
	ds_write_b128 v34, v[66:69] offset:18432
	ds_write_b128 v34, v[70:73] offset:23040
	ds_write_b128 v34, v[74:77] offset:27648
	s_waitcnt vmcnt(0)
	ds_write_b128 v34, v[144:147] offset:32256
	s_setprio 1
	s_waitcnt lgkmcnt(7)
	v_mfma_f32_32x32x16_bf16 v[2:17], v[50:53], v[78:81], v[2:17]
	ds_read_b128 v[54:57], v1 offset:36896
	ds_read_b128 v[58:61], v1 offset:36960
	global_load_dwordx4 v[62:65], v[38:39], off offset:1664
	global_load_dwordx4 v[66:69], v[42:43], off offset:1664
	global_load_dwordx4 v[70:73], v[44:45], off offset:1664
	global_load_dwordx4 v[74:77], v[48:49], off offset:1664
	global_load_dwordx4 v[140:143], v[40:41], off offset:1664
	global_load_dwordx4 v[144:147], v[46:47], off offset:1664
	ds_read_b128 v[78:81], v1 offset:41568
	s_waitcnt lgkmcnt(9)
	v_mfma_f32_32x32x16_bf16 v[18:33], v[50:53], v[82:85], v[18:33]
	ds_read_b128 v[50:53], v36 offset:9248
	s_waitcnt lgkmcnt(0)
	v_mfma_f32_32x32x16_bf16 v[2:17], v[50:53], v[54:57], v[2:17]
	ds_read_b128 v[54:57], v1 offset:41504
	s_waitcnt lgkmcnt(0)
	v_mfma_f32_32x32x16_bf16 v[18:33], v[50:53], v[54:57], v[18:33]
	ds_read_b128 v[50:53], v36 offset:9280
	ds_read_b128 v[54:57], v1 offset:36928
	s_waitcnt lgkmcnt(0)
	v_mfma_f32_32x32x16_bf16 v[2:17], v[50:53], v[54:57], v[2:17]
	ds_read_b128 v[54:57], v1 offset:41536
	s_waitcnt lgkmcnt(0)
	v_mfma_f32_32x32x16_bf16 v[18:33], v[50:53], v[54:57], v[18:33]
	ds_read_b128 v[50:53], v36 offset:9312
	s_waitcnt lgkmcnt(0)
	v_mfma_f32_32x32x16_bf16 v[2:17], v[50:53], v[58:61], v[2:17]
	v_mfma_f32_32x32x16_bf16 v[18:33], v[50:53], v[78:81], v[18:33]
	s_setprio 0
	s_barrier
; #define MFMA(a, b, c) __builtin_amdgcn_mfma_f32_32x32x16_bf16((a), (b), (c), 0, 0, 0)
; template <int TM, int TN>
; DI void gemm_mainloop(const u16* __restrict__ A, long lda, const u16* __restrict__ Bt, long ldb, int K, char* smem,
;                       f32x16 (&acc)[TM][TN]) {
;     ...
;   for (int kt = 0; kt < nk; kt++) {
;     const int buf = kt & 1;
;     const u16* cA = sA + buf * BM * LD + (wm * 32 * TM + r) * LD + h * 8;
;     const u16* cB = sB + buf * BN * LD + (wn * 32 * TN + r) * LD + h * 8;
;     bf16x8 af[TM], bfr[TN];
; #pragma unroll
;     for (int tm = 0; tm < TM; tm++) af[tm] = *(const bf16x8*)(cA + tm * 32 * LD);
; #pragma unroll
;     for (int tn = 0; tn < TN; tn++) bfr[tn] = *(const bf16x8*)(cB + tn * 32 * LD);
;     if (kt + 1 < nk) GEMM_SSTORE(buf ^ 1)
;     __builtin_amdgcn_sched_barrier(0);
;     __builtin_amdgcn_s_setprio(1);
; #pragma unroll
;     for (int tm = 0; tm < TM; tm++)
; #pragma unroll
;       for (int tn = 0; tn < TN; tn++) acc[tm][tn] = MFMA(af[tm], bfr[tn], acc[tm][tn]);
; #pragma unroll
;     for (int tm = 0; tm < TM; tm++) af[tm] = *(const bf16x8*)(cA + tm * 32 * LD + 16);
; #pragma unroll
;     for (int tn = 0; tn < TN; tn++) bfr[tn] = *(const bf16x8*)(cB + tn * 32 * LD + 16);
; #pragma unroll
;     for (int tm = 0; tm < TM; tm++)
; #pragma unroll
;       for (int tn = 0; tn < TN; tn++) acc[tm][tn] = MFMA(af[tm], bfr[tn], acc[tm][tn]);
;     __builtin_amdgcn_sched_group_barrier(0x8, 4, 0);
;     if (kt + 2 < nk) GEMM_GLOAD((kt + 2) * 64)
; #pragma unroll
;     for (int ks = 2; ks < 4; ks++) {
; #pragma unroll
;       for (int tm = 0; tm < TM; tm++) af[tm] = *(const bf16x8*)(cA + tm * 32 * LD + ks * 16);
; #pragma unroll
;       for (int tn = 0; tn < TN; tn++) bfr[tn] = *(const bf16x8*)(cB + tn * 32 * LD + ks * 16);
; #pragma unroll
;       for (int tm = 0; tm < TM; tm++)
; #pragma unroll
;         for (int tn = 0; tn < TN; tn++) acc[tm][tn] = MFMA(af[tm], bfr[tn], acc[tm][tn]);
;     }
;     __builtin_amdgcn_s_setprio(0);
;     __syncthreads();
;   }
	ds_read_b128 v[50:53], v36
	ds_read_b128 v[78:81], v1 offset:18432
	ds_read_b128 v[82:85], v1 offset:23040
	s_waitcnt vmcnt(1)
	ds_write_b128 v34, v[140:143] offset:9216
	ds_write_b128 v34, v[62:65] offset:13824
	ds_write_b128 v34, v[66:69] offset:36864
	ds_write_b128 v34, v[70:73] offset:41472
	ds_write_b128 v34, v[74:77] offset:46080
	s_waitcnt vmcnt(0)
	ds_write_b128 v34, v[144:147] offset:50688
	s_setprio 1
	s_waitcnt lgkmcnt(7)
	v_mfma_f32_32x32x16_bf16 v[2:17], v[50:53], v[78:81], v[2:17]
	ds_read_b128 v[54:57], v1 offset:18464
	ds_read_b128 v[58:61], v1 offset:18528
	global_load_dwordx4 v[62:65], v[38:39], off offset:1792
	global_load_dwordx4 v[66:69], v[42:43], off offset:1792
	global_load_dwordx4 v[70:73], v[44:45], off offset:1792
	global_load_dwordx4 v[74:77], v[48:49], off offset:1792
	global_load_dwordx4 v[140:143], v[40:41], off offset:1792
	global_load_dwordx4 v[144:147], v[46:47], off offset:1792
	ds_read_b128 v[78:81], v1 offset:23136
	s_waitcnt lgkmcnt(9)
	v_mfma_f32_32x32x16_bf16 v[18:33], v[50:53], v[82:85], v[18:33]
	ds_read_b128 v[50:53], v36 offset:32
	s_waitcnt lgkmcnt(0)
	v_mfma_f32_32x32x16_bf16 v[2:17], v[50:53], v[54:57], v[2:17]
	ds_read_b128 v[54:57], v1 offset:23072
	s_waitcnt lgkmcnt(0)
	v_mfma_f32_32x32x16_bf16 v[18:33], v[50:53], v[54:57], v[18:33]
	ds_read_b128 v[50:53], v36 offset:64
	ds_read_b128 v[54:57], v1 offset:18496
	s_waitcnt lgkmcnt(0)
	v_mfma_f32_32x32x16_bf16 v[2:17], v[50:53], v[54:57], v[2:17]
	ds_read_b128 v[54:57], v1 offset:23104
	s_waitcnt lgkmcnt(0)
	v_mfma_f32_32x32x16_bf16 v[18:33], v[50:53], v[54:57], v[18:33]
	ds_read_b128 v[50:53], v36 offset:96
	s_waitcnt lgkmcnt(0)
	v_mfma_f32_32x32x16_bf16 v[2:17], v[50:53], v[58:61], v[2:17]
	v_mfma_f32_32x32x16_bf16 v[18:33], v[50:53], v[78:81], v[18:33]
	s_setprio 0
	s_barrier
	ds_read_b128 v[50:53], v36 offset:9216
	ds_read_b128 v[78:81], v1 offset:36864
	ds_read_b128 v[82:85], v1 offset:41472
	s_waitcnt vmcnt(1)
	ds_write_b128 v34, v[140:143]
	ds_write_b128 v34, v[62:65] offset:4608
	ds_write_b128 v34, v[66:69] offset:18432
	ds_write_b128 v34, v[70:73] offset:23040
	ds_write_b128 v34, v[74:77] offset:27648
	s_waitcnt vmcnt(0)
	ds_write_b128 v34, v[144:147] offset:32256
	s_setprio 1
	s_waitcnt lgkmcnt(7)
	v_mfma_f32_32x32x16_bf16 v[2:17], v[50:53], v[78:81], v[2:17]
	ds_read_b128 v[54:57], v1 offset:36896
	global_load_dwordx4 v[62:65], v[38:39], off offset:1920
	global_load_dwordx4 v[66:69], v[42:43], off offset:1920
	global_load_dwordx4 v[70:73], v[44:45], off offset:1920
	global_load_dwordx4 v[74:77], v[48:49], off offset:1920
	global_load_dwordx4 v[140:143], v[40:41], off offset:1920
	global_load_dwordx4 v[144:147], v[46:47], off offset:1920
	ds_read_b128 v[58:61], v1 offset:36960
	ds_read_b128 v[42:45], v1 offset:41568
	s_waitcnt lgkmcnt(9)
	v_mfma_f32_32x32x16_bf16 v[18:33], v[50:53], v[82:85], v[18:33]
	ds_read_b128 v[50:53], v36 offset:9248
	s_waitcnt lgkmcnt(0)
	v_mfma_f32_32x32x16_bf16 v[2:17], v[50:53], v[54:57], v[2:17]
	ds_read_b128 v[54:57], v1 offset:41504
	s_waitcnt lgkmcnt(0)
	v_mfma_f32_32x32x16_bf16 v[18:33], v[50:53], v[54:57], v[18:33]
	ds_read_b128 v[50:53], v36 offset:9280
	ds_read_b128 v[54:57], v1 offset:36928
	s_waitcnt lgkmcnt(0)
	v_mfma_f32_32x32x16_bf16 v[2:17], v[50:53], v[54:57], v[2:17]
	ds_read_b128 v[54:57], v1 offset:41536
	s_waitcnt lgkmcnt(0)
	v_mfma_f32_32x32x16_bf16 v[18:33], v[50:53], v[54:57], v[18:33]
	ds_read_b128 v[50:53], v36 offset:9312
	s_waitcnt lgkmcnt(0)
	v_mfma_f32_32x32x16_bf16 v[2:17], v[50:53], v[58:61], v[2:17]
	v_mfma_f32_32x32x16_bf16 v[18:33], v[50:53], v[42:45], v[18:33]
	s_setprio 0
	s_barrier
	ds_read_b128 v[42:45], v36
	ds_read_b128 v[46:49], v1 offset:18432
	ds_read_b128 v[50:53], v1 offset:23040
	s_waitcnt vmcnt(1)
	ds_write_b128 v34, v[140:143] offset:9216
	ds_write_b128 v34, v[62:65] offset:13824
	ds_write_b128 v34, v[66:69] offset:36864
	ds_write_b128 v34, v[70:73] offset:41472
	ds_write_b128 v34, v[74:77] offset:46080
	s_waitcnt vmcnt(0)
	ds_write_b128 v34, v[144:147] offset:50688
	s_setprio 1
	ds_read_b128 v[38:41], v36 offset:32
	s_waitcnt lgkmcnt(8)
	v_mfma_f32_32x32x16_bf16 v[2:17], v[42:45], v[46:49], v[2:17]
	s_waitcnt lgkmcnt(7)
	v_mfma_f32_32x32x16_bf16 v[18:33], v[42:45], v[50:53], v[18:33]
	ds_read_b128 v[42:45], v1 offset:18464
	s_waitcnt lgkmcnt(0)
	v_mfma_f32_32x32x16_bf16 v[2:17], v[38:41], v[42:45], v[2:17]
	ds_read_b128 v[42:45], v1 offset:23072
	s_waitcnt lgkmcnt(0)
	v_mfma_f32_32x32x16_bf16 v[18:33], v[38:41], v[42:45], v[18:33]
	ds_read_b128 v[38:41], v36 offset:64
	ds_read_b128 v[42:45], v1 offset:18496
	s_waitcnt lgkmcnt(0)
	v_mfma_f32_32x32x16_bf16 v[2:17], v[38:41], v[42:45], v[2:17]
	ds_read_b128 v[42:45], v1 offset:23104
	s_waitcnt lgkmcnt(0)
	v_mfma_f32_32x32x16_bf16 v[18:33], v[38:41], v[42:45], v[18:33]
	ds_read_b128 v[38:41], v36 offset:96
	ds_read_b128 v[42:45], v1 offset:18528
	s_waitcnt lgkmcnt(0)
	v_mfma_f32_32x32x16_bf16 v[2:17], v[38:41], v[42:45], v[2:17]
	ds_read_b128 v[42:45], v1 offset:23136
	s_waitcnt lgkmcnt(0)
	v_mfma_f32_32x32x16_bf16 v[18:33], v[38:41], v[42:45], v[18:33]
	s_setprio 0
	s_barrier
; template <int TM, int TN>
; DI void gemm_mainloop(const u16* __restrict__ A, long lda, const u16* __restrict__ Bt, long ldb, int K, char* smem,
;                       f32x16 (&acc)[TM][TN]) {
;     ...
;   for (int kt = 0; kt < nk; kt++) {
;     const int buf = kt & 1;
;     const u16* cA = sA + buf * BM * LD + (wm * 32 * TM + r) * LD + h * 8;
;     const u16* cB = sB + buf * BN * LD + (wn * 32 * TN + r) * LD + h * 8;
;     bf16x8 af[TM], bfr[TN];
; #pragma unroll
;     for (int tm = 0; tm < TM; tm++) af[tm] = *(const bf16x8*)(cA + tm * 32 * LD);
; #pragma unroll
;     for (int tn = 0; tn < TN; tn++) bfr[tn] = *(const bf16x8*)(cB + tn * 32 * LD);
;     if (kt + 1 < nk) GEMM_SSTORE(buf ^ 1)
;     __builtin_amdgcn_sched_barrier(0);
;     __builtin_amdgcn_s_setprio(1);
; #pragma unroll
;     for (int tm = 0; tm < TM; tm++)
; #pragma unroll
;       for (int tn = 0; tn < TN; tn++) acc[tm][tn] = MFMA(af[tm], bfr[tn], acc[tm][tn]);
; #pragma unroll
;     for (int tm = 0; tm < TM; tm++) af[tm] = *(const bf16x8*)(cA + tm * 32 * LD + 16);
; #pragma unroll
;     for (int tn = 0; tn < TN; tn++) bfr[tn] = *(const bf16x8*)(cB + tn * 32 * LD + 16);
; #pragma unroll
;     for (int tm = 0; tm < TM; tm++)
; #pragma unroll
;       for (int tn = 0; tn < TN; tn++) acc[tm][tn] = MFMA(af[tm], bfr[tn], acc[tm][tn]);
;     __builtin_amdgcn_sched_group_barrier(0x8, 4, 0);
;     if (kt + 2 < nk) GEMM_GLOAD((kt + 2) * 64)
; #pragma unroll
;     for (int ks = 2; ks < 4; ks++) {
; #pragma unroll
;       for (int tm = 0; tm < TM; tm++) af[tm] = *(const bf16x8*)(cA + tm * 32 * LD + ks * 16);
; #pragma unroll
;       for (int tn = 0; tn < TN; tn++) bfr[tn] = *(const bf16x8*)(cB + tn * 32 * LD + ks * 16);
; #pragma unroll
;       for (int tm = 0; tm < TM; tm++)
; #pragma unroll
;         for (int tn = 0; tn < TN; tn++) acc[tm][tn] = MFMA(af[tm], bfr[tn], acc[tm][tn]);
;     }
;     __builtin_amdgcn_s_setprio(0);
;     __syncthreads();
;   }
; template <int TM, int TN, class Epi>
; DI void gemm_tile(const u16* A, long lda, const u16* Bt, long ldb, int K, int m0, int n0, char* smem, const Epi& epi) {
;     ...
; #pragma unroll
;   for (int tm = 0; tm < TM; tm++)
; #pragma unroll
;     for (int tn = 0; tn < TN; tn++)
; #pragma unroll
;       for (int i = 0; i < 16; i++)
;         Ct[(wm * 32 * TM + tm * 32 + crow(i, h)) * LDC + wn * 32 * TN + tn * 32 + r] = acc[tm][tn][i];
;   __syncthreads();
	ds_read_b128 v[38:41], v36 offset:9216
	ds_read_b128 v[42:45], v1 offset:36864
	ds_read_b128 v[46:49], v1 offset:41472
	s_setprio 1
	s_waitcnt lgkmcnt(1)
	v_mfma_f32_32x32x16_bf16 v[2:17], v[38:41], v[42:45], v[2:17]
	ds_read_b128 v[42:45], v1 offset:36896
	s_waitcnt lgkmcnt(1)
	v_mfma_f32_32x32x16_bf16 v[18:33], v[38:41], v[46:49], v[18:33]
	ds_read_b128 v[38:41], v36 offset:9248
	s_waitcnt lgkmcnt(0)
	v_mfma_f32_32x32x16_bf16 v[2:17], v[38:41], v[42:45], v[2:17]
	ds_read_b128 v[42:45], v1 offset:41504
	s_waitcnt lgkmcnt(0)
	v_mfma_f32_32x32x16_bf16 v[18:33], v[38:41], v[42:45], v[18:33]
	ds_read_b128 v[38:41], v36 offset:9280
	ds_read_b128 v[42:45], v1 offset:36928
	s_waitcnt lgkmcnt(0)
	v_mfma_f32_32x32x16_bf16 v[2:17], v[38:41], v[42:45], v[2:17]
	ds_read_b128 v[42:45], v1 offset:41536
	s_waitcnt lgkmcnt(0)
	v_mfma_f32_32x32x16_bf16 v[18:33], v[38:41], v[42:45], v[18:33]
	ds_read_b128 v[36:39], v36 offset:9312
	ds_read_b128 v[40:43], v1 offset:36960
	s_waitcnt lgkmcnt(0)
	v_mfma_f32_32x32x16_bf16 v[2:17], v[36:39], v[40:43], v[2:17]
	ds_read_b128 v[40:43], v1 offset:41568
	s_waitcnt lgkmcnt(0)
	v_mfma_f32_32x32x16_bf16 v[18:33], v[36:39], v[40:43], v[18:33]
	s_setprio 0
	v_mov_b32_e32 v1, v0
	s_barrier
	s_lshl_b32 s8, s14, 1
	v_lshrrev_b32_e32 v36, 3, v1
	v_lshrrev_b32_e32 v34, 2, v1
	v_and_b32_e32 v36, 4, v36
	v_and_or_b32 v34, v34, s3, v36
	s_movk_i32 s3, 0x210
	v_and_b32_e32 v36, 0x5f, v1
	v_mul_lo_u32 v34, v34, s3
	v_lshl_add_u32 v34, v36, 2, v34
	ds_write2_b32 v34, v2, v18 offset1:32
	v_add_u32_e32 v2, 0x400, v34
	ds_write2_b32 v2, v4, v20 offset0:8 offset1:40
	ds_write2_b32 v2, v5, v21 offset0:140 offset1:172
	v_add_u32_e32 v2, 0x1000, v34
	ds_write2_b32 v2, v6, v22 offset0:32 offset1:64
	ds_write2_b32 v2, v7, v23 offset0:164 offset1:196
	v_add_u32_e32 v2, 0x1400, v34
	ds_write2_b32 v2, v8, v24 offset0:40 offset1:72
	ds_write2_b32 v2, v9, v25 offset0:172 offset1:204
	v_add_u32_e32 v2, 0x2000, v34
	ds_write2_b32 v2, v10, v26 offset0:64 offset1:96
	ds_write2_b32 v2, v11, v27 offset0:196 offset1:228
	v_add_u32_e32 v2, 0x2400, v34
	ds_write2_b32 v2, v12, v28 offset0:72 offset1:104
	ds_write2_b32 v2, v13, v29 offset0:204 offset1:236
	v_add_u32_e32 v2, 0x3000, v34
	ds_write2_b32 v2, v14, v30 offset0:96 offset1:128
	v_add_u32_e32 v2, 0x3200, v34
	ds_write2_b32 v2, v15, v31 offset0:100 offset1:132
	v_add_u32_e32 v2, 0x3400, v34
	ds_write2_b32 v2, v16, v32 offset0:104 offset1:136
	v_add_u32_e32 v2, 0x3600, v34
	ds_write2_b32 v2, v17, v33 offset0:108 offset1:140
	v_lshlrev_b32_e32 v2, 3, v1
	v_ashrrev_i32_e32 v7, 4, v1
	v_and_b32_e32 v6, 0x78, v2
	v_add_u32_e32 v2, s11, v7
	v_mov_b64_e32 v[14:15], s[6:7]
	ds_write2_b32 v34, v3, v19 offset0:132 offset1:164
	v_mad_i64_i32 v[2:3], s[4:5], v2, s10, v[14:15]
	v_lshl_add_u64 v[2:3], v[2:3], 0, s[8:9]
	v_lshlrev_b32_e32 v34, 1, v6
	v_lshl_add_u64 v[16:17], v[2:3], 0, v[34:35]
	s_waitcnt lgkmcnt(0)
	s_barrier
	global_load_dwordx4 v[2:5], v[16:17], off
	v_add_u32_e32 v8, 0x100, v1
	v_ashrrev_i32_e32 v19, 4, v8
	v_lshlrev_b32_e32 v18, 2, v6
	v_add_u32_e32 v6, s11, v19
	v_mad_u64_u32 v[10:11], s[4:5], v7, s3, v[18:19]
	v_mad_i64_i32 v[6:7], s[4:5], v6, s10, v[14:15]
	v_lshl_add_u64 v[6:7], v[6:7], 0, s[8:9]
	v_lshl_add_u64 v[20:21], v[6:7], 0, v[34:35]
	ds_read_b128 v[6:9], v10
	ds_read_b128 v[10:13], v10 offset:16
	s_waitcnt vmcnt(0)
	v_lshlrev_b32_e32 v22, 16, v2
	v_and_b32_e32 v23, 0xffff0000, v2
	v_lshlrev_b32_e32 v2, 16, v3
	v_and_b32_e32 v3, 0xffff0000, v3
	v_lshlrev_b32_e32 v24, 16, v4
	v_and_b32_e32 v25, 0xffff0000, v4
	v_lshlrev_b32_e32 v4, 16, v5
	v_and_b32_e32 v5, 0xffff0000, v5
	s_waitcnt lgkmcnt(1)
	v_pk_add_f32 v[6:7], v[6:7], v[22:23]
	v_pk_add_f32 v[8:9], v[8:9], v[2:3]
	s_waitcnt lgkmcnt(0)
	v_pk_add_f32 v[10:11], v[10:11], v[24:25]
	v_pk_add_f32 v[12:13], v[12:13], v[4:5]
	v_cvt_pk_bf16_f32 v2, v6, v7
	v_cvt_pk_bf16_f32 v3, v8, v9
	v_cvt_pk_bf16_f32 v4, v10, v11
	v_cvt_pk_bf16_f32 v5, v12, v13
	global_store_dwordx4 v[16:17], v[2:5], off
	global_load_dwordx4 v[2:5], v[20:21], off
	v_add_u32_e32 v6, 0x200, v1
	v_ashrrev_i32_e32 v26, 4, v6
	v_add_u32_e32 v6, s11, v26
	v_mad_i64_i32 v[6:7], s[4:5], v6, s10, v[14:15]
	v_mad_u64_u32 v[10:11], s[4:5], v19, s3, v[18:19]
	v_lshl_add_u64 v[6:7], v[6:7], 0, s[8:9]
	v_lshl_add_u64 v[16:17], v[6:7], 0, v[34:35]
	ds_read_b128 v[6:9], v10
	ds_read_b128 v[10:13], v10 offset:16
	v_add_u32_e32 v1, 0x300, v1
	v_ashrrev_i32_e32 v1, 4, v1
	s_waitcnt vmcnt(0)
	v_lshlrev_b32_e32 v22, 16, v2
	v_and_b32_e32 v23, 0xffff0000, v2
	v_lshlrev_b32_e32 v2, 16, v3
	v_and_b32_e32 v3, 0xffff0000, v3
	v_lshlrev_b32_e32 v24, 16, v4
	v_and_b32_e32 v25, 0xffff0000, v4
	v_lshlrev_b32_e32 v4, 16, v5
	v_and_b32_e32 v5, 0xffff0000, v5
	s_waitcnt lgkmcnt(1)
	v_pk_add_f32 v[6:7], v[6:7], v[22:23]
	v_pk_add_f32 v[8:9], v[8:9], v[2:3]
	s_waitcnt lgkmcnt(0)
	v_pk_add_f32 v[10:11], v[10:11], v[24:25]
	v_pk_add_f32 v[12:13], v[12:13], v[4:5]
	v_cvt_pk_bf16_f32 v2, v6, v7
	v_cvt_pk_bf16_f32 v3, v8, v9
	v_cvt_pk_bf16_f32 v4, v10, v11
	v_cvt_pk_bf16_f32 v5, v12, v13
	global_store_dwordx4 v[20:21], v[2:5], off
	global_load_dwordx4 v[2:5], v[16:17], off
	v_add_u32_e32 v6, s11, v1
	v_mad_i64_i32 v[6:7], s[4:5], v6, s10, v[14:15]
	v_mad_u64_u32 v[10:11], s[4:5], v26, s3, v[18:19]
	v_lshl_add_u64 v[6:7], v[6:7], 0, s[8:9]
	v_lshl_add_u64 v[14:15], v[6:7], 0, v[34:35]
	ds_read_b128 v[6:9], v10
	ds_read_b128 v[10:13], v10 offset:16
	s_waitcnt vmcnt(0)
	v_lshlrev_b32_e32 v20, 16, v2
	v_and_b32_e32 v21, 0xffff0000, v2
	v_lshlrev_b32_e32 v2, 16, v3
	v_and_b32_e32 v3, 0xffff0000, v3
	v_lshlrev_b32_e32 v22, 16, v4
	v_and_b32_e32 v23, 0xffff0000, v4
	v_lshlrev_b32_e32 v4, 16, v5
	v_and_b32_e32 v5, 0xffff0000, v5
	s_waitcnt lgkmcnt(1)
	v_pk_add_f32 v[6:7], v[6:7], v[20:21]
	v_pk_add_f32 v[8:9], v[8:9], v[2:3]
	s_waitcnt lgkmcnt(0)
	v_pk_add_f32 v[10:11], v[10:11], v[22:23]
	v_pk_add_f32 v[12:13], v[12:13], v[4:5]
	v_cvt_pk_bf16_f32 v2, v6, v7
	v_cvt_pk_bf16_f32 v3, v8, v9
	v_cvt_pk_bf16_f32 v4, v10, v11
	v_cvt_pk_bf16_f32 v5, v12, v13
	global_store_dwordx4 v[16:17], v[2:5], off
	global_load_dwordx4 v[2:5], v[14:15], off
	v_mad_u64_u32 v[10:11], s[4:5], v1, s3, v[18:19]
	ds_read_b128 v[6:9], v10
	ds_read_b128 v[10:13], v10 offset:16
	s_waitcnt vmcnt(0)
	v_lshlrev_b32_e32 v16, 16, v2
	v_and_b32_e32 v17, 0xffff0000, v2
	v_lshlrev_b32_e32 v2, 16, v3
	v_and_b32_e32 v3, 0xffff0000, v3
	v_lshlrev_b32_e32 v18, 16, v4
	v_and_b32_e32 v19, 0xffff0000, v4
	v_lshlrev_b32_e32 v4, 16, v5
	v_and_b32_e32 v5, 0xffff0000, v5
	s_waitcnt lgkmcnt(1)
	v_pk_add_f32 v[6:7], v[6:7], v[16:17]
	v_pk_add_f32 v[8:9], v[8:9], v[2:3]
	s_waitcnt lgkmcnt(0)
	v_pk_add_f32 v[10:11], v[10:11], v[18:19]
	v_pk_add_f32 v[12:13], v[12:13], v[4:5]
	v_cvt_pk_bf16_f32 v2, v6, v7
	v_cvt_pk_bf16_f32 v3, v8, v9
	v_cvt_pk_bf16_f32 v4, v10, v11
	v_cvt_pk_bf16_f32 v5, v12, v13
	global_store_dwordx4 v[14:15], v[2:5], off
	s_barrier

; #define MFMA(a, b, c) __builtin_amdgcn_mfma_f32_32x32x16_bf16((a), (b), (c), 0, 0, 0)
; template <int TM, int TN>
; DI void gemm_mainloop(const u16* __restrict__ A, long lda, const u16* __restrict__ Bt, long ldb, int K, char* smem,
;                       f32x16 (&acc)[TM][TN]) {
;     ...
;   for (int kt = 0; kt < nk; kt++) {
;     const int buf = kt & 1;
;     const u16* cA = sA + buf * BM * LD + (wm * 32 * TM + r) * LD + h * 8;
;     const u16* cB = sB + buf * BN * LD + (wn * 32 * TN + r) * LD + h * 8;
;     bf16x8 af[TM], bfr[TN];
; #pragma unroll
;     for (int tm = 0; tm < TM; tm++) af[tm] = *(const bf16x8*)(cA + tm * 32 * LD);
; #pragma unroll
;     for (int tn = 0; tn < TN; tn++) bfr[tn] = *(const bf16x8*)(cB + tn * 32 * LD);
;     if (kt + 1 < nk) GEMM_SSTORE(buf ^ 1)
;     __builtin_amdgcn_sched_barrier(0);
;     __builtin_amdgcn_s_setprio(1);
; #pragma unroll
;     for (int tm = 0; tm < TM; tm++)
; #pragma unroll
;       for (int tn = 0; tn < TN; tn++) acc[tm][tn] = MFMA(af[tm], bfr[tn], acc[tm][tn]);
; #pragma unroll
;     for (int tm = 0; tm < TM; tm++) af[tm] = *(const bf16x8*)(cA + tm * 32 * LD + 16);
; #pragma unroll
;     for (int tn = 0; tn < TN; tn++) bfr[tn] = *(const bf16x8*)(cB + tn * 32 * LD + 16);
; #pragma unroll
;     for (int tm = 0; tm < TM; tm++)
; #pragma unroll
;       for (int tn = 0; tn < TN; tn++) acc[tm][tn] = MFMA(af[tm], bfr[tn], acc[tm][tn]);
;     __builtin_amdgcn_sched_group_barrier(0x8, 4, 0);
;     if (kt + 2 < nk) GEMM_GLOAD((kt + 2) * 64)
; #pragma unroll
;     for (int ks = 2; ks < 4; ks++) {
; #pragma unroll
;       for (int tm = 0; tm < TM; tm++) af[tm] = *(const bf16x8*)(cA + tm * 32 * LD + ks * 16);
; #pragma unroll
;       for (int tn = 0; tn < TN; tn++) bfr[tn] = *(const bf16x8*)(cB + tn * 32 * LD + ks * 16);
; #pragma unroll
;       for (int tm = 0; tm < TM; tm++)
; #pragma unroll
;         for (int tn = 0; tn < TN; tn++) acc[tm][tn] = MFMA(af[tm], bfr[tn], acc[tm][tn]);
;     }
;     __builtin_amdgcn_s_setprio(0);
;     __syncthreads();
;   }
.LBB0_1413:
	s_and_b32 s5, s4, 1
	s_mul_i32 s50, s5, 0x4800
	v_add_u32_e32 v109, s50, v102
	v_add_u32_e32 v126, s50, v98
	s_lshl_b32 s5, s5, 7
	ds_read_b128 v[110:113], v109
	ds_read_b128 v[114:117], v109 offset:4608
	ds_read_b128 v[118:121], v126 offset:36864
	ds_read_b128 v[122:125], v126 offset:41472
	s_xor_b32 s5, s5, 0x80
	s_mulk_i32 s5, 0x90
	s_add_i32 s4, s4, 1
	v_add_u32_e32 v127, s5, v108
	s_waitcnt vmcnt(7)
	ds_write_b128 v127, v[70:73]
	s_waitcnt vmcnt(6)
	ds_write_b128 v127, v[74:77] offset:4608
	s_waitcnt vmcnt(5)
	ds_write_b128 v127, v[66:69] offset:9216
	s_waitcnt vmcnt(4)
	ds_write_b128 v127, v[78:81] offset:13824
	s_waitcnt vmcnt(3)
	ds_write_b128 v127, v[82:85] offset:36864
	s_waitcnt vmcnt(2)
	ds_write_b128 v127, v[86:89] offset:41472
	s_waitcnt vmcnt(1)
	ds_write_b128 v127, v[90:93] offset:46080
	s_waitcnt vmcnt(0)
	ds_write_b128 v127, v[94:97] offset:50688
	s_setprio 1
	ds_read_b128 v[66:69], v109 offset:32
	s_waitcnt lgkmcnt(10)
	v_mfma_f32_32x32x16_bf16 v[50:65], v[110:113], v[118:121], v[50:65]
	ds_read_b128 v[70:73], v126 offset:36896
	ds_read_b128 v[74:77], v126 offset:41504
	ds_read_b128 v[86:89], v109 offset:4672
	ds_read_b128 v[78:81], v126 offset:36928
	v_lshl_add_u64 v[90:91], v[106:107], 0, s[16:17]
	ds_read_b128 v[82:85], v126 offset:41536
	ds_read_b128 v[94:97], v126 offset:36960
	s_waitcnt lgkmcnt(14)
	v_mfma_f32_32x32x16_bf16 v[34:49], v[110:113], v[122:125], v[34:49]
	ds_read_b128 v[110:113], v126 offset:41568
	s_waitcnt lgkmcnt(6)
	v_mfma_f32_32x32x16_bf16 v[50:65], v[66:69], v[70:73], v[50:65]
	s_waitcnt lgkmcnt(5)
	v_mfma_f32_32x32x16_bf16 v[34:49], v[66:69], v[74:77], v[34:49]
	ds_read_b128 v[66:69], v109 offset:4640
	v_mfma_f32_32x32x16_bf16 v[18:33], v[114:117], v[118:121], v[18:33]
	v_lshl_add_u64 v[118:119], v[104:105], 0, s[16:17]
	v_mfma_f32_32x32x16_bf16 v[2:17], v[114:117], v[122:125], v[2:17]
	ds_read_b128 v[114:117], v109 offset:4704
	s_waitcnt lgkmcnt(1)
	v_mfma_f32_32x32x16_bf16 v[18:33], v[66:69], v[70:73], v[18:33]
	v_add_co_u32_e32 v70, vcc, s30, v90
	s_nop 1
	v_addc_co_u32_e32 v71, vcc, 0, v91, vcc
	global_load_dwordx4 v[70:73], v[70:71], off offset:2304
	v_mfma_f32_32x32x16_bf16 v[2:17], v[66:69], v[74:77], v[2:17]
	ds_read_b128 v[66:69], v109 offset:64
	v_add_co_u32_e32 v74, vcc, s31, v90
	s_nop 1
	v_addc_co_u32_e32 v75, vcc, 0, v91, vcc
	global_load_dwordx4 v[74:77], v[74:75], off offset:2304
	s_waitcnt lgkmcnt(0)
	v_mfma_f32_32x32x16_bf16 v[50:65], v[66:69], v[78:81], v[50:65]
	v_mfma_f32_32x32x16_bf16 v[34:49], v[66:69], v[82:85], v[34:49]
	v_add_co_u32_e32 v66, vcc, s36, v90
	s_nop 1
	v_addc_co_u32_e32 v67, vcc, 0, v91, vcc
	global_load_dwordx4 v[66:69], v[66:67], off offset:2304
	v_mfma_f32_32x32x16_bf16 v[18:33], v[86:89], v[78:81], v[18:33]
	v_add_co_u32_e32 v78, vcc, s37, v90
	s_nop 1
	v_addc_co_u32_e32 v79, vcc, 0, v91, vcc
	ds_read_b128 v[90:93], v109 offset:96
	global_load_dwordx4 v[78:81], v[78:79], off offset:2304
	v_mfma_f32_32x32x16_bf16 v[2:17], v[86:89], v[82:85], v[2:17]
	v_add_co_u32_e32 v82, vcc, s38, v118
	s_nop 1
	v_addc_co_u32_e32 v83, vcc, 0, v119, vcc
	v_add_co_u32_e32 v86, vcc, s39, v118
	global_load_dwordx4 v[82:85], v[82:83], off offset:256
	s_nop 0
	v_addc_co_u32_e32 v87, vcc, 0, v119, vcc
	v_add_co_u32_e32 v120, vcc, s40, v118
	s_waitcnt lgkmcnt(0)
	v_mfma_f32_32x32x16_bf16 v[50:65], v[90:93], v[94:97], v[50:65]
	v_addc_co_u32_e32 v121, vcc, 0, v119, vcc
	v_add_co_u32_e32 v118, vcc, s41, v118
	global_load_dwordx4 v[86:89], v[86:87], off offset:256
	s_nop 0
	v_addc_co_u32_e32 v119, vcc, 0, v119, vcc
	v_mfma_f32_32x32x16_bf16 v[34:49], v[90:93], v[110:113], v[34:49]
	global_load_dwordx4 v[90:93], v[120:121], off offset:256
	v_mfma_f32_32x32x16_bf16 v[18:33], v[114:117], v[94:97], v[18:33]
	global_load_dwordx4 v[94:97], v[118:119], off offset:256
	v_mfma_f32_32x32x16_bf16 v[2:17], v[114:117], v[110:113], v[2:17]
	s_setprio 0
	s_add_u32 s16, s16, 0x80
	s_addc_u32 s17, s17, 0
	s_cmpk_eq_i32 s16, 0x1f00
	s_barrier
	s_cbranch_scc0 .LBB0_1413
	ds_read_b128 v[104:107], v102
	ds_read_b128 v[110:113], v102 offset:4608
	ds_read_b128 v[114:117], v98 offset:36864
	ds_read_b128 v[118:121], v98 offset:41472
	s_waitcnt vmcnt(7)
	ds_write_b128 v108, v[70:73] offset:18432
	s_waitcnt vmcnt(6)
	ds_write_b128 v108, v[74:77] offset:23040
	s_waitcnt vmcnt(5)
	ds_write_b128 v108, v[66:69] offset:27648
	s_waitcnt vmcnt(4)
	ds_write_b128 v108, v[78:81] offset:32256
	s_waitcnt vmcnt(3)
	ds_write_b128 v108, v[82:85] offset:55296
	s_waitcnt vmcnt(2)
	ds_write_b128 v108, v[86:89] offset:59904
	s_waitcnt vmcnt(1)
	ds_write_b128 v108, v[90:93] offset:64512
	s_waitcnt vmcnt(0)
	ds_write_b128 v103, v[94:97] offset:32256
	s_setprio 1
	ds_read_b128 v[66:69], v102 offset:32
	s_waitcnt lgkmcnt(10)
	v_mfma_f32_32x32x16_bf16 v[50:65], v[104:107], v[114:117], v[50:65]
	ds_read_b128 v[70:73], v98 offset:36896
	ds_read_b128 v[74:77], v98 offset:41504
	s_waitcnt lgkmcnt(11)
	v_mfma_f32_32x32x16_bf16 v[34:49], v[104:107], v[118:121], v[34:49]
	s_waitcnt lgkmcnt(1)
	v_mfma_f32_32x32x16_bf16 v[50:65], v[66:69], v[70:73], v[50:65]
	s_waitcnt lgkmcnt(0)
	v_mfma_f32_32x32x16_bf16 v[34:49], v[66:69], v[74:77], v[34:49]
	ds_read_b128 v[66:69], v102 offset:4640
	v_mfma_f32_32x32x16_bf16 v[18:33], v[110:113], v[114:117], v[18:33]
	v_mfma_f32_32x32x16_bf16 v[2:17], v[110:113], v[118:121], v[2:17]
	s_waitcnt lgkmcnt(0)
	v_mfma_f32_32x32x16_bf16 v[18:33], v[66:69], v[70:73], v[18:33]
	ds_read_b128 v[70:73], v98 offset:36928
	v_mfma_f32_32x32x16_bf16 v[2:17], v[66:69], v[74:77], v[2:17]
	ds_read_b128 v[66:69], v102 offset:64
	ds_read_b128 v[74:77], v98 offset:41536
	s_waitcnt lgkmcnt(1)
	v_mfma_f32_32x32x16_bf16 v[50:65], v[66:69], v[70:73], v[50:65]
	s_waitcnt lgkmcnt(0)
	v_mfma_f32_32x32x16_bf16 v[34:49], v[66:69], v[74:77], v[34:49]
	ds_read_b128 v[66:69], v102 offset:4672
	s_waitcnt lgkmcnt(0)
	v_mfma_f32_32x32x16_bf16 v[18:33], v[66:69], v[70:73], v[18:33]
	ds_read_b128 v[70:73], v98 offset:36960
	v_mfma_f32_32x32x16_bf16 v[2:17], v[66:69], v[74:77], v[2:17]
	ds_read_b128 v[66:69], v102 offset:96
	ds_read_b128 v[74:77], v98 offset:41568
	s_waitcnt lgkmcnt(1)
	v_mfma_f32_32x32x16_bf16 v[50:65], v[66:69], v[70:73], v[50:65]
	s_waitcnt lgkmcnt(0)
	v_mfma_f32_32x32x16_bf16 v[34:49], v[66:69], v[74:77], v[34:49]
	ds_read_b128 v[66:69], v102 offset:4704
	s_waitcnt lgkmcnt(0)
	v_mfma_f32_32x32x16_bf16 v[2:17], v[66:69], v[74:77], v[2:17]
	v_mfma_f32_32x32x16_bf16 v[18:33], v[66:69], v[70:73], v[18:33]
	s_setprio 0
	s_barrier
; DI int crow(int i, int h) { return (i & 3) + 8 * (i >> 2) + 4 * h; }
; template <int TM, int TN, class Epi>
; DI void gemm_tile(const u16* A, long lda, const u16* Bt, long ldb, int K, int m0, int n0, char* smem, const Epi& epi) {
;     ...
; #pragma unroll
;   for (int tm = 0; tm < TM; tm++)
; #pragma unroll
;     for (int tn = 0; tn < TN; tn++)
; #pragma unroll
;       for (int i = 0; i < 16; i++)
;         Ct[(wm * 32 * TM + tm * 32 + crow(i, h)) * LDC + wn * 32 * TN + tn * 32 + r] = acc[tm][tn][i];
;   __syncthreads();
;   DI void operator()(const float* Ct, int ldc, int m0, int n0, int tid, int bm) const {
;     ...
;     for (int it = 0; it < bm / 16; it++) {
;       int id = tid + 256 * it; int row = id >> 4, c8 = (id & 15) * 8;
;       int m = m0 + row;
;       const float* c = Ct + row * ldc + c8;
;       float4 a = *(const float4*)c, b = *(const float4*)(c + 4);
;       float x[8];
;       if (srcb != nullptr) {
;         unpack8(*(const uint4*)(srcb + (size_t)m * LDA + n0 + c8), x);
	ds_read_b128 v[66:69], v102 offset:18432
	ds_read_b128 v[70:73], v102 offset:23040
	ds_read_b128 v[74:77], v98 offset:55296
	ds_read_b128 v[78:81], v98 offset:59904
	s_setprio 1
	s_waitcnt lgkmcnt(1)
	v_mfma_f32_32x32x16_bf16 v[50:65], v[66:69], v[74:77], v[50:65]
	s_waitcnt lgkmcnt(0)
	v_mfma_f32_32x32x16_bf16 v[34:49], v[66:69], v[78:81], v[34:49]
	ds_read_b128 v[66:69], v102 offset:18464
	v_mfma_f32_32x32x16_bf16 v[18:33], v[70:73], v[74:77], v[18:33]
	ds_read_b128 v[74:77], v98 offset:59936
	v_mfma_f32_32x32x16_bf16 v[2:17], v[70:73], v[78:81], v[2:17]
	ds_read_b128 v[70:73], v98 offset:55328
	s_waitcnt lgkmcnt(0)
	v_mfma_f32_32x32x16_bf16 v[50:65], v[66:69], v[70:73], v[50:65]
	v_mfma_f32_32x32x16_bf16 v[34:49], v[66:69], v[74:77], v[34:49]
	ds_read_b128 v[66:69], v102 offset:23072
	s_waitcnt lgkmcnt(0)
	v_mfma_f32_32x32x16_bf16 v[18:33], v[66:69], v[70:73], v[18:33]
	ds_read_b128 v[70:73], v98 offset:55360
	v_mfma_f32_32x32x16_bf16 v[2:17], v[66:69], v[74:77], v[2:17]
	ds_read_b128 v[66:69], v102 offset:18496
	ds_read_b128 v[74:77], v98 offset:59968
	s_waitcnt lgkmcnt(1)
	v_mfma_f32_32x32x16_bf16 v[50:65], v[66:69], v[70:73], v[50:65]
	s_waitcnt lgkmcnt(0)
	v_mfma_f32_32x32x16_bf16 v[34:49], v[66:69], v[74:77], v[34:49]
	ds_read_b128 v[66:69], v102 offset:23104
	s_waitcnt lgkmcnt(0)
	v_mfma_f32_32x32x16_bf16 v[18:33], v[66:69], v[70:73], v[18:33]
	ds_read_b128 v[70:73], v98 offset:55392
	v_mfma_f32_32x32x16_bf16 v[2:17], v[66:69], v[74:77], v[2:17]
	ds_read_b128 v[66:69], v102 offset:18528
	ds_read_b128 v[74:77], v98 offset:60000
	s_waitcnt lgkmcnt(1)
	v_mfma_f32_32x32x16_bf16 v[50:65], v[66:69], v[70:73], v[50:65]
	s_waitcnt lgkmcnt(0)
	v_mfma_f32_32x32x16_bf16 v[34:49], v[66:69], v[74:77], v[34:49]
	ds_read_b128 v[66:69], v102 offset:23136
	s_waitcnt lgkmcnt(0)
	v_mfma_f32_32x32x16_bf16 v[2:17], v[66:69], v[74:77], v[2:17]
	v_mfma_f32_32x32x16_bf16 v[18:33], v[66:69], v[70:73], v[18:33]
	s_setprio 0
	v_mov_b32_e32 v66, v0
	s_barrier
	s_mov_b32 s4, 0
	v_lshrrev_b32_e32 v67, 1, v66
	v_and_b32_e32 v67, 0xfffffc0, v67
	v_lshrrev_b32_e32 v68, 3, v66
	v_and_or_b32 v67, v68, 4, v67
	v_and_b32_e32 v68, 0x5f, v66
	v_mul_lo_u32 v67, v67, s42
	v_lshl_add_u32 v67, v68, 2, v67
	ds_write2_b32 v67, v50, v34 offset1:32
	v_add_u32_e32 v34, 0x400, v67
	ds_write2_b32 v34, v52, v36 offset0:8 offset1:40
	ds_write2_b32 v34, v53, v37 offset0:140 offset1:172
	v_add_u32_e32 v34, 0x1000, v67
	ds_write2_b32 v34, v54, v38 offset0:32 offset1:64
	ds_write2_b32 v34, v55, v39 offset0:164 offset1:196
	v_add_u32_e32 v34, 0x1400, v67
	ds_write2_b32 v34, v56, v40 offset0:40 offset1:72
	ds_write2_b32 v34, v57, v41 offset0:172 offset1:204
	v_add_u32_e32 v34, 0x2000, v67
	ds_write2_b32 v34, v58, v42 offset0:64 offset1:96
	ds_write2_b32 v34, v59, v43 offset0:196 offset1:228
	v_add_u32_e32 v34, 0x2400, v67
	ds_write2_b32 v34, v60, v44 offset0:72 offset1:104
	ds_write2_b32 v34, v61, v45 offset0:204 offset1:236
	v_add_u32_e32 v34, 0x3000, v67
	ds_write2_b32 v34, v62, v46 offset0:96 offset1:128
	v_add_u32_e32 v34, 0x3200, v67
	ds_write2_b32 v34, v63, v47 offset0:100 offset1:132
	v_add_u32_e32 v34, 0x3400, v67
	ds_write2_b32 v34, v64, v48 offset0:104 offset1:136
	v_add_u32_e32 v34, 0x3600, v67
	ds_write2_b32 v34, v65, v49 offset0:108 offset1:140
	v_add_u32_e32 v34, 0x4000, v67
	ds_write2_b32 v34, v18, v2 offset0:128 offset1:160
	v_add_u32_e32 v2, 0x4400, v67
	ds_write2_b32 v2, v19, v3 offset0:4 offset1:36
	ds_write2_b32 v2, v20, v4 offset0:136 offset1:168
	v_add_u32_e32 v2, 0x4800, v67
	ds_write2_b32 v2, v21, v5 offset0:12 offset1:44
	v_add_u32_e32 v2, 0x5000, v67
	ds_write2_b32 v2, v22, v6 offset0:160 offset1:192
	v_add_u32_e32 v2, 0x5400, v67
	ds_write2_b32 v2, v23, v7 offset0:36 offset1:68
	ds_write2_b32 v2, v24, v8 offset0:168 offset1:200
	v_add_u32_e32 v2, 0x5800, v67
	ds_write2_b32 v2, v25, v9 offset0:44 offset1:76
	v_add_u32_e32 v2, 0x6000, v67
	ds_write2_b32 v2, v26, v10 offset0:192 offset1:224
	v_add_u32_e32 v2, 0x6400, v67
	ds_write2_b32 v2, v27, v11 offset0:68 offset1:100
	ds_write2_b32 v2, v28, v12 offset0:200 offset1:232
	v_add_u32_e32 v2, 0x6800, v67
	ds_write2_b32 v2, v29, v13 offset0:76 offset1:108
	v_add_u32_e32 v2, 0x7200, v67
	ds_write2_b32 v2, v30, v14 offset0:96 offset1:128
	v_add_u32_e32 v2, 0x7400, v67
	ds_write2_b32 v2, v31, v15 offset0:100 offset1:132
	v_add_u32_e32 v2, 0x7600, v67
	ds_write2_b32 v2, v32, v16 offset0:104 offset1:136
	v_add_u32_e32 v2, 0x7800, v67
	ds_write2_b32 v2, v33, v17 offset0:108 offset1:140
	v_lshlrev_b32_e32 v2, 3, v66
	v_and_b32_e32 v3, 0x78, v2
	v_lshlrev_b32_e32 v98, 1, v3
	v_lshlrev_b32_e32 v2, 2, v3
	v_lshl_add_u64 v[4:5], s[10:11], 0, v[98:99]
	ds_write2_b32 v67, v51, v35 offset0:132 offset1:164
	v_ashrrev_i32_e32 v190, 4, v66
	v_add_u32_e32 v190, s49, v190
	v_mad_i64_i32 v[192:193], vcc, v190, s43, v[4:5]
	global_load_dwordx4 v[150:153], v[192:193], off
	v_add_u32_e32 v191, 16, v190
	v_mad_i64_i32 v[192:193], vcc, v191, s43, v[4:5]
	global_load_dwordx4 v[154:157], v[192:193], off
	v_add_u32_e32 v191, 32, v190
	v_mad_i64_i32 v[192:193], vcc, v191, s43, v[4:5]
	global_load_dwordx4 v[158:161], v[192:193], off
	v_add_u32_e32 v191, 48, v190
	v_mad_i64_i32 v[192:193], vcc, v191, s43, v[4:5]
	global_load_dwordx4 v[162:165], v[192:193], off
	v_add_u32_e32 v191, 64, v190
	v_mad_i64_i32 v[192:193], vcc, v191, s43, v[4:5]
	global_load_dwordx4 v[166:169], v[192:193], off
	v_add_u32_e32 v191, 80, v190
	v_mad_i64_i32 v[192:193], vcc, v191, s43, v[4:5]
	global_load_dwordx4 v[170:173], v[192:193], off
	v_add_u32_e32 v191, 96, v190
	v_mad_i64_i32 v[192:193], vcc, v191, s43, v[4:5]
	global_load_dwordx4 v[174:177], v[192:193], off
	v_add_u32_e32 v191, 112, v190
	v_mad_i64_i32 v[192:193], vcc, v191, s43, v[4:5]
	global_load_dwordx4 v[178:181], v[192:193], off
	s_waitcnt lgkmcnt(0)
	s_barrier
;   DI void operator()(const float* Ct, int ldc, int m0, int n0, int tid, int bm) const {
;     ...
;     for (int it = 0; it < bm / 16; it++) {
;       int id = tid + 256 * it; int row = id >> 4, c8 = (id & 15) * 8;
;       int m = m0 + row;
;       const float* c = Ct + row * ldc + c8;
;       float4 a = *(const float4*)c, b = *(const float4*)(c + 4);
;       float x[8];
;       if (srcb != nullptr) {
;         unpack8(*(const uint4*)(srcb + (size_t)m * LDA + n0 + c8), x);
;       } else {
;         const float* sp = (m < NP ? src0 + (size_t)m * 1024 : src1 + (size_t)(m - NP) * 1024) + n0 + c8;
;         float4 sa = *(const float4*)sp, sb = *(const float4*)(sp + 4);
;         x[0] = sa.x; x[1] = sa.y; x[2] = sa.z; x[3] = sa.w; x[4] = sb.x; x[5] = sb.y; x[6] = sb.z; x[7] = sb.w;
;       }
;       x[0] += a.x; x[1] += a.y; x[2] += a.z; x[3] += a.w; x[4] += b.x; x[5] += b.y; x[6] += b.z; x[7] += b.w;
;       if (dstf != nullptr) {
;         float* o = dstf + (size_t)m * 1024 + n0 + c8;
;         *(float4*)o = make_float4(x[0], x[1], x[2], x[3]); *(float4*)(o + 4) = make_float4(x[4], x[5], x[6], x[7]);
;       } else {
;         *(uint4*)(dstb + (size_t)m * LDA + n0 + c8) = pack8(x);
;       }
.LBB0_1415:
	v_add_u32_e32 v3, s4, v66
	v_ashrrev_i32_e32 v10, 4, v3
	v_add_u32_e32 v6, s49, v10
	v_mad_i64_i32 v[18:19], s[16:17], v6, s43, v[4:5]
	v_add_u32_e32 v11, 0x100, v3
	v_mad_u64_u32 v[14:15], s[16:17], v10, s42, v[2:3]
	v_ashrrev_i32_e32 v26, 4, v11
	ds_read_b128 v[10:13], v14
	ds_read_b128 v[14:17], v14 offset:16
	v_add_u32_e32 v20, s49, v26
	v_mad_i64_i32 v[20:21], s[16:17], v20, s43, v[4:5]
	s_addk_i32 s4, 0x400
	s_cmpk_lg_i32 s4, 0x800
	s_waitcnt vmcnt(7)
	v_mov_b64_e32 v[6:7], v[150:151]
	v_mov_b64_e32 v[8:9], v[152:153]
	v_lshlrev_b32_e32 v22, 16, v6
	v_and_b32_e32 v23, 0xffff0000, v6
	v_lshlrev_b32_e32 v6, 16, v7
	v_and_b32_e32 v7, 0xffff0000, v7
	v_lshlrev_b32_e32 v24, 16, v8
	v_and_b32_e32 v25, 0xffff0000, v8
	v_lshlrev_b32_e32 v8, 16, v9
	v_and_b32_e32 v9, 0xffff0000, v9
	s_waitcnt lgkmcnt(1)
	v_pk_add_f32 v[10:11], v[10:11], v[22:23]
	v_pk_add_f32 v[12:13], v[12:13], v[6:7]
	s_waitcnt lgkmcnt(0)
	v_pk_add_f32 v[14:15], v[14:15], v[24:25]
	v_pk_add_f32 v[16:17], v[16:17], v[8:9]
	v_cvt_pk_bf16_f32 v6, v10, v11
	v_cvt_pk_bf16_f32 v7, v12, v13
	v_cvt_pk_bf16_f32 v8, v14, v15
	v_cvt_pk_bf16_f32 v9, v16, v17
	global_store_dwordx4 v[18:19], v[6:9], off
	v_add_u32_e32 v10, 0x200, v3
	v_mad_u64_u32 v[14:15], s[16:17], v26, s42, v[2:3]
	v_ashrrev_i32_e32 v27, 4, v10
	ds_read_b128 v[10:13], v14
	ds_read_b128 v[14:17], v14 offset:16
	v_add_u32_e32 v18, s49, v27
	v_mad_i64_i32 v[18:19], s[16:17], v18, s43, v[4:5]
	v_add_u32_e32 v3, 0x300, v3
	v_ashrrev_i32_e32 v3, 4, v3
	s_waitcnt vmcnt(7)
	v_mov_b64_e32 v[6:7], v[154:155]
	v_mov_b64_e32 v[8:9], v[156:157]
	v_lshlrev_b32_e32 v22, 16, v6
	v_and_b32_e32 v23, 0xffff0000, v6
	v_lshlrev_b32_e32 v6, 16, v7
	v_and_b32_e32 v7, 0xffff0000, v7
	v_lshlrev_b32_e32 v24, 16, v8
	v_and_b32_e32 v25, 0xffff0000, v8
	v_lshlrev_b32_e32 v8, 16, v9
	v_and_b32_e32 v9, 0xffff0000, v9
	s_waitcnt lgkmcnt(1)
	v_pk_add_f32 v[10:11], v[10:11], v[22:23]
	v_pk_add_f32 v[12:13], v[12:13], v[6:7]
	s_waitcnt lgkmcnt(0)
	v_pk_add_f32 v[14:15], v[14:15], v[24:25]
	v_pk_add_f32 v[16:17], v[16:17], v[8:9]
	v_cvt_pk_bf16_f32 v6, v10, v11
	v_cvt_pk_bf16_f32 v7, v12, v13
	v_cvt_pk_bf16_f32 v8, v14, v15
	v_cvt_pk_bf16_f32 v9, v16, v17
	global_store_dwordx4 v[20:21], v[6:9], off
	v_mad_u64_u32 v[14:15], s[16:17], v27, s42, v[2:3]
	ds_read_b128 v[10:13], v14
	ds_read_b128 v[14:17], v14 offset:16
	v_add_u32_e32 v20, s49, v3
	v_mad_i64_i32 v[20:21], s[16:17], v20, s43, v[4:5]
	s_waitcnt vmcnt(7)
	v_mov_b64_e32 v[6:7], v[158:159]
	v_mov_b64_e32 v[8:9], v[160:161]
	v_lshlrev_b32_e32 v22, 16, v6
	v_and_b32_e32 v23, 0xffff0000, v6
	v_lshlrev_b32_e32 v6, 16, v7
	v_and_b32_e32 v7, 0xffff0000, v7
	v_lshlrev_b32_e32 v24, 16, v8
	v_and_b32_e32 v25, 0xffff0000, v8
	v_lshlrev_b32_e32 v8, 16, v9
	v_and_b32_e32 v9, 0xffff0000, v9
	s_waitcnt lgkmcnt(1)
	v_pk_add_f32 v[10:11], v[10:11], v[22:23]
	v_pk_add_f32 v[12:13], v[12:13], v[6:7]
	s_waitcnt lgkmcnt(0)
	v_pk_add_f32 v[14:15], v[14:15], v[24:25]
	v_pk_add_f32 v[16:17], v[16:17], v[8:9]
	v_cvt_pk_bf16_f32 v6, v10, v11
	v_cvt_pk_bf16_f32 v7, v12, v13
	v_cvt_pk_bf16_f32 v8, v14, v15
	v_cvt_pk_bf16_f32 v9, v16, v17
	global_store_dwordx4 v[18:19], v[6:9], off
	v_mad_u64_u32 v[14:15], s[16:17], v3, s42, v[2:3]
	ds_read_b128 v[10:13], v14
	ds_read_b128 v[14:17], v14 offset:16
	s_waitcnt vmcnt(7)
	v_mov_b64_e32 v[6:7], v[162:163]
	v_mov_b64_e32 v[8:9], v[164:165]
	v_lshlrev_b32_e32 v18, 16, v6
	v_and_b32_e32 v19, 0xffff0000, v6
	v_lshlrev_b32_e32 v6, 16, v7
	v_and_b32_e32 v7, 0xffff0000, v7
	v_lshlrev_b32_e32 v22, 16, v8
	v_and_b32_e32 v23, 0xffff0000, v8
	v_lshlrev_b32_e32 v8, 16, v9
	v_and_b32_e32 v9, 0xffff0000, v9
	s_waitcnt lgkmcnt(1)
	v_pk_add_f32 v[10:11], v[10:11], v[18:19]
	v_pk_add_f32 v[12:13], v[12:13], v[6:7]
	s_waitcnt lgkmcnt(0)
	v_pk_add_f32 v[14:15], v[14:15], v[22:23]
	v_pk_add_f32 v[16:17], v[16:17], v[8:9]
	v_cvt_pk_bf16_f32 v6, v10, v11
	v_cvt_pk_bf16_f32 v7, v12, v13
	v_cvt_pk_bf16_f32 v8, v14, v15
	v_cvt_pk_bf16_f32 v9, v16, v17
	global_store_dwordx4 v[20:21], v[6:9], off
	v_add_u32_e32 v3, s4, v66
	v_ashrrev_i32_e32 v10, 4, v3
	v_add_u32_e32 v6, s49, v10
	v_mad_i64_i32 v[18:19], s[16:17], v6, s43, v[4:5]
	v_add_u32_e32 v11, 0x100, v3
	v_mad_u64_u32 v[14:15], s[16:17], v10, s42, v[2:3]
	v_ashrrev_i32_e32 v26, 4, v11
	ds_read_b128 v[10:13], v14
	ds_read_b128 v[14:17], v14 offset:16
	v_add_u32_e32 v20, s49, v26
	v_mad_i64_i32 v[20:21], s[16:17], v20, s43, v[4:5]
	s_addk_i32 s4, 0x400
	s_cmpk_lg_i32 s4, 0x800
	s_waitcnt vmcnt(7)
	v_mov_b64_e32 v[6:7], v[166:167]
	v_mov_b64_e32 v[8:9], v[168:169]
	v_lshlrev_b32_e32 v22, 16, v6
	v_and_b32_e32 v23, 0xffff0000, v6
	v_lshlrev_b32_e32 v6, 16, v7
	v_and_b32_e32 v7, 0xffff0000, v7
	v_lshlrev_b32_e32 v24, 16, v8
	v_and_b32_e32 v25, 0xffff0000, v8
	v_lshlrev_b32_e32 v8, 16, v9
	v_and_b32_e32 v9, 0xffff0000, v9
	s_waitcnt lgkmcnt(1)
	v_pk_add_f32 v[10:11], v[10:11], v[22:23]
	v_pk_add_f32 v[12:13], v[12:13], v[6:7]
	s_waitcnt lgkmcnt(0)
	v_pk_add_f32 v[14:15], v[14:15], v[24:25]
	v_pk_add_f32 v[16:17], v[16:17], v[8:9]
	v_cvt_pk_bf16_f32 v6, v10, v11
	v_cvt_pk_bf16_f32 v7, v12, v13
	v_cvt_pk_bf16_f32 v8, v14, v15
	v_cvt_pk_bf16_f32 v9, v16, v17
	global_store_dwordx4 v[18:19], v[6:9], off
	v_add_u32_e32 v10, 0x200, v3
	v_mad_u64_u32 v[14:15], s[16:17], v26, s42, v[2:3]
	v_ashrrev_i32_e32 v27, 4, v10
	ds_read_b128 v[10:13], v14
	ds_read_b128 v[14:17], v14 offset:16
	v_add_u32_e32 v18, s49, v27
	v_mad_i64_i32 v[18:19], s[16:17], v18, s43, v[4:5]
	v_add_u32_e32 v3, 0x300, v3
	v_ashrrev_i32_e32 v3, 4, v3
	s_waitcnt vmcnt(7)
; template <int TM, int TN>
; DI void gemm_mainloop(const u16* __restrict__ A, long lda, const u16* __restrict__ Bt, long ldb, int K, char* smem,
;                       f32x16 (&acc)[TM][TN]) {
;     ...
;   const int lrow = tid >> 3, lch = (tid & 7) * 8;
;   const u16* gA = A + (long)lrow * lda + lch;
;   const u16* gB = Bt + (long)lrow * ldb + lch;
;   const int soff = lrow * LD + lch;
;     ...
;   GEMM_GLOAD(0)
;   __syncthreads();
;   GEMM_SSTORE(0)
;   if (nk > 1) GEMM_GLOAD(64)
;   __syncthreads();
;   DI void operator()(const float* Ct, int ldc, int m0, int n0, int tid, int bm) const {
;     ...
;     for (int it = 0; it < bm / 16; it++) {
;       int id = tid + 256 * it; int row = id >> 4, c8 = (id & 15) * 8;
;       int m = m0 + row;
;       const float* c = Ct + row * ldc + c8;
;       float4 a = *(const float4*)c, b = *(const float4*)(c + 4);
;       float x[8];
;       if (srcb != nullptr) {
;         unpack8(*(const uint4*)(srcb + (size_t)m * LDA + n0 + c8), x);
;       } else {
;         const float* sp = (m < NP ? src0 + (size_t)m * 1024 : src1 + (size_t)(m - NP) * 1024) + n0 + c8;
;         float4 sa = *(const float4*)sp, sb = *(const float4*)(sp + 4);
;         x[0] = sa.x; x[1] = sa.y; x[2] = sa.z; x[3] = sa.w; x[4] = sb.x; x[5] = sb.y; x[6] = sb.z; x[7] = sb.w;
;       }
;       x[0] += a.x; x[1] += a.y; x[2] += a.z; x[3] += a.w; x[4] += b.x; x[5] += b.y; x[6] += b.z; x[7] += b.w;
;       if (dstf != nullptr) {
;         float* o = dstf + (size_t)m * 1024 + n0 + c8;
;         *(float4*)o = make_float4(x[0], x[1], x[2], x[3]); *(float4*)(o + 4) = make_float4(x[4], x[5], x[6], x[7]);
;       } else {
;         *(uint4*)(dstb + (size_t)m * LDA + n0 + c8) = pack8(x);
;       }
	v_mov_b64_e32 v[6:7], v[170:171]
	v_mov_b64_e32 v[8:9], v[172:173]
	v_lshlrev_b32_e32 v22, 16, v6
	v_and_b32_e32 v23, 0xffff0000, v6
	v_lshlrev_b32_e32 v6, 16, v7
	v_and_b32_e32 v7, 0xffff0000, v7
	v_lshlrev_b32_e32 v24, 16, v8
	v_and_b32_e32 v25, 0xffff0000, v8
	v_lshlrev_b32_e32 v8, 16, v9
	v_and_b32_e32 v9, 0xffff0000, v9
	s_waitcnt lgkmcnt(1)
	v_pk_add_f32 v[10:11], v[10:11], v[22:23]
	v_pk_add_f32 v[12:13], v[12:13], v[6:7]
	s_waitcnt lgkmcnt(0)
	v_pk_add_f32 v[14:15], v[14:15], v[24:25]
	v_pk_add_f32 v[16:17], v[16:17], v[8:9]
	v_cvt_pk_bf16_f32 v6, v10, v11
	v_cvt_pk_bf16_f32 v7, v12, v13
	v_cvt_pk_bf16_f32 v8, v14, v15
	v_cvt_pk_bf16_f32 v9, v16, v17
	global_store_dwordx4 v[20:21], v[6:9], off
	v_mad_u64_u32 v[14:15], s[16:17], v27, s42, v[2:3]
	ds_read_b128 v[10:13], v14
	ds_read_b128 v[14:17], v14 offset:16
	v_add_u32_e32 v20, s49, v3
	v_mad_i64_i32 v[20:21], s[16:17], v20, s43, v[4:5]
	s_waitcnt vmcnt(7)
	v_mov_b64_e32 v[6:7], v[174:175]
	v_mov_b64_e32 v[8:9], v[176:177]
	v_lshlrev_b32_e32 v22, 16, v6
	v_and_b32_e32 v23, 0xffff0000, v6
	v_lshlrev_b32_e32 v6, 16, v7
	v_and_b32_e32 v7, 0xffff0000, v7
	v_lshlrev_b32_e32 v24, 16, v8
	v_and_b32_e32 v25, 0xffff0000, v8
	v_lshlrev_b32_e32 v8, 16, v9
	v_and_b32_e32 v9, 0xffff0000, v9
	s_waitcnt lgkmcnt(1)
	v_pk_add_f32 v[10:11], v[10:11], v[22:23]
	v_pk_add_f32 v[12:13], v[12:13], v[6:7]
	s_waitcnt lgkmcnt(0)
	v_pk_add_f32 v[14:15], v[14:15], v[24:25]
	v_pk_add_f32 v[16:17], v[16:17], v[8:9]
	v_cvt_pk_bf16_f32 v6, v10, v11
	v_cvt_pk_bf16_f32 v7, v12, v13
	v_cvt_pk_bf16_f32 v8, v14, v15
	v_cvt_pk_bf16_f32 v9, v16, v17
	global_store_dwordx4 v[18:19], v[6:9], off
	v_mad_u64_u32 v[14:15], s[16:17], v3, s42, v[2:3]
	ds_read_b128 v[10:13], v14
	ds_read_b128 v[14:17], v14 offset:16
	s_waitcnt vmcnt(7)
	v_mov_b64_e32 v[6:7], v[178:179]
	v_mov_b64_e32 v[8:9], v[180:181]
	v_lshlrev_b32_e32 v18, 16, v6
	v_and_b32_e32 v19, 0xffff0000, v6
	v_lshlrev_b32_e32 v6, 16, v7
	v_and_b32_e32 v7, 0xffff0000, v7
	v_lshlrev_b32_e32 v22, 16, v8
	v_and_b32_e32 v23, 0xffff0000, v8
	v_lshlrev_b32_e32 v8, 16, v9
	v_and_b32_e32 v9, 0xffff0000, v9
	s_waitcnt lgkmcnt(1)
	v_pk_add_f32 v[10:11], v[10:11], v[18:19]
	v_pk_add_f32 v[12:13], v[12:13], v[6:7]
	s_waitcnt lgkmcnt(0)
	v_pk_add_f32 v[14:15], v[14:15], v[22:23]
	v_pk_add_f32 v[16:17], v[16:17], v[8:9]
	v_cvt_pk_bf16_f32 v6, v10, v11
	v_cvt_pk_bf16_f32 v7, v12, v13
	v_cvt_pk_bf16_f32 v8, v14, v15
	v_cvt_pk_bf16_f32 v9, v16, v17
	global_store_dwordx4 v[20:21], v[6:9], off
	s_add_i32 s4, s48, 8
	s_addk_i32 s23, 0x2000
	s_cmp_lt_u32 s48, 24
	s_mov_b32 s48, s4
	s_barrier
	s_cbranch_scc1 .LBB0_1412
	s_lshl_b32 s4, s79, 6
	s_add_i32 s4, s80, s4
	s_cmpk_gt_i32 s4, 0xff
	s_cbranch_scc1 .LBB0_1421
	s_ashr_i32 s5, s4, 4
	s_and_b32 s10, s5, 0x1fffff8
	s_bfe_u32 s15, s4, 0x30004
	s_or_b32 s4, s10, s15
	s_lshl_b32 s10, s80, 6
	s_lshl_b32 s4, s4, 7
	s_and_b32 s22, s10, 64
	s_or_b32 s14, s4, s22
	s_add_i32 s14, s14, 0x8000
	s_and_b32 s4, s10, 0x380
	s_mul_i32 s11, s14, 0x2080
	s_mul_hi_i32 s10, s14, 0x2080
	s_add_u32 s16, s19, s11
	v_mov_b32_e32 v1, v0
	s_addc_u32 s17, s20, s10
	s_mul_i32 s10, s4, 0x2080
	s_movk_i32 s23, 0x2080
	v_lshlrev_b32_e32 v2, 3, v1
	s_add_u32 s20, s3, s10
	v_ashrrev_i32_e32 v65, 3, v1
	v_and_b32_e32 v64, 56, v2
	v_mov_b64_e32 v[2:3], s[16:17]
	s_addc_u32 s21, s18, 0
	v_mad_i64_i32 v[4:5], s[16:17], v65, s23, v[2:3]
	v_lshlrev_b32_e32 v2, 1, v64
	v_mov_b32_e32 v3, 0
	v_lshl_add_u64 v[28:29], v[4:5], 0, v[2:3]
	v_mov_b64_e32 v[4:5], s[20:21]
	s_mov_b32 s3, 0x41000
	v_mad_i64_i32 v[12:13], s[16:17], v65, s23, v[4:5]
	v_add_co_u32_e32 v30, vcc, s3, v28
	v_lshl_add_u64 v[32:33], v[12:13], 0, v[2:3]
	s_nop 0
	v_addc_co_u32_e32 v31, vcc, 0, v29, vcc
	v_add_co_u32_e32 v58, vcc, s3, v32
	s_mov_b32 s3, 0x82000
	s_nop 0
	v_addc_co_u32_e32 v59, vcc, 0, v33, vcc
	v_add_co_u32_e32 v60, vcc, s3, v32
	s_mov_b32 s3, 0xc3000
	s_nop 0
	v_addc_co_u32_e32 v61, vcc, 0, v33, vcc
	v_add_co_u32_e32 v62, vcc, s3, v32
	global_load_dwordx4 v[4:7], v[28:29], off
	global_load_dwordx4 v[8:11], v[30:31], off
	global_load_dwordx4 v[12:15], v[32:33], off
	global_load_dwordx4 v[16:19], v[58:59], off
	v_addc_co_u32_e32 v63, vcc, 0, v33, vcc
	global_load_dwordx4 v[20:23], v[60:61], off
	global_load_dwordx4 v[24:27], v[62:63], off
	s_barrier
	global_load_dwordx4 v[34:37], v[28:29], off offset:128
	global_load_dwordx4 v[50:53], v[30:31], off offset:128
	global_load_dwordx4 v[46:49], v[32:33], off offset:128
	global_load_dwordx4 v[42:45], v[58:59], off offset:128
	global_load_dwordx4 v[38:41], v[60:61], off offset:128
	global_load_dwordx4 v[54:57], v[62:63], off offset:128
	s_movk_i32 s3, 0x48
	v_and_b32_e32 v2, 31, v1
	v_lshrrev_b32_e32 v28, 2, v1
	v_lshrrev_b32_e32 v29, 1, v1
	v_and_b32_e32 v30, 0x5f, v1
	v_lshlrev_b32_e32 v31, 4, v1
	v_mul_lo_u32 v1, v65, s3
	s_lshl_b32 s3, s5, 7
	s_and_b32 s3, s3, 0xfffffc00
	s_lshl_b32 s5, s15, 7
	s_or_b32 s3, s3, s5
	s_or_b32 s3, s3, s22
	s_add_i32 s3, s3, 0x8000
	s_mov_b32 s11, 0
	s_mov_b32 s16, 0xfffffe0
	v_add_lshl_u32 v64, v1, v64, 1
	s_mul_hi_i32 s5, s3, 0x2080
	s_mulk_i32 s3, 0x2080
	s_movk_i32 s17, 0x90
	v_and_or_b32 v32, v28, s16, v2
	v_and_b32_e32 v2, 16, v29
	v_mov_b64_e32 v[28:29], s[10:11]
	v_mad_u64_u32 v[58:59], s[10:11], v32, s17, v[2:3]
	v_mad_u32_u24 v1, v30, s17, v2
	v_mad_i64_i32 v[28:29], s[10:11], v65, s23, v[28:29]
	v_and_b32_e32 v2, 0x70, v31
	v_or_b32_e32 v28, v28, v2
	v_lshl_add_u64 v[60:61], s[8:9], 0, v[28:29]
	s_mov_b32 s15, 0x19ca000
	s_mov_b32 s16, 0x1a0b000
	v_mov_b32_e32 v28, v3
	v_mov_b32_e32 v29, v3
	v_mov_b32_e32 v30, v3
	v_mov_b32_e32 v31, v3
	v_mov_b32_e32 v32, v3
	v_mov_b32_e32 v33, v3
	s_waitcnt vmcnt(11)
	ds_write_b128 v64, v[4:7]
	s_waitcnt vmcnt(10)
	ds_write_b128 v64, v[8:11] offset:4608
	s_waitcnt vmcnt(9)
	ds_write_b128 v64, v[12:15] offset:18432
	s_waitcnt vmcnt(8)
	ds_write_b128 v64, v[16:19] offset:23040
	s_waitcnt vmcnt(7)
	ds_write_b128 v64, v[20:23] offset:27648
	s_waitcnt vmcnt(6)
	ds_write_b128 v64, v[24:27] offset:32256
	v_mov_b32_e32 v4, s3
	v_mov_b32_e32 v5, s5
	v_mad_i64_i32 v[4:5], s[10:11], v65, s23, v[4:5]
	v_or_b32_e32 v4, v4, v2
	v_lshl_add_u64 v[62:63], s[8:9], 0, v[4:5]
	s_mov_b64 s[8:9], 0
	s_mov_b32 s3, 0xa92c000
	s_mov_b32 s5, 0xa96d000
	s_mov_b32 s10, 0x1948000
	s_mov_b32 s11, 0x1989000
	v_mov_b32_e32 v2, v3
	v_mov_b32_e32 v4, v3
	v_mov_b32_e32 v5, v3
	v_mov_b32_e32 v6, v3
	v_mov_b32_e32 v7, v3
	v_mov_b32_e32 v8, v3
	v_mov_b32_e32 v9, v3
	v_mov_b32_e32 v10, v3
	v_mov_b32_e32 v11, v3
	v_mov_b32_e32 v12, v3
	v_mov_b32_e32 v13, v3
	v_mov_b32_e32 v14, v3
	v_mov_b32_e32 v15, v3
	v_mov_b32_e32 v16, v3
	v_mov_b32_e32 v17, v3
	v_mov_b32_e32 v18, v3
	v_mov_b32_e32 v19, v3
	v_mov_b32_e32 v20, v3
	v_mov_b32_e32 v21, v3
	v_mov_b32_e32 v22, v3
	v_mov_b32_e32 v23, v3
	v_mov_b32_e32 v24, v3
	v_mov_b32_e32 v25, v3
	v_mov_b32_e32 v26, v3
	v_mov_b32_e32 v27, v3
	s_waitcnt lgkmcnt(0)
	s_barrier

; #define MFMA(a, b, c) __builtin_amdgcn_mfma_f32_32x32x16_bf16((a), (b), (c), 0, 0, 0)
; template <int TM, int TN>
; DI void gemm_mainloop(const u16* __restrict__ A, long lda, const u16* __restrict__ Bt, long ldb, int K, char* smem,
;                       f32x16 (&acc)[TM][TN]) {
;     ...
;   for (int kt = 0; kt < nk; kt++) {
;     const int buf = kt & 1;
;     const u16* cA = sA + buf * BM * LD + (wm * 32 * TM + r) * LD + h * 8;
;     const u16* cB = sB + buf * BN * LD + (wn * 32 * TN + r) * LD + h * 8;
;     bf16x8 af[TM], bfr[TN];
; #pragma unroll
;     for (int tm = 0; tm < TM; tm++) af[tm] = *(const bf16x8*)(cA + tm * 32 * LD);
; #pragma unroll
;     for (int tn = 0; tn < TN; tn++) bfr[tn] = *(const bf16x8*)(cB + tn * 32 * LD);
;     if (kt + 1 < nk) GEMM_SSTORE(buf ^ 1)
;     __builtin_amdgcn_sched_barrier(0);
;     __builtin_amdgcn_s_setprio(1);
; #pragma unroll
;     for (int tm = 0; tm < TM; tm++)
; #pragma unroll
;       for (int tn = 0; tn < TN; tn++) acc[tm][tn] = MFMA(af[tm], bfr[tn], acc[tm][tn]);
; #pragma unroll
;     for (int tm = 0; tm < TM; tm++) af[tm] = *(const bf16x8*)(cA + tm * 32 * LD + 16);
; #pragma unroll
;     for (int tn = 0; tn < TN; tn++) bfr[tn] = *(const bf16x8*)(cB + tn * 32 * LD + 16);
; #pragma unroll
;     for (int tm = 0; tm < TM; tm++)
; #pragma unroll
;       for (int tn = 0; tn < TN; tn++) acc[tm][tn] = MFMA(af[tm], bfr[tn], acc[tm][tn]);
;     __builtin_amdgcn_sched_group_barrier(0x8, 4, 0);
;     if (kt + 2 < nk) GEMM_GLOAD((kt + 2) * 64)
; #pragma unroll
;     for (int ks = 2; ks < 4; ks++) {
; #pragma unroll
;       for (int tm = 0; tm < TM; tm++) af[tm] = *(const bf16x8*)(cA + tm * 32 * LD + ks * 16);
; #pragma unroll
;       for (int tn = 0; tn < TN; tn++) bfr[tn] = *(const bf16x8*)(cB + tn * 32 * LD + ks * 16);
; #pragma unroll
;       for (int tm = 0; tm < TM; tm++)
; #pragma unroll
;         for (int tn = 0; tn < TN; tn++) acc[tm][tn] = MFMA(af[tm], bfr[tn], acc[tm][tn]);
;     }
;     __builtin_amdgcn_s_setprio(0);
;     __syncthreads();
;   }
.LBB0_2343:
	s_and_b32 s38, s37, 1
	s_mul_i32 s39, s38, 0x4800
	v_add_u32_e32 v109, s39, v102
	v_add_u32_e32 v126, s39, v98
	s_lshl_b32 s38, s38, 7
	ds_read_b128 v[110:113], v109
	ds_read_b128 v[114:117], v109 offset:4608
	ds_read_b128 v[118:121], v126 offset:36864
	ds_read_b128 v[122:125], v126 offset:41472
	s_xor_b32 s38, s38, 0x80
	s_mulk_i32 s38, 0x90
	s_add_i32 s37, s37, 1
	v_add_u32_e32 v127, s38, v108
	s_waitcnt vmcnt(7)
	ds_write_b128 v127, v[70:73]
	s_waitcnt vmcnt(6)
	ds_write_b128 v127, v[74:77] offset:4608
	s_waitcnt vmcnt(5)
	ds_write_b128 v127, v[66:69] offset:9216
	s_waitcnt vmcnt(4)
	ds_write_b128 v127, v[78:81] offset:13824
	s_waitcnt vmcnt(3)
	ds_write_b128 v127, v[82:85] offset:36864
	s_waitcnt vmcnt(2)
	ds_write_b128 v127, v[86:89] offset:41472
	s_waitcnt vmcnt(1)
	ds_write_b128 v127, v[90:93] offset:46080
	s_waitcnt vmcnt(0)
	ds_write_b128 v127, v[94:97] offset:50688
	s_setprio 1
	ds_read_b128 v[66:69], v109 offset:32
	s_waitcnt lgkmcnt(10)
	v_mfma_f32_32x32x16_bf16 v[50:65], v[110:113], v[118:121], v[50:65]
	ds_read_b128 v[70:73], v126 offset:36896
	ds_read_b128 v[74:77], v126 offset:41504
	ds_read_b128 v[86:89], v109 offset:4672
	ds_read_b128 v[78:81], v126 offset:36928
	ds_read_b128 v[82:85], v126 offset:41536
	v_lshl_add_u64 v[90:91], v[106:107], 0, s[14:15]
	ds_read_b128 v[94:97], v126 offset:36960
	s_waitcnt lgkmcnt(14)
	v_mfma_f32_32x32x16_bf16 v[34:49], v[110:113], v[122:125], v[34:49]
	ds_read_b128 v[110:113], v126 offset:41568
	s_waitcnt lgkmcnt(6)
	v_mfma_f32_32x32x16_bf16 v[50:65], v[66:69], v[70:73], v[50:65]
	s_waitcnt lgkmcnt(5)
	v_mfma_f32_32x32x16_bf16 v[34:49], v[66:69], v[74:77], v[34:49]
	ds_read_b128 v[66:69], v109 offset:4640
	v_mfma_f32_32x32x16_bf16 v[18:33], v[114:117], v[118:121], v[18:33]
	v_lshl_add_u64 v[118:119], v[104:105], 0, s[14:15]
	v_mfma_f32_32x32x16_bf16 v[2:17], v[114:117], v[122:125], v[2:17]
	ds_read_b128 v[114:117], v109 offset:4704
	s_waitcnt lgkmcnt(1)
	v_mfma_f32_32x32x16_bf16 v[18:33], v[66:69], v[70:73], v[18:33]
	global_load_dwordx4 v[70:73], v[90:91], off offset:256
	v_mfma_f32_32x32x16_bf16 v[2:17], v[66:69], v[74:77], v[2:17]
	ds_read_b128 v[66:69], v109 offset:64
	v_add_co_u32_e32 v74, vcc, s21, v90
	s_nop 1
	v_addc_co_u32_e32 v75, vcc, 0, v91, vcc
	global_load_dwordx4 v[74:77], v[74:75], off offset:256
	s_waitcnt lgkmcnt(0)
	v_mfma_f32_32x32x16_bf16 v[50:65], v[66:69], v[78:81], v[50:65]
	v_mfma_f32_32x32x16_bf16 v[34:49], v[66:69], v[82:85], v[34:49]
	v_add_co_u32_e32 v66, vcc, s22, v90
	s_nop 1
	v_addc_co_u32_e32 v67, vcc, 0, v91, vcc
	global_load_dwordx4 v[66:69], v[66:67], off offset:256
	v_mfma_f32_32x32x16_bf16 v[18:33], v[86:89], v[78:81], v[18:33]
	v_add_co_u32_e32 v78, vcc, s23, v90
	s_nop 1
	v_addc_co_u32_e32 v79, vcc, 0, v91, vcc
	ds_read_b128 v[90:93], v109 offset:96
	global_load_dwordx4 v[78:81], v[78:79], off offset:256
	v_mfma_f32_32x32x16_bf16 v[2:17], v[86:89], v[82:85], v[2:17]
	v_add_co_u32_e32 v82, vcc, s26, v118
	s_nop 1
	v_addc_co_u32_e32 v83, vcc, 0, v119, vcc
	v_add_co_u32_e32 v86, vcc, s27, v118
	global_load_dwordx4 v[82:85], v[82:83], off offset:256
	s_nop 0
	v_addc_co_u32_e32 v87, vcc, 0, v119, vcc
	v_add_co_u32_e32 v120, vcc, s28, v118
	s_waitcnt lgkmcnt(0)
	v_mfma_f32_32x32x16_bf16 v[50:65], v[90:93], v[94:97], v[50:65]
	v_addc_co_u32_e32 v121, vcc, 0, v119, vcc
	v_add_co_u32_e32 v118, vcc, s29, v118
	global_load_dwordx4 v[86:89], v[86:87], off offset:256
	s_nop 0
	v_addc_co_u32_e32 v119, vcc, 0, v119, vcc
	v_mfma_f32_32x32x16_bf16 v[34:49], v[90:93], v[110:113], v[34:49]
	global_load_dwordx4 v[90:93], v[120:121], off offset:256
	v_mfma_f32_32x32x16_bf16 v[18:33], v[114:117], v[94:97], v[18:33]
	global_load_dwordx4 v[94:97], v[118:119], off offset:256
	v_mfma_f32_32x32x16_bf16 v[2:17], v[114:117], v[110:113], v[2:17]
	s_setprio 0
	s_add_u32 s14, s14, 0x80
	s_addc_u32 s15, s15, 0
	s_cmpk_eq_i32 s14, 0x700
	s_barrier
	s_cbranch_scc0 .LBB0_2343
	ds_read_b128 v[104:107], v102
	ds_read_b128 v[110:113], v102 offset:4608
	ds_read_b128 v[114:117], v98 offset:36864
	ds_read_b128 v[118:121], v98 offset:41472
	s_waitcnt vmcnt(7)
	ds_write_b128 v108, v[70:73] offset:18432
	s_waitcnt vmcnt(6)
	ds_write_b128 v108, v[74:77] offset:23040
	s_waitcnt vmcnt(5)
	ds_write_b128 v108, v[66:69] offset:27648
	s_waitcnt vmcnt(4)
	ds_write_b128 v108, v[78:81] offset:32256
	s_waitcnt vmcnt(3)
	ds_write_b128 v108, v[82:85] offset:55296
	s_waitcnt vmcnt(2)
	ds_write_b128 v108, v[86:89] offset:59904
	s_waitcnt vmcnt(1)
	ds_write_b128 v108, v[90:93] offset:64512
	s_waitcnt vmcnt(0)
	ds_write_b128 v103, v[94:97] offset:32256
	s_setprio 1
	ds_read_b128 v[66:69], v102 offset:32
	s_waitcnt lgkmcnt(10)
	v_mfma_f32_32x32x16_bf16 v[50:65], v[104:107], v[114:117], v[50:65]
	ds_read_b128 v[70:73], v98 offset:36896
	ds_read_b128 v[74:77], v98 offset:41504
	s_waitcnt lgkmcnt(11)
	v_mfma_f32_32x32x16_bf16 v[34:49], v[104:107], v[118:121], v[34:49]
	s_waitcnt lgkmcnt(1)
	v_mfma_f32_32x32x16_bf16 v[50:65], v[66:69], v[70:73], v[50:65]
	s_waitcnt lgkmcnt(0)
	v_mfma_f32_32x32x16_bf16 v[34:49], v[66:69], v[74:77], v[34:49]
	ds_read_b128 v[66:69], v102 offset:4640
	v_mfma_f32_32x32x16_bf16 v[18:33], v[110:113], v[114:117], v[18:33]
	v_mfma_f32_32x32x16_bf16 v[2:17], v[110:113], v[118:121], v[2:17]
	s_waitcnt lgkmcnt(0)
	v_mfma_f32_32x32x16_bf16 v[18:33], v[66:69], v[70:73], v[18:33]
	ds_read_b128 v[70:73], v98 offset:36928
	v_mfma_f32_32x32x16_bf16 v[2:17], v[66:69], v[74:77], v[2:17]
	ds_read_b128 v[66:69], v102 offset:64
	ds_read_b128 v[74:77], v98 offset:41536
	s_waitcnt lgkmcnt(1)
	v_mfma_f32_32x32x16_bf16 v[50:65], v[66:69], v[70:73], v[50:65]
	s_waitcnt lgkmcnt(0)
	v_mfma_f32_32x32x16_bf16 v[34:49], v[66:69], v[74:77], v[34:49]
	ds_read_b128 v[66:69], v102 offset:4672
	s_waitcnt lgkmcnt(0)
	v_mfma_f32_32x32x16_bf16 v[18:33], v[66:69], v[70:73], v[18:33]
	ds_read_b128 v[70:73], v98 offset:36960
	v_mfma_f32_32x32x16_bf16 v[2:17], v[66:69], v[74:77], v[2:17]
	ds_read_b128 v[66:69], v102 offset:96
	ds_read_b128 v[74:77], v98 offset:41568
	s_waitcnt lgkmcnt(1)
	v_mfma_f32_32x32x16_bf16 v[50:65], v[66:69], v[70:73], v[50:65]
	s_waitcnt lgkmcnt(0)
	v_mfma_f32_32x32x16_bf16 v[34:49], v[66:69], v[74:77], v[34:49]
	ds_read_b128 v[66:69], v102 offset:4704
	s_waitcnt lgkmcnt(0)
	v_mfma_f32_32x32x16_bf16 v[2:17], v[66:69], v[74:77], v[2:17]
	v_mfma_f32_32x32x16_bf16 v[18:33], v[66:69], v[70:73], v[18:33]
	s_setprio 0
	s_barrier
; DI int crow(int i, int h) { return (i & 3) + 8 * (i >> 2) + 4 * h; }
; template <int TM, int TN, class Epi>
; DI void gemm_tile(const u16* A, long lda, const u16* Bt, long ldb, int K, int m0, int n0, char* smem, const Epi& epi) {
;     ...
; #pragma unroll
;   for (int tm = 0; tm < TM; tm++)
; #pragma unroll
;     for (int tn = 0; tn < TN; tn++)
; #pragma unroll
;       for (int i = 0; i < 16; i++)
;         Ct[(wm * 32 * TM + tm * 32 + crow(i, h)) * LDC + wn * 32 * TN + tn * 32 + r] = acc[tm][tn][i];
;   __syncthreads();
;   DI void operator()(const float* Ct, int ldc, int m0, int n0, int tid, int bm) const {
;     ...
;     for (int it = 0; it < bm / 16; it++) {
;       int id = tid + 256 * it; int row = id >> 4, c8 = (id & 15) * 8;
;       int m = m0 + row;
;       const float* c = Ct + row * ldc + c8;
;       float4 a = *(const float4*)c, b = *(const float4*)(c + 4);
;       float x[8];
;       if (srcb != nullptr) {
;         unpack8(*(const uint4*)(srcb + (size_t)m * LDA + n0 + c8), x);
	ds_read_b128 v[66:69], v102 offset:18432
	ds_read_b128 v[70:73], v102 offset:23040
	ds_read_b128 v[74:77], v98 offset:55296
	ds_read_b128 v[78:81], v98 offset:59904
	s_setprio 1
	s_waitcnt lgkmcnt(1)
	v_mfma_f32_32x32x16_bf16 v[50:65], v[66:69], v[74:77], v[50:65]
	s_waitcnt lgkmcnt(0)
	v_mfma_f32_32x32x16_bf16 v[34:49], v[66:69], v[78:81], v[34:49]
	ds_read_b128 v[66:69], v102 offset:18464
	v_mfma_f32_32x32x16_bf16 v[18:33], v[70:73], v[74:77], v[18:33]
	ds_read_b128 v[74:77], v98 offset:59936
	v_mfma_f32_32x32x16_bf16 v[2:17], v[70:73], v[78:81], v[2:17]
	ds_read_b128 v[70:73], v98 offset:55328
	s_waitcnt lgkmcnt(0)
	v_mfma_f32_32x32x16_bf16 v[50:65], v[66:69], v[70:73], v[50:65]
	v_mfma_f32_32x32x16_bf16 v[34:49], v[66:69], v[74:77], v[34:49]
	ds_read_b128 v[66:69], v102 offset:23072
	s_waitcnt lgkmcnt(0)
	v_mfma_f32_32x32x16_bf16 v[18:33], v[66:69], v[70:73], v[18:33]
	ds_read_b128 v[70:73], v98 offset:55360
	v_mfma_f32_32x32x16_bf16 v[2:17], v[66:69], v[74:77], v[2:17]
	ds_read_b128 v[66:69], v102 offset:18496
	ds_read_b128 v[74:77], v98 offset:59968
	s_waitcnt lgkmcnt(1)
	v_mfma_f32_32x32x16_bf16 v[50:65], v[66:69], v[70:73], v[50:65]
	s_waitcnt lgkmcnt(0)
	v_mfma_f32_32x32x16_bf16 v[34:49], v[66:69], v[74:77], v[34:49]
	ds_read_b128 v[66:69], v102 offset:23104
	s_waitcnt lgkmcnt(0)
	v_mfma_f32_32x32x16_bf16 v[18:33], v[66:69], v[70:73], v[18:33]
	ds_read_b128 v[70:73], v98 offset:55392
	v_mfma_f32_32x32x16_bf16 v[2:17], v[66:69], v[74:77], v[2:17]
	ds_read_b128 v[66:69], v102 offset:18528
	ds_read_b128 v[74:77], v98 offset:60000
	s_waitcnt lgkmcnt(1)
	v_mfma_f32_32x32x16_bf16 v[50:65], v[66:69], v[70:73], v[50:65]
	s_waitcnt lgkmcnt(0)
	v_mfma_f32_32x32x16_bf16 v[34:49], v[66:69], v[74:77], v[34:49]
	ds_read_b128 v[66:69], v102 offset:23136
	s_waitcnt lgkmcnt(0)
	v_mfma_f32_32x32x16_bf16 v[2:17], v[66:69], v[74:77], v[2:17]
	v_mfma_f32_32x32x16_bf16 v[18:33], v[66:69], v[70:73], v[18:33]
	s_setprio 0
	v_mov_b32_e32 v66, v0
	s_barrier
	s_mov_b32 s14, 0
	v_lshrrev_b32_e32 v67, 1, v66
	v_and_b32_e32 v67, 0xfffffc0, v67
	v_lshrrev_b32_e32 v68, 3, v66
	v_and_or_b32 v67, v68, 4, v67
	v_and_b32_e32 v68, 0x5f, v66
	v_mul_lo_u32 v67, v67, s30
	v_lshl_add_u32 v67, v68, 2, v67
	ds_write2_b32 v67, v50, v34 offset1:32
	v_add_u32_e32 v34, 0x400, v67
	ds_write2_b32 v34, v52, v36 offset0:8 offset1:40
	ds_write2_b32 v34, v53, v37 offset0:140 offset1:172
	v_add_u32_e32 v34, 0x1000, v67
	ds_write2_b32 v34, v54, v38 offset0:32 offset1:64
	ds_write2_b32 v34, v55, v39 offset0:164 offset1:196
	v_add_u32_e32 v34, 0x1400, v67
	ds_write2_b32 v34, v56, v40 offset0:40 offset1:72
	ds_write2_b32 v34, v57, v41 offset0:172 offset1:204
	v_add_u32_e32 v34, 0x2000, v67
	ds_write2_b32 v34, v58, v42 offset0:64 offset1:96
	ds_write2_b32 v34, v59, v43 offset0:196 offset1:228
	v_add_u32_e32 v34, 0x2400, v67
	ds_write2_b32 v34, v60, v44 offset0:72 offset1:104
	ds_write2_b32 v34, v61, v45 offset0:204 offset1:236
	v_add_u32_e32 v34, 0x3000, v67
	ds_write2_b32 v34, v62, v46 offset0:96 offset1:128
	v_add_u32_e32 v34, 0x3200, v67
	ds_write2_b32 v34, v63, v47 offset0:100 offset1:132
	v_add_u32_e32 v34, 0x3400, v67
	ds_write2_b32 v34, v64, v48 offset0:104 offset1:136
	v_add_u32_e32 v34, 0x3600, v67
	ds_write2_b32 v34, v65, v49 offset0:108 offset1:140
	v_add_u32_e32 v34, 0x4000, v67
	ds_write2_b32 v34, v18, v2 offset0:128 offset1:160
	v_add_u32_e32 v2, 0x4400, v67
	ds_write2_b32 v2, v19, v3 offset0:4 offset1:36
	ds_write2_b32 v2, v20, v4 offset0:136 offset1:168
	v_add_u32_e32 v2, 0x4800, v67
	ds_write2_b32 v2, v21, v5 offset0:12 offset1:44
	v_add_u32_e32 v2, 0x5000, v67
	ds_write2_b32 v2, v22, v6 offset0:160 offset1:192
	v_add_u32_e32 v2, 0x5400, v67
	ds_write2_b32 v2, v23, v7 offset0:36 offset1:68
	ds_write2_b32 v2, v24, v8 offset0:168 offset1:200
	v_add_u32_e32 v2, 0x5800, v67
	ds_write2_b32 v2, v25, v9 offset0:44 offset1:76
	v_add_u32_e32 v2, 0x6000, v67
	ds_write2_b32 v2, v26, v10 offset0:192 offset1:224
	v_add_u32_e32 v2, 0x6400, v67
	ds_write2_b32 v2, v27, v11 offset0:68 offset1:100
	ds_write2_b32 v2, v28, v12 offset0:200 offset1:232
	v_add_u32_e32 v2, 0x6800, v67
	ds_write2_b32 v2, v29, v13 offset0:76 offset1:108
	v_add_u32_e32 v2, 0x7200, v67
	ds_write2_b32 v2, v30, v14 offset0:96 offset1:128
	v_add_u32_e32 v2, 0x7400, v67
	ds_write2_b32 v2, v31, v15 offset0:100 offset1:132
	v_add_u32_e32 v2, 0x7600, v67
	ds_write2_b32 v2, v32, v16 offset0:104 offset1:136
	v_add_u32_e32 v2, 0x7800, v67
	ds_write2_b32 v2, v33, v17 offset0:108 offset1:140
	v_lshlrev_b32_e32 v2, 3, v66
	v_and_b32_e32 v3, 0x78, v2
	v_lshlrev_b32_e32 v98, 1, v3
	v_lshlrev_b32_e32 v2, 2, v3
	v_lshl_add_u64 v[4:5], s[10:11], 0, v[98:99]
	ds_write2_b32 v67, v51, v35 offset0:132 offset1:164
	v_ashrrev_i32_e32 v190, 4, v66
	v_add_u32_e32 v190, s36, v190
	v_mad_i64_i32 v[192:193], vcc, v190, s18, v[4:5]
	global_load_dwordx4 v[150:153], v[192:193], off
	v_add_u32_e32 v191, 16, v190
	v_mad_i64_i32 v[192:193], vcc, v191, s18, v[4:5]
	global_load_dwordx4 v[154:157], v[192:193], off
	v_add_u32_e32 v191, 32, v190
	v_mad_i64_i32 v[192:193], vcc, v191, s18, v[4:5]
	global_load_dwordx4 v[158:161], v[192:193], off
	v_add_u32_e32 v191, 48, v190
	v_mad_i64_i32 v[192:193], vcc, v191, s18, v[4:5]
	global_load_dwordx4 v[162:165], v[192:193], off
	v_add_u32_e32 v191, 64, v190
	v_mad_i64_i32 v[192:193], vcc, v191, s18, v[4:5]
	global_load_dwordx4 v[166:169], v[192:193], off
	v_add_u32_e32 v191, 80, v190
	v_mad_i64_i32 v[192:193], vcc, v191, s18, v[4:5]
	global_load_dwordx4 v[170:173], v[192:193], off
	v_add_u32_e32 v191, 96, v190
	v_mad_i64_i32 v[192:193], vcc, v191, s18, v[4:5]
	global_load_dwordx4 v[174:177], v[192:193], off
	v_add_u32_e32 v191, 112, v190
	v_mad_i64_i32 v[192:193], vcc, v191, s18, v[4:5]
	global_load_dwordx4 v[178:181], v[192:193], off
	s_waitcnt lgkmcnt(0)
	s_barrier
;   DI void operator()(const float* Ct, int ldc, int m0, int n0, int tid, int bm) const {
;     ...
;     for (int it = 0; it < bm / 16; it++) {
;       int id = tid + 256 * it; int row = id >> 4, c8 = (id & 15) * 8;
;       int m = m0 + row;
;       const float* c = Ct + row * ldc + c8;
;       float4 a = *(const float4*)c, b = *(const float4*)(c + 4);
;       float x[8];
;       if (srcb != nullptr) {
;         unpack8(*(const uint4*)(srcb + (size_t)m * LDA + n0 + c8), x);
;       } else {
;         const float* sp = (m < NP ? src0 + (size_t)m * 1024 : src1 + (size_t)(m - NP) * 1024) + n0 + c8;
;         float4 sa = *(const float4*)sp, sb = *(const float4*)(sp + 4);
;         x[0] = sa.x; x[1] = sa.y; x[2] = sa.z; x[3] = sa.w; x[4] = sb.x; x[5] = sb.y; x[6] = sb.z; x[7] = sb.w;
;       }
;       x[0] += a.x; x[1] += a.y; x[2] += a.z; x[3] += a.w; x[4] += b.x; x[5] += b.y; x[6] += b.z; x[7] += b.w;
;       if (dstf != nullptr) {
;         float* o = dstf + (size_t)m * 1024 + n0 + c8;
;         *(float4*)o = make_float4(x[0], x[1], x[2], x[3]); *(float4*)(o + 4) = make_float4(x[4], x[5], x[6], x[7]);
;       } else {
;         *(uint4*)(dstb + (size_t)m * LDA + n0 + c8) = pack8(x);
;       }
.LBB0_2345:
	v_add_u32_e32 v3, s14, v66
	v_ashrrev_i32_e32 v10, 4, v3
	v_add_u32_e32 v6, s36, v10
	v_mad_i64_i32 v[18:19], s[38:39], v6, s18, v[4:5]
	v_add_u32_e32 v11, 0x100, v3
	v_mad_u64_u32 v[14:15], s[38:39], v10, s30, v[2:3]
	v_ashrrev_i32_e32 v26, 4, v11
	ds_read_b128 v[10:13], v14
	ds_read_b128 v[14:17], v14 offset:16
	v_add_u32_e32 v20, s36, v26
	v_mad_i64_i32 v[20:21], s[38:39], v20, s18, v[4:5]
	s_addk_i32 s14, 0x400
	s_cmpk_lg_i32 s14, 0x800
	s_waitcnt vmcnt(7)
	v_mov_b64_e32 v[6:7], v[150:151]
	v_mov_b64_e32 v[8:9], v[152:153]
	v_lshlrev_b32_e32 v22, 16, v6
	v_and_b32_e32 v23, 0xffff0000, v6
	v_lshlrev_b32_e32 v6, 16, v7
	v_and_b32_e32 v7, 0xffff0000, v7
	v_lshlrev_b32_e32 v24, 16, v8
	v_and_b32_e32 v25, 0xffff0000, v8
	v_lshlrev_b32_e32 v8, 16, v9
	v_and_b32_e32 v9, 0xffff0000, v9
	s_waitcnt lgkmcnt(1)
	v_pk_add_f32 v[10:11], v[10:11], v[22:23]
	v_pk_add_f32 v[12:13], v[12:13], v[6:7]
	s_waitcnt lgkmcnt(0)
	v_pk_add_f32 v[14:15], v[14:15], v[24:25]
	v_pk_add_f32 v[16:17], v[16:17], v[8:9]
	v_cvt_pk_bf16_f32 v6, v10, v11
	v_cvt_pk_bf16_f32 v7, v12, v13
	v_cvt_pk_bf16_f32 v8, v14, v15
	v_cvt_pk_bf16_f32 v9, v16, v17
	global_store_dwordx4 v[18:19], v[6:9], off
	v_add_u32_e32 v10, 0x200, v3
	v_mad_u64_u32 v[14:15], s[38:39], v26, s30, v[2:3]
	v_ashrrev_i32_e32 v27, 4, v10
	ds_read_b128 v[10:13], v14
	ds_read_b128 v[14:17], v14 offset:16
	v_add_u32_e32 v18, s36, v27
	v_mad_i64_i32 v[18:19], s[38:39], v18, s18, v[4:5]
	v_add_u32_e32 v3, 0x300, v3
	v_ashrrev_i32_e32 v3, 4, v3
	s_waitcnt vmcnt(7)
	v_mov_b64_e32 v[6:7], v[154:155]
	v_mov_b64_e32 v[8:9], v[156:157]
	v_lshlrev_b32_e32 v22, 16, v6
	v_and_b32_e32 v23, 0xffff0000, v6
	v_lshlrev_b32_e32 v6, 16, v7
	v_and_b32_e32 v7, 0xffff0000, v7
	v_lshlrev_b32_e32 v24, 16, v8
	v_and_b32_e32 v25, 0xffff0000, v8
	v_lshlrev_b32_e32 v8, 16, v9
	v_and_b32_e32 v9, 0xffff0000, v9
	s_waitcnt lgkmcnt(1)
	v_pk_add_f32 v[10:11], v[10:11], v[22:23]
	v_pk_add_f32 v[12:13], v[12:13], v[6:7]
	s_waitcnt lgkmcnt(0)
	v_pk_add_f32 v[14:15], v[14:15], v[24:25]
	v_pk_add_f32 v[16:17], v[16:17], v[8:9]
	v_cvt_pk_bf16_f32 v6, v10, v11
	v_cvt_pk_bf16_f32 v7, v12, v13
	v_cvt_pk_bf16_f32 v8, v14, v15
	v_cvt_pk_bf16_f32 v9, v16, v17
	global_store_dwordx4 v[20:21], v[6:9], off
	v_mad_u64_u32 v[14:15], s[38:39], v27, s30, v[2:3]
	ds_read_b128 v[10:13], v14
	ds_read_b128 v[14:17], v14 offset:16
	v_add_u32_e32 v20, s36, v3
	v_mad_i64_i32 v[20:21], s[38:39], v20, s18, v[4:5]
	s_waitcnt vmcnt(7)
	v_mov_b64_e32 v[6:7], v[158:159]
	v_mov_b64_e32 v[8:9], v[160:161]
	v_lshlrev_b32_e32 v22, 16, v6
	v_and_b32_e32 v23, 0xffff0000, v6
	v_lshlrev_b32_e32 v6, 16, v7
	v_and_b32_e32 v7, 0xffff0000, v7
	v_lshlrev_b32_e32 v24, 16, v8
	v_and_b32_e32 v25, 0xffff0000, v8
	v_lshlrev_b32_e32 v8, 16, v9
	v_and_b32_e32 v9, 0xffff0000, v9
	s_waitcnt lgkmcnt(1)
	v_pk_add_f32 v[10:11], v[10:11], v[22:23]
	v_pk_add_f32 v[12:13], v[12:13], v[6:7]
	s_waitcnt lgkmcnt(0)
	v_pk_add_f32 v[14:15], v[14:15], v[24:25]
	v_pk_add_f32 v[16:17], v[16:17], v[8:9]
	v_cvt_pk_bf16_f32 v6, v10, v11
	v_cvt_pk_bf16_f32 v7, v12, v13
	v_cvt_pk_bf16_f32 v8, v14, v15
	v_cvt_pk_bf16_f32 v9, v16, v17
	global_store_dwordx4 v[18:19], v[6:9], off
	v_mad_u64_u32 v[14:15], s[38:39], v3, s30, v[2:3]
	ds_read_b128 v[10:13], v14
	ds_read_b128 v[14:17], v14 offset:16
	s_waitcnt vmcnt(7)
	v_mov_b64_e32 v[6:7], v[162:163]
	v_mov_b64_e32 v[8:9], v[164:165]
	v_lshlrev_b32_e32 v18, 16, v6
	v_and_b32_e32 v19, 0xffff0000, v6
	v_lshlrev_b32_e32 v6, 16, v7
	v_and_b32_e32 v7, 0xffff0000, v7
	v_lshlrev_b32_e32 v22, 16, v8
	v_and_b32_e32 v23, 0xffff0000, v8
	v_lshlrev_b32_e32 v8, 16, v9
	v_and_b32_e32 v9, 0xffff0000, v9
	s_waitcnt lgkmcnt(1)
	v_pk_add_f32 v[10:11], v[10:11], v[18:19]
	v_pk_add_f32 v[12:13], v[12:13], v[6:7]
	s_waitcnt lgkmcnt(0)
	v_pk_add_f32 v[14:15], v[14:15], v[22:23]
	v_pk_add_f32 v[16:17], v[16:17], v[8:9]
	v_cvt_pk_bf16_f32 v6, v10, v11
	v_cvt_pk_bf16_f32 v7, v12, v13
	v_cvt_pk_bf16_f32 v8, v14, v15
	v_cvt_pk_bf16_f32 v9, v16, v17
	global_store_dwordx4 v[20:21], v[6:9], off
	v_add_u32_e32 v3, s14, v66
	v_ashrrev_i32_e32 v10, 4, v3
	v_add_u32_e32 v6, s36, v10
	v_mad_i64_i32 v[18:19], s[38:39], v6, s18, v[4:5]
	v_add_u32_e32 v11, 0x100, v3
	v_mad_u64_u32 v[14:15], s[38:39], v10, s30, v[2:3]
	v_ashrrev_i32_e32 v26, 4, v11
	ds_read_b128 v[10:13], v14
	ds_read_b128 v[14:17], v14 offset:16
	v_add_u32_e32 v20, s36, v26
	v_mad_i64_i32 v[20:21], s[38:39], v20, s18, v[4:5]
	s_addk_i32 s14, 0x400
	s_cmpk_lg_i32 s14, 0x800
	s_waitcnt vmcnt(7)
	v_mov_b64_e32 v[6:7], v[166:167]
	v_mov_b64_e32 v[8:9], v[168:169]
	v_lshlrev_b32_e32 v22, 16, v6
	v_and_b32_e32 v23, 0xffff0000, v6
	v_lshlrev_b32_e32 v6, 16, v7
	v_and_b32_e32 v7, 0xffff0000, v7
	v_lshlrev_b32_e32 v24, 16, v8
	v_and_b32_e32 v25, 0xffff0000, v8
	v_lshlrev_b32_e32 v8, 16, v9
	v_and_b32_e32 v9, 0xffff0000, v9
	s_waitcnt lgkmcnt(1)
	v_pk_add_f32 v[10:11], v[10:11], v[22:23]
	v_pk_add_f32 v[12:13], v[12:13], v[6:7]
	s_waitcnt lgkmcnt(0)
	v_pk_add_f32 v[14:15], v[14:15], v[24:25]
	v_pk_add_f32 v[16:17], v[16:17], v[8:9]
	v_cvt_pk_bf16_f32 v6, v10, v11
	v_cvt_pk_bf16_f32 v7, v12, v13
	v_cvt_pk_bf16_f32 v8, v14, v15
	v_cvt_pk_bf16_f32 v9, v16, v17
	global_store_dwordx4 v[18:19], v[6:9], off
	v_add_u32_e32 v10, 0x200, v3
	v_mad_u64_u32 v[14:15], s[38:39], v26, s30, v[2:3]
	v_ashrrev_i32_e32 v27, 4, v10
	ds_read_b128 v[10:13], v14
	ds_read_b128 v[14:17], v14 offset:16
	v_add_u32_e32 v18, s36, v27
	v_mad_i64_i32 v[18:19], s[38:39], v18, s18, v[4:5]
	v_add_u32_e32 v3, 0x300, v3
	v_ashrrev_i32_e32 v3, 4, v3
	s_waitcnt vmcnt(7)
; template <int TM, int TN>
; DI void gemm_mainloop(const u16* __restrict__ A, long lda, const u16* __restrict__ Bt, long ldb, int K, char* smem,
;                       f32x16 (&acc)[TM][TN]) {
;     ...
;   const int lrow = tid >> 3, lch = (tid & 7) * 8;
;   const u16* gA = A + (long)lrow * lda + lch;
;   const u16* gB = Bt + (long)lrow * ldb + lch;
;   const int soff = lrow * LD + lch;
;     ...
;   GEMM_GLOAD(0)
;   __syncthreads();
;   GEMM_SSTORE(0)
;   if (nk > 1) GEMM_GLOAD(64)
;   __syncthreads();
;   DI void operator()(const float* Ct, int ldc, int m0, int n0, int tid, int bm) const {
;     ...
;     for (int it = 0; it < bm / 16; it++) {
;       int id = tid + 256 * it; int row = id >> 4, c8 = (id & 15) * 8;
;       int m = m0 + row;
;       const float* c = Ct + row * ldc + c8;
;       float4 a = *(const float4*)c, b = *(const float4*)(c + 4);
;       float x[8];
;       if (srcb != nullptr) {
;         unpack8(*(const uint4*)(srcb + (size_t)m * LDA + n0 + c8), x);
;       } else {
;         const float* sp = (m < NP ? src0 + (size_t)m * 1024 : src1 + (size_t)(m - NP) * 1024) + n0 + c8;
;         float4 sa = *(const float4*)sp, sb = *(const float4*)(sp + 4);
;         x[0] = sa.x; x[1] = sa.y; x[2] = sa.z; x[3] = sa.w; x[4] = sb.x; x[5] = sb.y; x[6] = sb.z; x[7] = sb.w;
;       }
;       x[0] += a.x; x[1] += a.y; x[2] += a.z; x[3] += a.w; x[4] += b.x; x[5] += b.y; x[6] += b.z; x[7] += b.w;
;       if (dstf != nullptr) {
;         float* o = dstf + (size_t)m * 1024 + n0 + c8;
;         *(float4*)o = make_float4(x[0], x[1], x[2], x[3]); *(float4*)(o + 4) = make_float4(x[4], x[5], x[6], x[7]);
;       } else {
;         *(uint4*)(dstb + (size_t)m * LDA + n0 + c8) = pack8(x);
;       }
	v_mov_b64_e32 v[6:7], v[170:171]
	v_mov_b64_e32 v[8:9], v[172:173]
	v_lshlrev_b32_e32 v22, 16, v6
	v_and_b32_e32 v23, 0xffff0000, v6
	v_lshlrev_b32_e32 v6, 16, v7
	v_and_b32_e32 v7, 0xffff0000, v7
	v_lshlrev_b32_e32 v24, 16, v8
	v_and_b32_e32 v25, 0xffff0000, v8
	v_lshlrev_b32_e32 v8, 16, v9
	v_and_b32_e32 v9, 0xffff0000, v9
	s_waitcnt lgkmcnt(1)
	v_pk_add_f32 v[10:11], v[10:11], v[22:23]
	v_pk_add_f32 v[12:13], v[12:13], v[6:7]
	s_waitcnt lgkmcnt(0)
	v_pk_add_f32 v[14:15], v[14:15], v[24:25]
	v_pk_add_f32 v[16:17], v[16:17], v[8:9]
	v_cvt_pk_bf16_f32 v6, v10, v11
	v_cvt_pk_bf16_f32 v7, v12, v13
	v_cvt_pk_bf16_f32 v8, v14, v15
	v_cvt_pk_bf16_f32 v9, v16, v17
	global_store_dwordx4 v[20:21], v[6:9], off
	v_mad_u64_u32 v[14:15], s[38:39], v27, s30, v[2:3]
	ds_read_b128 v[10:13], v14
	ds_read_b128 v[14:17], v14 offset:16
	v_add_u32_e32 v20, s36, v3
	v_mad_i64_i32 v[20:21], s[38:39], v20, s18, v[4:5]
	s_waitcnt vmcnt(7)
	v_mov_b64_e32 v[6:7], v[174:175]
	v_mov_b64_e32 v[8:9], v[176:177]
	v_lshlrev_b32_e32 v22, 16, v6
	v_and_b32_e32 v23, 0xffff0000, v6
	v_lshlrev_b32_e32 v6, 16, v7
	v_and_b32_e32 v7, 0xffff0000, v7
	v_lshlrev_b32_e32 v24, 16, v8
	v_and_b32_e32 v25, 0xffff0000, v8
	v_lshlrev_b32_e32 v8, 16, v9
	v_and_b32_e32 v9, 0xffff0000, v9
	s_waitcnt lgkmcnt(1)
	v_pk_add_f32 v[10:11], v[10:11], v[22:23]
	v_pk_add_f32 v[12:13], v[12:13], v[6:7]
	s_waitcnt lgkmcnt(0)
	v_pk_add_f32 v[14:15], v[14:15], v[24:25]
	v_pk_add_f32 v[16:17], v[16:17], v[8:9]
	v_cvt_pk_bf16_f32 v6, v10, v11
	v_cvt_pk_bf16_f32 v7, v12, v13
	v_cvt_pk_bf16_f32 v8, v14, v15
	v_cvt_pk_bf16_f32 v9, v16, v17
	global_store_dwordx4 v[18:19], v[6:9], off
	v_mad_u64_u32 v[14:15], s[38:39], v3, s30, v[2:3]
	ds_read_b128 v[10:13], v14
	ds_read_b128 v[14:17], v14 offset:16
	s_waitcnt vmcnt(7)
	v_mov_b64_e32 v[6:7], v[178:179]
	v_mov_b64_e32 v[8:9], v[180:181]
	v_lshlrev_b32_e32 v18, 16, v6
	v_and_b32_e32 v19, 0xffff0000, v6
	v_lshlrev_b32_e32 v6, 16, v7
	v_and_b32_e32 v7, 0xffff0000, v7
	v_lshlrev_b32_e32 v22, 16, v8
	v_and_b32_e32 v23, 0xffff0000, v8
	v_lshlrev_b32_e32 v8, 16, v9
	v_and_b32_e32 v9, 0xffff0000, v9
	s_waitcnt lgkmcnt(1)
	v_pk_add_f32 v[10:11], v[10:11], v[18:19]
	v_pk_add_f32 v[12:13], v[12:13], v[6:7]
	s_waitcnt lgkmcnt(0)
	v_pk_add_f32 v[14:15], v[14:15], v[22:23]
	v_pk_add_f32 v[16:17], v[16:17], v[8:9]
	v_cvt_pk_bf16_f32 v6, v10, v11
	v_cvt_pk_bf16_f32 v7, v12, v13
	v_cvt_pk_bf16_f32 v8, v14, v15
	v_cvt_pk_bf16_f32 v9, v16, v17
	global_store_dwordx4 v[20:21], v[6:9], off
	s_add_i32 s14, s31, 8
	s_addk_i32 s19, 0x2000
	s_cmp_lt_u32 s31, 24
	s_mov_b32 s31, s14
	s_barrier
	s_cbranch_scc1 .LBB0_2342
	s_lshl_b32 s6, s79, 6
	s_add_i32 s6, s80, s6
	s_cmpk_gt_i32 s6, 0xff
	s_cbranch_scc1 .LBB0_2349
	s_lshl_b32 s6, s6, 3
	s_lshl_b32 s10, s80, 6
	s_and_b32 s6, s6, 0xffffff80
	s_and_b32 s7, s10, 64
	s_or_b32 s7, s6, s7
	s_add_i32 s7, s7, 0x8000
	s_and_b32 s10, s10, 0x380
	s_mul_i32 s14, s7, 0x880
	s_mul_hi_i32 s11, s7, 0x880
	s_add_u32 s4, s4, s14
	v_mov_b32_e32 v1, v0
	s_addc_u32 s5, s5, s11
	s_mul_i32 s11, s10, 0x880
	s_movk_i32 s6, 0x880
	v_lshlrev_b32_e32 v2, 3, v1
	s_add_u32 s14, s3, s11
	v_ashrrev_i32_e32 v36, 3, v1
	v_and_b32_e32 v37, 56, v2
	v_mov_b64_e32 v[2:3], s[4:5]
	s_addc_u32 s15, s16, 0
	v_mad_i64_i32 v[2:3], s[4:5], v36, s6, v[2:3]
	v_lshlrev_b32_e32 v34, 1, v37
	v_mov_b32_e32 v35, 0
	v_lshl_add_u64 v[38:39], v[2:3], 0, v[34:35]
	v_mov_b64_e32 v[2:3], s[14:15]
	s_mov_b32 s3, 0x11000
	v_mad_i64_i32 v[10:11], s[4:5], v36, s6, v[2:3]
	v_add_co_u32_e32 v40, vcc, s3, v38
	v_lshl_add_u64 v[44:45], v[10:11], 0, v[34:35]
	s_nop 0
	v_addc_co_u32_e32 v41, vcc, 0, v39, vcc
	v_add_co_u32_e32 v42, vcc, s3, v44
	s_mov_b32 s3, 0x22000
	s_nop 0
	v_addc_co_u32_e32 v43, vcc, 0, v45, vcc
	v_add_co_u32_e32 v46, vcc, s3, v44
	s_mov_b32 s3, 0x33000
	s_nop 0
	v_addc_co_u32_e32 v47, vcc, 0, v45, vcc
	v_add_co_u32_e32 v48, vcc, s3, v44
	global_load_dwordx4 v[2:5], v[38:39], off
	s_nop 0
	v_addc_co_u32_e32 v49, vcc, 0, v45, vcc
	global_load_dwordx4 v[6:9], v[40:41], off
	global_load_dwordx4 v[10:13], v[44:45], off
	global_load_dwordx4 v[14:17], v[42:43], off
	global_load_dwordx4 v[18:21], v[46:47], off
	global_load_dwordx4 v[22:25], v[48:49], off
	s_barrier
	global_load_dwordx4 v[26:29], v[38:39], off offset:128
	global_load_dwordx4 v[30:33], v[40:41], off offset:128
	global_load_dwordx4 v[50:53], v[44:45], off offset:128
	global_load_dwordx4 v[54:57], v[42:43], off offset:128
	global_load_dwordx4 v[58:61], v[46:47], off offset:128
	global_load_dwordx4 v[62:65], v[48:49], off offset:128
	s_movk_i32 s4, 0x48
	s_mov_b32 s3, 0xfffffe0
	v_and_b32_e32 v34, 31, v1
	v_lshrrev_b32_e32 v66, 2, v1
	v_lshrrev_b32_e32 v67, 1, v1
	s_movk_i32 s11, 0x90
	v_and_b32_e32 v1, 0x5f, v1
	v_mul_lo_u32 v36, v36, s4
	v_and_or_b32 v68, v66, s3, v34
	v_and_b32_e32 v66, 16, v67
	v_add_lshl_u32 v34, v36, v37, 1
	v_mad_u64_u32 v[36:37], s[14:15], v68, s11, v[66:67]
	v_mad_u32_u24 v1, v1, s11, v66
	s_mov_b32 s5, 0
	s_waitcnt vmcnt(11)
	ds_write_b128 v34, v[2:5]
	s_waitcnt vmcnt(10)
	ds_write_b128 v34, v[6:9] offset:4608
	s_waitcnt vmcnt(9)
	ds_write_b128 v34, v[10:13] offset:18432
	s_waitcnt vmcnt(8)
	ds_write_b128 v34, v[14:17] offset:23040
	s_waitcnt vmcnt(7)
	ds_write_b128 v34, v[18:21] offset:27648
	s_waitcnt vmcnt(6)
	ds_write_b128 v34, v[22:25] offset:32256
	s_waitcnt lgkmcnt(0)
	s_barrier
; #define MFMA(a, b, c) __builtin_amdgcn_mfma_f32_32x32x16_bf16((a), (b), (c), 0, 0, 0)
; template <int TM, int TN>
; DI void gemm_mainloop(const u16* __restrict__ A, long lda, const u16* __restrict__ Bt, long ldb, int K, char* smem,
;                       f32x16 (&acc)[TM][TN]) {
;     ...
;   for (int kt = 0; kt < nk; kt++) {
;     const int buf = kt & 1;
;     const u16* cA = sA + buf * BM * LD + (wm * 32 * TM + r) * LD + h * 8;
;     const u16* cB = sB + buf * BN * LD + (wn * 32 * TN + r) * LD + h * 8;
;     bf16x8 af[TM], bfr[TN];
; #pragma unroll
;     for (int tm = 0; tm < TM; tm++) af[tm] = *(const bf16x8*)(cA + tm * 32 * LD);
; #pragma unroll
;     for (int tn = 0; tn < TN; tn++) bfr[tn] = *(const bf16x8*)(cB + tn * 32 * LD);
;     if (kt + 1 < nk) GEMM_SSTORE(buf ^ 1)
;     __builtin_amdgcn_sched_barrier(0);
;     __builtin_amdgcn_s_setprio(1);
; #pragma unroll
;     for (int tm = 0; tm < TM; tm++)
; #pragma unroll
;       for (int tn = 0; tn < TN; tn++) acc[tm][tn] = MFMA(af[tm], bfr[tn], acc[tm][tn]);
; #pragma unroll
;     for (int tm = 0; tm < TM; tm++) af[tm] = *(const bf16x8*)(cA + tm * 32 * LD + 16);
; #pragma unroll
;     for (int tn = 0; tn < TN; tn++) bfr[tn] = *(const bf16x8*)(cB + tn * 32 * LD + 16);
; #pragma unroll
;     for (int tm = 0; tm < TM; tm++)
; #pragma unroll
;       for (int tn = 0; tn < TN; tn++) acc[tm][tn] = MFMA(af[tm], bfr[tn], acc[tm][tn]);
;     __builtin_amdgcn_sched_group_barrier(0x8, 4, 0);
;     if (kt + 2 < nk) GEMM_GLOAD((kt + 2) * 64)
; #pragma unroll
;     for (int ks = 2; ks < 4; ks++) {
; #pragma unroll
;       for (int tm = 0; tm < TM; tm++) af[tm] = *(const bf16x8*)(cA + tm * 32 * LD + ks * 16);
; #pragma unroll
;       for (int tn = 0; tn < TN; tn++) bfr[tn] = *(const bf16x8*)(cB + tn * 32 * LD + ks * 16);
; #pragma unroll
;       for (int tm = 0; tm < TM; tm++)
; #pragma unroll
;         for (int tn = 0; tn < TN; tn++) acc[tm][tn] = MFMA(af[tm], bfr[tn], acc[tm][tn]);
;     }
;     __builtin_amdgcn_s_setprio(0);
;     __syncthreads();
;   }
	ds_read_b128 v[18:21], v36
	ds_read_b128 v[2:5], v1 offset:18432
	ds_read_b128 v[22:25], v1 offset:23040
	s_waitcnt vmcnt(5)
	ds_write_b128 v34, v[26:29] offset:9216
	s_waitcnt vmcnt(4)
	ds_write_b128 v34, v[30:33] offset:13824
	s_waitcnt vmcnt(3)
	ds_write_b128 v34, v[50:53] offset:36864
	s_waitcnt vmcnt(2)
	ds_write_b128 v34, v[54:57] offset:41472
	s_waitcnt vmcnt(1)
	ds_write_b128 v34, v[58:61] offset:46080
	s_waitcnt vmcnt(0)
	ds_write_b128 v34, v[62:65] offset:50688
	s_setprio 1
	ds_read_b128 v[50:53], v36 offset:32
	s_waitcnt lgkmcnt(8)
	v_mfma_f32_32x32x16_bf16 v[2:17], v[18:21], v[2:5], 0
	ds_read_b128 v[54:57], v1 offset:18464
	ds_read_b128 v[58:61], v1 offset:18528
	global_load_dwordx4 v[62:65], v[40:41], off offset:256
	global_load_dwordx4 v[66:69], v[44:45], off offset:256
	global_load_dwordx4 v[70:73], v[42:43], off offset:256
	global_load_dwordx4 v[74:77], v[46:47], off offset:256
	global_load_dwordx4 v[140:143], v[38:39], off offset:256
	global_load_dwordx4 v[144:147], v[48:49], off offset:256
	ds_read_b128 v[78:81], v1 offset:23136
	s_waitcnt lgkmcnt(10)
	v_mfma_f32_32x32x16_bf16 v[18:33], v[18:21], v[22:25], 0
	s_waitcnt lgkmcnt(2)
	v_mfma_f32_32x32x16_bf16 v[2:17], v[50:53], v[54:57], v[2:17]
	ds_read_b128 v[54:57], v1 offset:23072
	s_waitcnt lgkmcnt(0)
	v_mfma_f32_32x32x16_bf16 v[18:33], v[50:53], v[54:57], v[18:33]
	ds_read_b128 v[50:53], v36 offset:64
	ds_read_b128 v[54:57], v1 offset:18496
	s_waitcnt lgkmcnt(0)
	v_mfma_f32_32x32x16_bf16 v[2:17], v[50:53], v[54:57], v[2:17]
	ds_read_b128 v[54:57], v1 offset:23104
	s_waitcnt lgkmcnt(0)
	v_mfma_f32_32x32x16_bf16 v[18:33], v[50:53], v[54:57], v[18:33]
	ds_read_b128 v[50:53], v36 offset:96
	s_waitcnt lgkmcnt(0)
	v_mfma_f32_32x32x16_bf16 v[2:17], v[50:53], v[58:61], v[2:17]
	v_mfma_f32_32x32x16_bf16 v[18:33], v[50:53], v[78:81], v[18:33]
	s_setprio 0
	s_barrier
	ds_read_b128 v[50:53], v36 offset:9216
	ds_read_b128 v[78:81], v1 offset:36864
	ds_read_b128 v[82:85], v1 offset:41472
	s_waitcnt vmcnt(1)
	ds_write_b128 v34, v[140:143]
	ds_write_b128 v34, v[62:65] offset:4608
	ds_write_b128 v34, v[66:69] offset:18432
	ds_write_b128 v34, v[70:73] offset:23040
	ds_write_b128 v34, v[74:77] offset:27648
	s_waitcnt vmcnt(0)
	ds_write_b128 v34, v[144:147] offset:32256
	s_setprio 1
	s_waitcnt lgkmcnt(7)
	v_mfma_f32_32x32x16_bf16 v[2:17], v[50:53], v[78:81], v[2:17]
	ds_read_b128 v[54:57], v1 offset:36896
	ds_read_b128 v[58:61], v1 offset:36960
	global_load_dwordx4 v[62:65], v[40:41], off offset:384
	global_load_dwordx4 v[66:69], v[44:45], off offset:384
	global_load_dwordx4 v[70:73], v[42:43], off offset:384
	global_load_dwordx4 v[74:77], v[46:47], off offset:384
	global_load_dwordx4 v[140:143], v[38:39], off offset:384
	global_load_dwordx4 v[144:147], v[48:49], off offset:384
	ds_read_b128 v[78:81], v1 offset:41568
	s_waitcnt lgkmcnt(9)
	v_mfma_f32_32x32x16_bf16 v[18:33], v[50:53], v[82:85], v[18:33]
	ds_read_b128 v[50:53], v36 offset:9248
	s_waitcnt lgkmcnt(0)
	v_mfma_f32_32x32x16_bf16 v[2:17], v[50:53], v[54:57], v[2:17]
	ds_read_b128 v[54:57], v1 offset:41504
	s_waitcnt lgkmcnt(0)
	v_mfma_f32_32x32x16_bf16 v[18:33], v[50:53], v[54:57], v[18:33]
	ds_read_b128 v[50:53], v36 offset:9280
	ds_read_b128 v[54:57], v1 offset:36928
	s_waitcnt lgkmcnt(0)
	v_mfma_f32_32x32x16_bf16 v[2:17], v[50:53], v[54:57], v[2:17]
	ds_read_b128 v[54:57], v1 offset:41536
	s_waitcnt lgkmcnt(0)
	v_mfma_f32_32x32x16_bf16 v[18:33], v[50:53], v[54:57], v[18:33]
	ds_read_b128 v[50:53], v36 offset:9312
	s_waitcnt lgkmcnt(0)
	v_mfma_f32_32x32x16_bf16 v[2:17], v[50:53], v[58:61], v[2:17]
	v_mfma_f32_32x32x16_bf16 v[18:33], v[50:53], v[78:81], v[18:33]
	s_setprio 0
	s_barrier
	ds_read_b128 v[50:53], v36
	ds_read_b128 v[78:81], v1 offset:18432
	ds_read_b128 v[82:85], v1 offset:23040
	s_waitcnt vmcnt(1)
	ds_write_b128 v34, v[140:143] offset:9216
	ds_write_b128 v34, v[62:65] offset:13824
	ds_write_b128 v34, v[66:69] offset:36864
	ds_write_b128 v34, v[70:73] offset:41472
	ds_write_b128 v34, v[74:77] offset:46080
	s_waitcnt vmcnt(0)
	ds_write_b128 v34, v[144:147] offset:50688
	s_setprio 1
	s_waitcnt lgkmcnt(7)
	v_mfma_f32_32x32x16_bf16 v[2:17], v[50:53], v[78:81], v[2:17]
	ds_read_b128 v[54:57], v1 offset:18464
	ds_read_b128 v[58:61], v1 offset:18528
	global_load_dwordx4 v[62:65], v[40:41], off offset:512
	global_load_dwordx4 v[66:69], v[44:45], off offset:512
	global_load_dwordx4 v[70:73], v[42:43], off offset:512
	global_load_dwordx4 v[74:77], v[46:47], off offset:512
	global_load_dwordx4 v[140:143], v[38:39], off offset:512
	global_load_dwordx4 v[144:147], v[48:49], off offset:512
	ds_read_b128 v[78:81], v1 offset:23136
	s_waitcnt lgkmcnt(9)
	v_mfma_f32_32x32x16_bf16 v[18:33], v[50:53], v[82:85], v[18:33]
	ds_read_b128 v[50:53], v36 offset:32
	s_waitcnt lgkmcnt(0)
	v_mfma_f32_32x32x16_bf16 v[2:17], v[50:53], v[54:57], v[2:17]
	ds_read_b128 v[54:57], v1 offset:23072
	s_waitcnt lgkmcnt(0)
	v_mfma_f32_32x32x16_bf16 v[18:33], v[50:53], v[54:57], v[18:33]
	ds_read_b128 v[50:53], v36 offset:64
	ds_read_b128 v[54:57], v1 offset:18496
	s_waitcnt lgkmcnt(0)
	v_mfma_f32_32x32x16_bf16 v[2:17], v[50:53], v[54:57], v[2:17]
	ds_read_b128 v[54:57], v1 offset:23104
	s_waitcnt lgkmcnt(0)
	v_mfma_f32_32x32x16_bf16 v[18:33], v[50:53], v[54:57], v[18:33]
	ds_read_b128 v[50:53], v36 offset:96
	s_waitcnt lgkmcnt(0)
	v_mfma_f32_32x32x16_bf16 v[2:17], v[50:53], v[58:61], v[2:17]
	v_mfma_f32_32x32x16_bf16 v[18:33], v[50:53], v[78:81], v[18:33]
	s_setprio 0
	s_barrier
; #define MFMA(a, b, c) __builtin_amdgcn_mfma_f32_32x32x16_bf16((a), (b), (c), 0, 0, 0)
; template <int TM, int TN>
; DI void gemm_mainloop(const u16* __restrict__ A, long lda, const u16* __restrict__ Bt, long ldb, int K, char* smem,
;                       f32x16 (&acc)[TM][TN]) {
;     ...
;   for (int kt = 0; kt < nk; kt++) {
;     const int buf = kt & 1;
;     const u16* cA = sA + buf * BM * LD + (wm * 32 * TM + r) * LD + h * 8;
;     const u16* cB = sB + buf * BN * LD + (wn * 32 * TN + r) * LD + h * 8;
;     bf16x8 af[TM], bfr[TN];
; #pragma unroll
;     for (int tm = 0; tm < TM; tm++) af[tm] = *(const bf16x8*)(cA + tm * 32 * LD);
; #pragma unroll
;     for (int tn = 0; tn < TN; tn++) bfr[tn] = *(const bf16x8*)(cB + tn * 32 * LD);
;     if (kt + 1 < nk) GEMM_SSTORE(buf ^ 1)
;     __builtin_amdgcn_sched_barrier(0);
;     __builtin_amdgcn_s_setprio(1);
; #pragma unroll
;     for (int tm = 0; tm < TM; tm++)
; #pragma unroll
;       for (int tn = 0; tn < TN; tn++) acc[tm][tn] = MFMA(af[tm], bfr[tn], acc[tm][tn]);
; #pragma unroll
;     for (int tm = 0; tm < TM; tm++) af[tm] = *(const bf16x8*)(cA + tm * 32 * LD + 16);
; #pragma unroll
;     for (int tn = 0; tn < TN; tn++) bfr[tn] = *(const bf16x8*)(cB + tn * 32 * LD + 16);
; #pragma unroll
;     for (int tm = 0; tm < TM; tm++)
; #pragma unroll
;       for (int tn = 0; tn < TN; tn++) acc[tm][tn] = MFMA(af[tm], bfr[tn], acc[tm][tn]);
;     __builtin_amdgcn_sched_group_barrier(0x8, 4, 0);
;     if (kt + 2 < nk) GEMM_GLOAD((kt + 2) * 64)
; #pragma unroll
;     for (int ks = 2; ks < 4; ks++) {
; #pragma unroll
;       for (int tm = 0; tm < TM; tm++) af[tm] = *(const bf16x8*)(cA + tm * 32 * LD + ks * 16);
; #pragma unroll
;       for (int tn = 0; tn < TN; tn++) bfr[tn] = *(const bf16x8*)(cB + tn * 32 * LD + ks * 16);
; #pragma unroll
;       for (int tm = 0; tm < TM; tm++)
; #pragma unroll
;         for (int tn = 0; tn < TN; tn++) acc[tm][tn] = MFMA(af[tm], bfr[tn], acc[tm][tn]);
;     }
;     __builtin_amdgcn_s_setprio(0);
;     __syncthreads();
;   }
	ds_read_b128 v[50:53], v36 offset:9216
	ds_read_b128 v[78:81], v1 offset:36864
	ds_read_b128 v[82:85], v1 offset:41472
	s_waitcnt vmcnt(1)
	ds_write_b128 v34, v[140:143]
	ds_write_b128 v34, v[62:65] offset:4608
	ds_write_b128 v34, v[66:69] offset:18432
	ds_write_b128 v34, v[70:73] offset:23040
	ds_write_b128 v34, v[74:77] offset:27648
	s_waitcnt vmcnt(0)
	ds_write_b128 v34, v[144:147] offset:32256
	s_setprio 1
	s_waitcnt lgkmcnt(7)
	v_mfma_f32_32x32x16_bf16 v[2:17], v[50:53], v[78:81], v[2:17]
	ds_read_b128 v[54:57], v1 offset:36896
	ds_read_b128 v[58:61], v1 offset:36960
	global_load_dwordx4 v[62:65], v[40:41], off offset:640
	global_load_dwordx4 v[66:69], v[44:45], off offset:640
	global_load_dwordx4 v[70:73], v[42:43], off offset:640
	global_load_dwordx4 v[74:77], v[46:47], off offset:640
	global_load_dwordx4 v[140:143], v[38:39], off offset:640
	global_load_dwordx4 v[144:147], v[48:49], off offset:640
	ds_read_b128 v[78:81], v1 offset:41568
	s_waitcnt lgkmcnt(9)
	v_mfma_f32_32x32x16_bf16 v[18:33], v[50:53], v[82:85], v[18:33]
	ds_read_b128 v[50:53], v36 offset:9248
	s_waitcnt lgkmcnt(0)
	v_mfma_f32_32x32x16_bf16 v[2:17], v[50:53], v[54:57], v[2:17]
	ds_read_b128 v[54:57], v1 offset:41504
	s_waitcnt lgkmcnt(0)
	v_mfma_f32_32x32x16_bf16 v[18:33], v[50:53], v[54:57], v[18:33]
	ds_read_b128 v[50:53], v36 offset:9280
	ds_read_b128 v[54:57], v1 offset:36928
	s_waitcnt lgkmcnt(0)
	v_mfma_f32_32x32x16_bf16 v[2:17], v[50:53], v[54:57], v[2:17]
	ds_read_b128 v[54:57], v1 offset:41536
	s_waitcnt lgkmcnt(0)
	v_mfma_f32_32x32x16_bf16 v[18:33], v[50:53], v[54:57], v[18:33]
	ds_read_b128 v[50:53], v36 offset:9312
	s_waitcnt lgkmcnt(0)
	v_mfma_f32_32x32x16_bf16 v[2:17], v[50:53], v[58:61], v[2:17]
	v_mfma_f32_32x32x16_bf16 v[18:33], v[50:53], v[78:81], v[18:33]
	s_setprio 0
	s_barrier
	ds_read_b128 v[50:53], v36
	ds_read_b128 v[78:81], v1 offset:18432
	ds_read_b128 v[82:85], v1 offset:23040
	s_waitcnt vmcnt(1)
	ds_write_b128 v34, v[140:143] offset:9216
	ds_write_b128 v34, v[62:65] offset:13824
	ds_write_b128 v34, v[66:69] offset:36864
	ds_write_b128 v34, v[70:73] offset:41472
	ds_write_b128 v34, v[74:77] offset:46080
	s_waitcnt vmcnt(0)
	ds_write_b128 v34, v[144:147] offset:50688
	s_setprio 1
	s_waitcnt lgkmcnt(7)
	v_mfma_f32_32x32x16_bf16 v[2:17], v[50:53], v[78:81], v[2:17]
	ds_read_b128 v[54:57], v1 offset:18464
	ds_read_b128 v[58:61], v1 offset:18528
	global_load_dwordx4 v[62:65], v[40:41], off offset:768
	global_load_dwordx4 v[66:69], v[44:45], off offset:768
	global_load_dwordx4 v[70:73], v[42:43], off offset:768
	global_load_dwordx4 v[74:77], v[46:47], off offset:768
	global_load_dwordx4 v[140:143], v[38:39], off offset:768
	global_load_dwordx4 v[144:147], v[48:49], off offset:768
	ds_read_b128 v[78:81], v1 offset:23136
	s_waitcnt lgkmcnt(9)
	v_mfma_f32_32x32x16_bf16 v[18:33], v[50:53], v[82:85], v[18:33]
	ds_read_b128 v[50:53], v36 offset:32
	s_waitcnt lgkmcnt(0)
	v_mfma_f32_32x32x16_bf16 v[2:17], v[50:53], v[54:57], v[2:17]
	ds_read_b128 v[54:57], v1 offset:23072
	s_waitcnt lgkmcnt(0)
	v_mfma_f32_32x32x16_bf16 v[18:33], v[50:53], v[54:57], v[18:33]
	ds_read_b128 v[50:53], v36 offset:64
	ds_read_b128 v[54:57], v1 offset:18496
	s_waitcnt lgkmcnt(0)
	v_mfma_f32_32x32x16_bf16 v[2:17], v[50:53], v[54:57], v[2:17]
	ds_read_b128 v[54:57], v1 offset:23104
	s_waitcnt lgkmcnt(0)
	v_mfma_f32_32x32x16_bf16 v[18:33], v[50:53], v[54:57], v[18:33]
	ds_read_b128 v[50:53], v36 offset:96
	s_waitcnt lgkmcnt(0)
	v_mfma_f32_32x32x16_bf16 v[2:17], v[50:53], v[58:61], v[2:17]
	v_mfma_f32_32x32x16_bf16 v[18:33], v[50:53], v[78:81], v[18:33]
	s_setprio 0
	s_barrier
	ds_read_b128 v[50:53], v36 offset:9216
	ds_read_b128 v[78:81], v1 offset:36864
	ds_read_b128 v[82:85], v1 offset:41472
	s_waitcnt vmcnt(1)
	ds_write_b128 v34, v[140:143]
	ds_write_b128 v34, v[62:65] offset:4608
	ds_write_b128 v34, v[66:69] offset:18432
	ds_write_b128 v34, v[70:73] offset:23040
	ds_write_b128 v34, v[74:77] offset:27648
	s_waitcnt vmcnt(0)
	ds_write_b128 v34, v[144:147] offset:32256
	s_setprio 1
	s_waitcnt lgkmcnt(7)
	v_mfma_f32_32x32x16_bf16 v[2:17], v[50:53], v[78:81], v[2:17]
	ds_read_b128 v[54:57], v1 offset:36896
	ds_read_b128 v[58:61], v1 offset:36960
	global_load_dwordx4 v[62:65], v[40:41], off offset:896
	global_load_dwordx4 v[66:69], v[44:45], off offset:896
	global_load_dwordx4 v[70:73], v[42:43], off offset:896
	global_load_dwordx4 v[74:77], v[46:47], off offset:896
	global_load_dwordx4 v[140:143], v[38:39], off offset:896
	global_load_dwordx4 v[144:147], v[48:49], off offset:896
	ds_read_b128 v[78:81], v1 offset:41568
	s_waitcnt lgkmcnt(9)
	v_mfma_f32_32x32x16_bf16 v[18:33], v[50:53], v[82:85], v[18:33]
	ds_read_b128 v[50:53], v36 offset:9248
	s_waitcnt lgkmcnt(0)
	v_mfma_f32_32x32x16_bf16 v[2:17], v[50:53], v[54:57], v[2:17]
	ds_read_b128 v[54:57], v1 offset:41504
	s_waitcnt lgkmcnt(0)
	v_mfma_f32_32x32x16_bf16 v[18:33], v[50:53], v[54:57], v[18:33]
	ds_read_b128 v[50:53], v36 offset:9280
	ds_read_b128 v[54:57], v1 offset:36928
	s_waitcnt lgkmcnt(0)
	v_mfma_f32_32x32x16_bf16 v[2:17], v[50:53], v[54:57], v[2:17]
	ds_read_b128 v[54:57], v1 offset:41536
	s_waitcnt lgkmcnt(0)
	v_mfma_f32_32x32x16_bf16 v[18:33], v[50:53], v[54:57], v[18:33]
	ds_read_b128 v[50:53], v36 offset:9312
	s_waitcnt lgkmcnt(0)
	v_mfma_f32_32x32x16_bf16 v[2:17], v[50:53], v[58:61], v[2:17]
	v_mfma_f32_32x32x16_bf16 v[18:33], v[50:53], v[78:81], v[18:33]
	s_setprio 0
	s_barrier
; #define MFMA(a, b, c) __builtin_amdgcn_mfma_f32_32x32x16_bf16((a), (b), (c), 0, 0, 0)
; template <int TM, int TN>
; DI void gemm_mainloop(const u16* __restrict__ A, long lda, const u16* __restrict__ Bt, long ldb, int K, char* smem,
;                       f32x16 (&acc)[TM][TN]) {
;     ...
;   for (int kt = 0; kt < nk; kt++) {
;     const int buf = kt & 1;
;     const u16* cA = sA + buf * BM * LD + (wm * 32 * TM + r) * LD + h * 8;
;     const u16* cB = sB + buf * BN * LD + (wn * 32 * TN + r) * LD + h * 8;
;     bf16x8 af[TM], bfr[TN];
; #pragma unroll
;     for (int tm = 0; tm < TM; tm++) af[tm] = *(const bf16x8*)(cA + tm * 32 * LD);
; #pragma unroll
;     for (int tn = 0; tn < TN; tn++) bfr[tn] = *(const bf16x8*)(cB + tn * 32 * LD);
;     if (kt + 1 < nk) GEMM_SSTORE(buf ^ 1)
;     __builtin_amdgcn_sched_barrier(0);
;     __builtin_amdgcn_s_setprio(1);
; #pragma unroll
;     for (int tm = 0; tm < TM; tm++)
; #pragma unroll
;       for (int tn = 0; tn < TN; tn++) acc[tm][tn] = MFMA(af[tm], bfr[tn], acc[tm][tn]);
; #pragma unroll
;     for (int tm = 0; tm < TM; tm++) af[tm] = *(const bf16x8*)(cA + tm * 32 * LD + 16);
; #pragma unroll
;     for (int tn = 0; tn < TN; tn++) bfr[tn] = *(const bf16x8*)(cB + tn * 32 * LD + 16);
; #pragma unroll
;     for (int tm = 0; tm < TM; tm++)
; #pragma unroll
;       for (int tn = 0; tn < TN; tn++) acc[tm][tn] = MFMA(af[tm], bfr[tn], acc[tm][tn]);
;     __builtin_amdgcn_sched_group_barrier(0x8, 4, 0);
;     if (kt + 2 < nk) GEMM_GLOAD((kt + 2) * 64)
; #pragma unroll
;     for (int ks = 2; ks < 4; ks++) {
; #pragma unroll
;       for (int tm = 0; tm < TM; tm++) af[tm] = *(const bf16x8*)(cA + tm * 32 * LD + ks * 16);
; #pragma unroll
;       for (int tn = 0; tn < TN; tn++) bfr[tn] = *(const bf16x8*)(cB + tn * 32 * LD + ks * 16);
; #pragma unroll
;       for (int tm = 0; tm < TM; tm++)
; #pragma unroll
;         for (int tn = 0; tn < TN; tn++) acc[tm][tn] = MFMA(af[tm], bfr[tn], acc[tm][tn]);
;     }
;     __builtin_amdgcn_s_setprio(0);
;     __syncthreads();
;   }
	ds_read_b128 v[50:53], v36
	ds_read_b128 v[78:81], v1 offset:18432
	ds_read_b128 v[82:85], v1 offset:23040
	s_waitcnt vmcnt(1)
	ds_write_b128 v34, v[140:143] offset:9216
	ds_write_b128 v34, v[62:65] offset:13824
	ds_write_b128 v34, v[66:69] offset:36864
	ds_write_b128 v34, v[70:73] offset:41472
	ds_write_b128 v34, v[74:77] offset:46080
	s_waitcnt vmcnt(0)
	ds_write_b128 v34, v[144:147] offset:50688
	s_setprio 1
	s_waitcnt lgkmcnt(7)
	v_mfma_f32_32x32x16_bf16 v[2:17], v[50:53], v[78:81], v[2:17]
	ds_read_b128 v[54:57], v1 offset:18464
	ds_read_b128 v[58:61], v1 offset:18528
	global_load_dwordx4 v[62:65], v[40:41], off offset:1024
	global_load_dwordx4 v[66:69], v[44:45], off offset:1024
	global_load_dwordx4 v[70:73], v[42:43], off offset:1024
	global_load_dwordx4 v[74:77], v[46:47], off offset:1024
	global_load_dwordx4 v[140:143], v[38:39], off offset:1024
	global_load_dwordx4 v[144:147], v[48:49], off offset:1024
	ds_read_b128 v[78:81], v1 offset:23136
	s_waitcnt lgkmcnt(9)
	v_mfma_f32_32x32x16_bf16 v[18:33], v[50:53], v[82:85], v[18:33]
	ds_read_b128 v[50:53], v36 offset:32
	s_waitcnt lgkmcnt(0)
	v_mfma_f32_32x32x16_bf16 v[2:17], v[50:53], v[54:57], v[2:17]
	ds_read_b128 v[54:57], v1 offset:23072
	s_waitcnt lgkmcnt(0)
	v_mfma_f32_32x32x16_bf16 v[18:33], v[50:53], v[54:57], v[18:33]
	ds_read_b128 v[50:53], v36 offset:64
	ds_read_b128 v[54:57], v1 offset:18496
	s_waitcnt lgkmcnt(0)
	v_mfma_f32_32x32x16_bf16 v[2:17], v[50:53], v[54:57], v[2:17]
	ds_read_b128 v[54:57], v1 offset:23104
	s_waitcnt lgkmcnt(0)
	v_mfma_f32_32x32x16_bf16 v[18:33], v[50:53], v[54:57], v[18:33]
	ds_read_b128 v[50:53], v36 offset:96
	s_waitcnt lgkmcnt(0)
	v_mfma_f32_32x32x16_bf16 v[2:17], v[50:53], v[58:61], v[2:17]
	v_mfma_f32_32x32x16_bf16 v[18:33], v[50:53], v[78:81], v[18:33]
	s_setprio 0
	s_barrier
	ds_read_b128 v[50:53], v36 offset:9216
	ds_read_b128 v[78:81], v1 offset:36864
	ds_read_b128 v[82:85], v1 offset:41472
	s_waitcnt vmcnt(1)
	ds_write_b128 v34, v[140:143]
	ds_write_b128 v34, v[62:65] offset:4608
	ds_write_b128 v34, v[66:69] offset:18432
	ds_write_b128 v34, v[70:73] offset:23040
	ds_write_b128 v34, v[74:77] offset:27648
	s_waitcnt vmcnt(0)
	ds_write_b128 v34, v[144:147] offset:32256
	s_setprio 1
	s_waitcnt lgkmcnt(7)
	v_mfma_f32_32x32x16_bf16 v[2:17], v[50:53], v[78:81], v[2:17]
	ds_read_b128 v[54:57], v1 offset:36896
	ds_read_b128 v[58:61], v1 offset:36960
	global_load_dwordx4 v[62:65], v[40:41], off offset:1152
	global_load_dwordx4 v[66:69], v[44:45], off offset:1152
	global_load_dwordx4 v[70:73], v[42:43], off offset:1152
	global_load_dwordx4 v[74:77], v[46:47], off offset:1152
	global_load_dwordx4 v[140:143], v[38:39], off offset:1152
	global_load_dwordx4 v[144:147], v[48:49], off offset:1152
	ds_read_b128 v[78:81], v1 offset:41568
	s_waitcnt lgkmcnt(9)
	v_mfma_f32_32x32x16_bf16 v[18:33], v[50:53], v[82:85], v[18:33]
	ds_read_b128 v[50:53], v36 offset:9248
	s_waitcnt lgkmcnt(0)
	v_mfma_f32_32x32x16_bf16 v[2:17], v[50:53], v[54:57], v[2:17]
	ds_read_b128 v[54:57], v1 offset:41504
	s_waitcnt lgkmcnt(0)
	v_mfma_f32_32x32x16_bf16 v[18:33], v[50:53], v[54:57], v[18:33]
	ds_read_b128 v[50:53], v36 offset:9280
	ds_read_b128 v[54:57], v1 offset:36928
	s_waitcnt lgkmcnt(0)
	v_mfma_f32_32x32x16_bf16 v[2:17], v[50:53], v[54:57], v[2:17]
	ds_read_b128 v[54:57], v1 offset:41536
	s_waitcnt lgkmcnt(0)
	v_mfma_f32_32x32x16_bf16 v[18:33], v[50:53], v[54:57], v[18:33]
	ds_read_b128 v[50:53], v36 offset:9312
	s_waitcnt lgkmcnt(0)
	v_mfma_f32_32x32x16_bf16 v[2:17], v[50:53], v[58:61], v[2:17]
	v_mfma_f32_32x32x16_bf16 v[18:33], v[50:53], v[78:81], v[18:33]
	s_setprio 0
	s_barrier
	ds_read_b128 v[50:53], v36
	ds_read_b128 v[78:81], v1 offset:18432
	ds_read_b128 v[82:85], v1 offset:23040
	s_waitcnt vmcnt(1)
	ds_write_b128 v34, v[140:143] offset:9216
	ds_write_b128 v34, v[62:65] offset:13824
	ds_write_b128 v34, v[66:69] offset:36864
	ds_write_b128 v34, v[70:73] offset:41472
	ds_write_b128 v34, v[74:77] offset:46080
	s_waitcnt vmcnt(0)
	ds_write_b128 v34, v[144:147] offset:50688
	s_setprio 1
	s_waitcnt lgkmcnt(7)
	v_mfma_f32_32x32x16_bf16 v[2:17], v[50:53], v[78:81], v[2:17]
	ds_read_b128 v[54:57], v1 offset:18464
	ds_read_b128 v[58:61], v1 offset:18528
	global_load_dwordx4 v[62:65], v[40:41], off offset:1280
	global_load_dwordx4 v[66:69], v[44:45], off offset:1280
	global_load_dwordx4 v[70:73], v[42:43], off offset:1280
	global_load_dwordx4 v[74:77], v[46:47], off offset:1280
	global_load_dwordx4 v[140:143], v[38:39], off offset:1280
	global_load_dwordx4 v[144:147], v[48:49], off offset:1280
	ds_read_b128 v[78:81], v1 offset:23136
	s_waitcnt lgkmcnt(9)
	v_mfma_f32_32x32x16_bf16 v[18:33], v[50:53], v[82:85], v[18:33]
	ds_read_b128 v[50:53], v36 offset:32
	s_waitcnt lgkmcnt(0)
	v_mfma_f32_32x32x16_bf16 v[2:17], v[50:53], v[54:57], v[2:17]
	ds_read_b128 v[54:57], v1 offset:23072
	s_waitcnt lgkmcnt(0)
	v_mfma_f32_32x32x16_bf16 v[18:33], v[50:53], v[54:57], v[18:33]
	ds_read_b128 v[50:53], v36 offset:64
	ds_read_b128 v[54:57], v1 offset:18496
	s_waitcnt lgkmcnt(0)
	v_mfma_f32_32x32x16_bf16 v[2:17], v[50:53], v[54:57], v[2:17]
	ds_read_b128 v[54:57], v1 offset:23104
	s_waitcnt lgkmcnt(0)
	v_mfma_f32_32x32x16_bf16 v[18:33], v[50:53], v[54:57], v[18:33]
	ds_read_b128 v[50:53], v36 offset:96
	s_waitcnt lgkmcnt(0)
	v_mfma_f32_32x32x16_bf16 v[2:17], v[50:53], v[58:61], v[2:17]
	v_mfma_f32_32x32x16_bf16 v[18:33], v[50:53], v[78:81], v[18:33]
	s_setprio 0
	s_barrier
; #define MFMA(a, b, c) __builtin_amdgcn_mfma_f32_32x32x16_bf16((a), (b), (c), 0, 0, 0)
; template <int TM, int TN>
; DI void gemm_mainloop(const u16* __restrict__ A, long lda, const u16* __restrict__ Bt, long ldb, int K, char* smem,
;                       f32x16 (&acc)[TM][TN]) {
;     ...
;   for (int kt = 0; kt < nk; kt++) {
;     const int buf = kt & 1;
;     const u16* cA = sA + buf * BM * LD + (wm * 32 * TM + r) * LD + h * 8;
;     const u16* cB = sB + buf * BN * LD + (wn * 32 * TN + r) * LD + h * 8;
;     bf16x8 af[TM], bfr[TN];
; #pragma unroll
;     for (int tm = 0; tm < TM; tm++) af[tm] = *(const bf16x8*)(cA + tm * 32 * LD);
; #pragma unroll
;     for (int tn = 0; tn < TN; tn++) bfr[tn] = *(const bf16x8*)(cB + tn * 32 * LD);
;     if (kt + 1 < nk) GEMM_SSTORE(buf ^ 1)
;     __builtin_amdgcn_sched_barrier(0);
;     __builtin_amdgcn_s_setprio(1);
; #pragma unroll
;     for (int tm = 0; tm < TM; tm++)
; #pragma unroll
;       for (int tn = 0; tn < TN; tn++) acc[tm][tn] = MFMA(af[tm], bfr[tn], acc[tm][tn]);
; #pragma unroll
;     for (int tm = 0; tm < TM; tm++) af[tm] = *(const bf16x8*)(cA + tm * 32 * LD + 16);
; #pragma unroll
;     for (int tn = 0; tn < TN; tn++) bfr[tn] = *(const bf16x8*)(cB + tn * 32 * LD + 16);
; #pragma unroll
;     for (int tm = 0; tm < TM; tm++)
; #pragma unroll
;       for (int tn = 0; tn < TN; tn++) acc[tm][tn] = MFMA(af[tm], bfr[tn], acc[tm][tn]);
;     __builtin_amdgcn_sched_group_barrier(0x8, 4, 0);
;     if (kt + 2 < nk) GEMM_GLOAD((kt + 2) * 64)
; #pragma unroll
;     for (int ks = 2; ks < 4; ks++) {
; #pragma unroll
;       for (int tm = 0; tm < TM; tm++) af[tm] = *(const bf16x8*)(cA + tm * 32 * LD + ks * 16);
; #pragma unroll
;       for (int tn = 0; tn < TN; tn++) bfr[tn] = *(const bf16x8*)(cB + tn * 32 * LD + ks * 16);
; #pragma unroll
;       for (int tm = 0; tm < TM; tm++)
; #pragma unroll
;         for (int tn = 0; tn < TN; tn++) acc[tm][tn] = MFMA(af[tm], bfr[tn], acc[tm][tn]);
;     }
;     __builtin_amdgcn_s_setprio(0);
;     __syncthreads();
;   }
	ds_read_b128 v[50:53], v36 offset:9216
	ds_read_b128 v[78:81], v1 offset:36864
	ds_read_b128 v[82:85], v1 offset:41472
	s_waitcnt vmcnt(1)
	ds_write_b128 v34, v[140:143]
	ds_write_b128 v34, v[62:65] offset:4608
	ds_write_b128 v34, v[66:69] offset:18432
	ds_write_b128 v34, v[70:73] offset:23040
	ds_write_b128 v34, v[74:77] offset:27648
	s_waitcnt vmcnt(0)
	ds_write_b128 v34, v[144:147] offset:32256
	s_setprio 1
	s_waitcnt lgkmcnt(7)
	v_mfma_f32_32x32x16_bf16 v[2:17], v[50:53], v[78:81], v[2:17]
	ds_read_b128 v[54:57], v1 offset:36896
	ds_read_b128 v[58:61], v1 offset:36960
	global_load_dwordx4 v[62:65], v[40:41], off offset:1408
	global_load_dwordx4 v[66:69], v[44:45], off offset:1408
	global_load_dwordx4 v[70:73], v[42:43], off offset:1408
	global_load_dwordx4 v[74:77], v[46:47], off offset:1408
	global_load_dwordx4 v[140:143], v[38:39], off offset:1408
	global_load_dwordx4 v[144:147], v[48:49], off offset:1408
	ds_read_b128 v[78:81], v1 offset:41568
	s_waitcnt lgkmcnt(9)
	v_mfma_f32_32x32x16_bf16 v[18:33], v[50:53], v[82:85], v[18:33]
	ds_read_b128 v[50:53], v36 offset:9248
	s_waitcnt lgkmcnt(0)
	v_mfma_f32_32x32x16_bf16 v[2:17], v[50:53], v[54:57], v[2:17]
	ds_read_b128 v[54:57], v1 offset:41504
	s_waitcnt lgkmcnt(0)
	v_mfma_f32_32x32x16_bf16 v[18:33], v[50:53], v[54:57], v[18:33]
	ds_read_b128 v[50:53], v36 offset:9280
	ds_read_b128 v[54:57], v1 offset:36928
	s_waitcnt lgkmcnt(0)
	v_mfma_f32_32x32x16_bf16 v[2:17], v[50:53], v[54:57], v[2:17]
	ds_read_b128 v[54:57], v1 offset:41536
	s_waitcnt lgkmcnt(0)
	v_mfma_f32_32x32x16_bf16 v[18:33], v[50:53], v[54:57], v[18:33]
	ds_read_b128 v[50:53], v36 offset:9312
	s_waitcnt lgkmcnt(0)
	v_mfma_f32_32x32x16_bf16 v[2:17], v[50:53], v[58:61], v[2:17]
	v_mfma_f32_32x32x16_bf16 v[18:33], v[50:53], v[78:81], v[18:33]
	s_setprio 0
	s_barrier
	ds_read_b128 v[50:53], v36
	ds_read_b128 v[78:81], v1 offset:18432
	ds_read_b128 v[82:85], v1 offset:23040
	s_waitcnt vmcnt(1)
	ds_write_b128 v34, v[140:143] offset:9216
	ds_write_b128 v34, v[62:65] offset:13824
	ds_write_b128 v34, v[66:69] offset:36864
	ds_write_b128 v34, v[70:73] offset:41472
	ds_write_b128 v34, v[74:77] offset:46080
	s_waitcnt vmcnt(0)
	ds_write_b128 v34, v[144:147] offset:50688
	s_setprio 1
	s_waitcnt lgkmcnt(7)
	v_mfma_f32_32x32x16_bf16 v[2:17], v[50:53], v[78:81], v[2:17]
	ds_read_b128 v[54:57], v1 offset:18464
	ds_read_b128 v[58:61], v1 offset:18528
	global_load_dwordx4 v[62:65], v[40:41], off offset:1536
	global_load_dwordx4 v[66:69], v[44:45], off offset:1536
	global_load_dwordx4 v[70:73], v[42:43], off offset:1536
	global_load_dwordx4 v[74:77], v[46:47], off offset:1536
	global_load_dwordx4 v[140:143], v[38:39], off offset:1536
	global_load_dwordx4 v[144:147], v[48:49], off offset:1536
	ds_read_b128 v[78:81], v1 offset:23136
	s_waitcnt lgkmcnt(9)
	v_mfma_f32_32x32x16_bf16 v[18:33], v[50:53], v[82:85], v[18:33]
	ds_read_b128 v[50:53], v36 offset:32
	s_waitcnt lgkmcnt(0)
	v_mfma_f32_32x32x16_bf16 v[2:17], v[50:53], v[54:57], v[2:17]
	ds_read_b128 v[54:57], v1 offset:23072
	s_waitcnt lgkmcnt(0)
	v_mfma_f32_32x32x16_bf16 v[18:33], v[50:53], v[54:57], v[18:33]
	ds_read_b128 v[50:53], v36 offset:64
	ds_read_b128 v[54:57], v1 offset:18496
	s_waitcnt lgkmcnt(0)
	v_mfma_f32_32x32x16_bf16 v[2:17], v[50:53], v[54:57], v[2:17]
	ds_read_b128 v[54:57], v1 offset:23104
	s_waitcnt lgkmcnt(0)
	v_mfma_f32_32x32x16_bf16 v[18:33], v[50:53], v[54:57], v[18:33]
	ds_read_b128 v[50:53], v36 offset:96
	s_waitcnt lgkmcnt(0)
	v_mfma_f32_32x32x16_bf16 v[2:17], v[50:53], v[58:61], v[2:17]
	v_mfma_f32_32x32x16_bf16 v[18:33], v[50:53], v[78:81], v[18:33]
	s_setprio 0
	s_barrier
	ds_read_b128 v[50:53], v36 offset:9216
	ds_read_b128 v[78:81], v1 offset:36864
	ds_read_b128 v[82:85], v1 offset:41472
	s_waitcnt vmcnt(1)
	ds_write_b128 v34, v[140:143]
	ds_write_b128 v34, v[62:65] offset:4608
	ds_write_b128 v34, v[66:69] offset:18432
	ds_write_b128 v34, v[70:73] offset:23040
	ds_write_b128 v34, v[74:77] offset:27648
	s_waitcnt vmcnt(0)
	ds_write_b128 v34, v[144:147] offset:32256
	s_setprio 1
	s_waitcnt lgkmcnt(7)
	v_mfma_f32_32x32x16_bf16 v[2:17], v[50:53], v[78:81], v[2:17]
	ds_read_b128 v[54:57], v1 offset:36896
	ds_read_b128 v[58:61], v1 offset:36960
	global_load_dwordx4 v[62:65], v[40:41], off offset:1664
	global_load_dwordx4 v[66:69], v[44:45], off offset:1664
	global_load_dwordx4 v[70:73], v[42:43], off offset:1664
	global_load_dwordx4 v[74:77], v[46:47], off offset:1664
	global_load_dwordx4 v[140:143], v[38:39], off offset:1664
	global_load_dwordx4 v[144:147], v[48:49], off offset:1664
	ds_read_b128 v[78:81], v1 offset:41568
	s_waitcnt lgkmcnt(9)
	v_mfma_f32_32x32x16_bf16 v[18:33], v[50:53], v[82:85], v[18:33]
	ds_read_b128 v[50:53], v36 offset:9248
	s_waitcnt lgkmcnt(0)
	v_mfma_f32_32x32x16_bf16 v[2:17], v[50:53], v[54:57], v[2:17]
	ds_read_b128 v[54:57], v1 offset:41504
	s_waitcnt lgkmcnt(0)
	v_mfma_f32_32x32x16_bf16 v[18:33], v[50:53], v[54:57], v[18:33]
	ds_read_b128 v[50:53], v36 offset:9280
	ds_read_b128 v[54:57], v1 offset:36928
	s_waitcnt lgkmcnt(0)
	v_mfma_f32_32x32x16_bf16 v[2:17], v[50:53], v[54:57], v[2:17]
	ds_read_b128 v[54:57], v1 offset:41536
	s_waitcnt lgkmcnt(0)
	v_mfma_f32_32x32x16_bf16 v[18:33], v[50:53], v[54:57], v[18:33]
	ds_read_b128 v[50:53], v36 offset:9312
	s_waitcnt lgkmcnt(0)
	v_mfma_f32_32x32x16_bf16 v[2:17], v[50:53], v[58:61], v[2:17]
	v_mfma_f32_32x32x16_bf16 v[18:33], v[50:53], v[78:81], v[18:33]
	s_setprio 0
	s_barrier
; #define MFMA(a, b, c) __builtin_amdgcn_mfma_f32_32x32x16_bf16((a), (b), (c), 0, 0, 0)
; template <int TM, int TN>
; DI void gemm_mainloop(const u16* __restrict__ A, long lda, const u16* __restrict__ Bt, long ldb, int K, char* smem,
;                       f32x16 (&acc)[TM][TN]) {
;     ...
;   for (int kt = 0; kt < nk; kt++) {
;     const int buf = kt & 1;
;     const u16* cA = sA + buf * BM * LD + (wm * 32 * TM + r) * LD + h * 8;
;     const u16* cB = sB + buf * BN * LD + (wn * 32 * TN + r) * LD + h * 8;
;     bf16x8 af[TM], bfr[TN];
; #pragma unroll
;     for (int tm = 0; tm < TM; tm++) af[tm] = *(const bf16x8*)(cA + tm * 32 * LD);
; #pragma unroll
;     for (int tn = 0; tn < TN; tn++) bfr[tn] = *(const bf16x8*)(cB + tn * 32 * LD);
;     if (kt + 1 < nk) GEMM_SSTORE(buf ^ 1)
;     __builtin_amdgcn_sched_barrier(0);
;     __builtin_amdgcn_s_setprio(1);
; #pragma unroll
;     for (int tm = 0; tm < TM; tm++)
; #pragma unroll
;       for (int tn = 0; tn < TN; tn++) acc[tm][tn] = MFMA(af[tm], bfr[tn], acc[tm][tn]);
; #pragma unroll
;     for (int tm = 0; tm < TM; tm++) af[tm] = *(const bf16x8*)(cA + tm * 32 * LD + 16);
; #pragma unroll
;     for (int tn = 0; tn < TN; tn++) bfr[tn] = *(const bf16x8*)(cB + tn * 32 * LD + 16);
; #pragma unroll
;     for (int tm = 0; tm < TM; tm++)
; #pragma unroll
;       for (int tn = 0; tn < TN; tn++) acc[tm][tn] = MFMA(af[tm], bfr[tn], acc[tm][tn]);
;     __builtin_amdgcn_sched_group_barrier(0x8, 4, 0);
;     if (kt + 2 < nk) GEMM_GLOAD((kt + 2) * 64)
; #pragma unroll
;     for (int ks = 2; ks < 4; ks++) {
; #pragma unroll
;       for (int tm = 0; tm < TM; tm++) af[tm] = *(const bf16x8*)(cA + tm * 32 * LD + ks * 16);
; #pragma unroll
;       for (int tn = 0; tn < TN; tn++) bfr[tn] = *(const bf16x8*)(cB + tn * 32 * LD + ks * 16);
; #pragma unroll
;       for (int tm = 0; tm < TM; tm++)
; #pragma unroll
;         for (int tn = 0; tn < TN; tn++) acc[tm][tn] = MFMA(af[tm], bfr[tn], acc[tm][tn]);
;     }
;     __builtin_amdgcn_s_setprio(0);
;     __syncthreads();
;   }
	ds_read_b128 v[50:53], v36
	ds_read_b128 v[78:81], v1 offset:18432
	ds_read_b128 v[82:85], v1 offset:23040
	s_waitcnt vmcnt(1)
	ds_write_b128 v34, v[140:143] offset:9216
	ds_write_b128 v34, v[62:65] offset:13824
	ds_write_b128 v34, v[66:69] offset:36864
	ds_write_b128 v34, v[70:73] offset:41472
	ds_write_b128 v34, v[74:77] offset:46080
	s_waitcnt vmcnt(0)
	ds_write_b128 v34, v[144:147] offset:50688
	s_setprio 1
	s_waitcnt lgkmcnt(7)
	v_mfma_f32_32x32x16_bf16 v[2:17], v[50:53], v[78:81], v[2:17]
	ds_read_b128 v[54:57], v1 offset:18464
	ds_read_b128 v[58:61], v1 offset:18528
	global_load_dwordx4 v[62:65], v[40:41], off offset:1792
	global_load_dwordx4 v[66:69], v[44:45], off offset:1792
	global_load_dwordx4 v[70:73], v[42:43], off offset:1792
	global_load_dwordx4 v[74:77], v[46:47], off offset:1792
	global_load_dwordx4 v[140:143], v[38:39], off offset:1792
	global_load_dwordx4 v[144:147], v[48:49], off offset:1792
	ds_read_b128 v[78:81], v1 offset:23136
	s_waitcnt lgkmcnt(9)
	v_mfma_f32_32x32x16_bf16 v[18:33], v[50:53], v[82:85], v[18:33]
	ds_read_b128 v[50:53], v36 offset:32
	s_waitcnt lgkmcnt(0)
	v_mfma_f32_32x32x16_bf16 v[2:17], v[50:53], v[54:57], v[2:17]
	ds_read_b128 v[54:57], v1 offset:23072
	s_waitcnt lgkmcnt(0)
	v_mfma_f32_32x32x16_bf16 v[18:33], v[50:53], v[54:57], v[18:33]
	ds_read_b128 v[50:53], v36 offset:64
	ds_read_b128 v[54:57], v1 offset:18496
	s_waitcnt lgkmcnt(0)
	v_mfma_f32_32x32x16_bf16 v[2:17], v[50:53], v[54:57], v[2:17]
	ds_read_b128 v[54:57], v1 offset:23104
	s_waitcnt lgkmcnt(0)
	v_mfma_f32_32x32x16_bf16 v[18:33], v[50:53], v[54:57], v[18:33]
	ds_read_b128 v[50:53], v36 offset:96
	s_waitcnt lgkmcnt(0)
	v_mfma_f32_32x32x16_bf16 v[2:17], v[50:53], v[58:61], v[2:17]
	v_mfma_f32_32x32x16_bf16 v[18:33], v[50:53], v[78:81], v[18:33]
	s_setprio 0
	s_barrier
	ds_read_b128 v[50:53], v36 offset:9216
	ds_read_b128 v[78:81], v1 offset:36864
	ds_read_b128 v[82:85], v1 offset:41472
	s_waitcnt vmcnt(1)
	ds_write_b128 v34, v[140:143]
	ds_write_b128 v34, v[62:65] offset:4608
	ds_write_b128 v34, v[66:69] offset:18432
	ds_write_b128 v34, v[70:73] offset:23040
	ds_write_b128 v34, v[74:77] offset:27648
	s_waitcnt vmcnt(0)
	ds_write_b128 v34, v[144:147] offset:32256
	s_setprio 1
	s_waitcnt lgkmcnt(7)
	v_mfma_f32_32x32x16_bf16 v[2:17], v[50:53], v[78:81], v[2:17]
	ds_read_b128 v[54:57], v1 offset:36896
	global_load_dwordx4 v[62:65], v[40:41], off offset:1920
	global_load_dwordx4 v[66:69], v[44:45], off offset:1920
	global_load_dwordx4 v[70:73], v[42:43], off offset:1920
	global_load_dwordx4 v[74:77], v[46:47], off offset:1920
	global_load_dwordx4 v[140:143], v[38:39], off offset:1920
	global_load_dwordx4 v[144:147], v[48:49], off offset:1920
	ds_read_b128 v[58:61], v1 offset:36960
	ds_read_b128 v[42:45], v1 offset:41568
	s_waitcnt lgkmcnt(9)
	v_mfma_f32_32x32x16_bf16 v[18:33], v[50:53], v[82:85], v[18:33]
	ds_read_b128 v[50:53], v36 offset:9248
	s_waitcnt lgkmcnt(0)
	v_mfma_f32_32x32x16_bf16 v[2:17], v[50:53], v[54:57], v[2:17]
	ds_read_b128 v[54:57], v1 offset:41504
	s_waitcnt lgkmcnt(0)
	v_mfma_f32_32x32x16_bf16 v[18:33], v[50:53], v[54:57], v[18:33]
	ds_read_b128 v[50:53], v36 offset:9280
	ds_read_b128 v[54:57], v1 offset:36928
	s_waitcnt lgkmcnt(0)
	v_mfma_f32_32x32x16_bf16 v[2:17], v[50:53], v[54:57], v[2:17]
	ds_read_b128 v[54:57], v1 offset:41536
	s_waitcnt lgkmcnt(0)
	v_mfma_f32_32x32x16_bf16 v[18:33], v[50:53], v[54:57], v[18:33]
	ds_read_b128 v[50:53], v36 offset:9312
	s_waitcnt lgkmcnt(0)
	v_mfma_f32_32x32x16_bf16 v[2:17], v[50:53], v[58:61], v[2:17]
	v_mfma_f32_32x32x16_bf16 v[18:33], v[50:53], v[42:45], v[18:33]
	s_setprio 0
	s_barrier
	ds_read_b128 v[42:45], v36
	ds_read_b128 v[46:49], v1 offset:18432
	ds_read_b128 v[50:53], v1 offset:23040
	s_waitcnt vmcnt(1)
	ds_write_b128 v34, v[140:143] offset:9216
	ds_write_b128 v34, v[62:65] offset:13824
	ds_write_b128 v34, v[66:69] offset:36864
	ds_write_b128 v34, v[70:73] offset:41472
	ds_write_b128 v34, v[74:77] offset:46080
	s_waitcnt vmcnt(0)
	ds_write_b128 v34, v[144:147] offset:50688
	s_setprio 1
	ds_read_b128 v[38:41], v36 offset:32
	s_waitcnt lgkmcnt(8)
	v_mfma_f32_32x32x16_bf16 v[2:17], v[42:45], v[46:49], v[2:17]
	s_waitcnt lgkmcnt(7)
	v_mfma_f32_32x32x16_bf16 v[18:33], v[42:45], v[50:53], v[18:33]
	ds_read_b128 v[42:45], v1 offset:18464
	s_waitcnt lgkmcnt(0)
	v_mfma_f32_32x32x16_bf16 v[2:17], v[38:41], v[42:45], v[2:17]
	ds_read_b128 v[42:45], v1 offset:23072
	s_waitcnt lgkmcnt(0)
	v_mfma_f32_32x32x16_bf16 v[18:33], v[38:41], v[42:45], v[18:33]
	ds_read_b128 v[38:41], v36 offset:64
	ds_read_b128 v[42:45], v1 offset:18496
	s_waitcnt lgkmcnt(0)
	v_mfma_f32_32x32x16_bf16 v[2:17], v[38:41], v[42:45], v[2:17]
	ds_read_b128 v[42:45], v1 offset:23104
	s_waitcnt lgkmcnt(0)
	v_mfma_f32_32x32x16_bf16 v[18:33], v[38:41], v[42:45], v[18:33]
	ds_read_b128 v[38:41], v36 offset:96
	ds_read_b128 v[42:45], v1 offset:18528
	s_waitcnt lgkmcnt(0)
	v_mfma_f32_32x32x16_bf16 v[2:17], v[38:41], v[42:45], v[2:17]
	ds_read_b128 v[42:45], v1 offset:23136
	s_waitcnt lgkmcnt(0)
	v_mfma_f32_32x32x16_bf16 v[18:33], v[38:41], v[42:45], v[18:33]
	s_setprio 0
	s_barrier
; DI int crow(int i, int h) { return (i & 3) + 8 * (i >> 2) + 4 * h; }
; template <int TM, int TN, class Epi>
; DI void gemm_tile(const u16* A, long lda, const u16* Bt, long ldb, int K, int m0, int n0, char* smem, const Epi& epi) {
;     ...
; #pragma unroll
;   for (int tm = 0; tm < TM; tm++)
; #pragma unroll
;     for (int tn = 0; tn < TN; tn++)
; #pragma unroll
;       for (int i = 0; i < 16; i++)
;         Ct[(wm * 32 * TM + tm * 32 + crow(i, h)) * LDC + wn * 32 * TN + tn * 32 + r] = acc[tm][tn][i];
;   __syncthreads();
;   DI void operator()(const float* Ct, int ldc, int m0, int n0, int tid, int bm) const {
;     ...
;     for (int it = 0; it < bm / 16; it++) {
;       int id = tid + 256 * it; int row = id >> 4, c8 = (id & 15) * 8;
;       int m = m0 + row;
;       const float* c = Ct + row * ldc + c8;
;       float4 a = *(const float4*)c, b = *(const float4*)(c + 4);
;       float x[8];
;       if (srcb != nullptr) {
;         unpack8(*(const uint4*)(srcb + (size_t)m * LDA + n0 + c8), x);
;       } else {
;         const float* sp = (m < NP ? src0 + (size_t)m * 1024 : src1 + (size_t)(m - NP) * 1024) + n0 + c8;
;         float4 sa = *(const float4*)sp, sb = *(const float4*)(sp + 4);
;         x[0] = sa.x; x[1] = sa.y; x[2] = sa.z; x[3] = sa.w; x[4] = sb.x; x[5] = sb.y; x[6] = sb.z; x[7] = sb.w;
;       }
;       x[0] += a.x; x[1] += a.y; x[2] += a.z; x[3] += a.w; x[4] += b.x; x[5] += b.y; x[6] += b.z; x[7] += b.w;
;       if (dstf != nullptr) {
;         float* o = dstf + (size_t)m * 1024 + n0 + c8;
;         *(float4*)o = make_float4(x[0], x[1], x[2], x[3]); *(float4*)(o + 4) = make_float4(x[4], x[5], x[6], x[7]);
;       } else {
;         *(uint4*)(dstb + (size_t)m * LDA + n0 + c8) = pack8(x);
;       }
	ds_read_b128 v[38:41], v36 offset:9216
	ds_read_b128 v[42:45], v1 offset:36864
	ds_read_b128 v[46:49], v1 offset:41472
	s_setprio 1
	s_waitcnt lgkmcnt(1)
	v_mfma_f32_32x32x16_bf16 v[2:17], v[38:41], v[42:45], v[2:17]
	ds_read_b128 v[42:45], v1 offset:36896
	s_waitcnt lgkmcnt(1)
	v_mfma_f32_32x32x16_bf16 v[18:33], v[38:41], v[46:49], v[18:33]
	ds_read_b128 v[38:41], v36 offset:9248
	s_waitcnt lgkmcnt(0)
	v_mfma_f32_32x32x16_bf16 v[2:17], v[38:41], v[42:45], v[2:17]
	ds_read_b128 v[42:45], v1 offset:41504
	s_waitcnt lgkmcnt(0)
	v_mfma_f32_32x32x16_bf16 v[18:33], v[38:41], v[42:45], v[18:33]
	ds_read_b128 v[38:41], v36 offset:9280
	ds_read_b128 v[42:45], v1 offset:36928
	s_waitcnt lgkmcnt(0)
	v_mfma_f32_32x32x16_bf16 v[2:17], v[38:41], v[42:45], v[2:17]
	ds_read_b128 v[42:45], v1 offset:41536
	s_waitcnt lgkmcnt(0)
	v_mfma_f32_32x32x16_bf16 v[18:33], v[38:41], v[42:45], v[18:33]
	ds_read_b128 v[36:39], v36 offset:9312
	ds_read_b128 v[40:43], v1 offset:36960
	s_waitcnt lgkmcnt(0)
	v_mfma_f32_32x32x16_bf16 v[2:17], v[36:39], v[40:43], v[2:17]
	ds_read_b128 v[40:43], v1 offset:41568
	s_waitcnt lgkmcnt(0)
	v_mfma_f32_32x32x16_bf16 v[18:33], v[36:39], v[40:43], v[18:33]
	s_setprio 0
	v_mov_b32_e32 v1, v0
	s_barrier
	s_lshl_b32 s4, s10, 1
	v_lshrrev_b32_e32 v36, 3, v1
	v_lshrrev_b32_e32 v34, 2, v1
	v_and_b32_e32 v36, 4, v36
	v_and_or_b32 v34, v34, s3, v36
	s_movk_i32 s3, 0x210
	v_and_b32_e32 v36, 0x5f, v1
	v_mul_lo_u32 v34, v34, s3
	v_lshl_add_u32 v34, v36, 2, v34
	ds_write2_b32 v34, v2, v18 offset1:32
	v_add_u32_e32 v2, 0x400, v34
	ds_write2_b32 v2, v4, v20 offset0:8 offset1:40
	ds_write2_b32 v2, v5, v21 offset0:140 offset1:172
	v_add_u32_e32 v2, 0x1000, v34
	ds_write2_b32 v2, v6, v22 offset0:32 offset1:64
	ds_write2_b32 v2, v7, v23 offset0:164 offset1:196
	v_add_u32_e32 v2, 0x1400, v34
	ds_write2_b32 v2, v8, v24 offset0:40 offset1:72
	ds_write2_b32 v2, v9, v25 offset0:172 offset1:204
	v_add_u32_e32 v2, 0x2000, v34
	ds_write2_b32 v2, v10, v26 offset0:64 offset1:96
	ds_write2_b32 v2, v11, v27 offset0:196 offset1:228
	v_add_u32_e32 v2, 0x2400, v34
	ds_write2_b32 v2, v12, v28 offset0:72 offset1:104
	ds_write2_b32 v2, v13, v29 offset0:204 offset1:236
	v_add_u32_e32 v2, 0x3000, v34
	ds_write2_b32 v2, v14, v30 offset0:96 offset1:128
	v_add_u32_e32 v2, 0x3200, v34
	ds_write2_b32 v2, v15, v31 offset0:100 offset1:132
	v_add_u32_e32 v2, 0x3400, v34
	ds_write2_b32 v2, v16, v32 offset0:104 offset1:136
	v_add_u32_e32 v2, 0x3600, v34
	ds_write2_b32 v2, v17, v33 offset0:108 offset1:140
	v_lshlrev_b32_e32 v2, 3, v1
	v_ashrrev_i32_e32 v7, 4, v1
	v_and_b32_e32 v6, 0x78, v2
	v_add_u32_e32 v2, s7, v7
	v_mov_b64_e32 v[14:15], s[8:9]
	ds_write2_b32 v34, v3, v19 offset0:132 offset1:164
	v_mad_i64_i32 v[2:3], s[8:9], v2, s6, v[14:15]
	v_lshl_add_u64 v[2:3], v[2:3], 0, s[4:5]
	v_lshlrev_b32_e32 v34, 1, v6
	v_lshl_add_u64 v[16:17], v[2:3], 0, v[34:35]
	s_waitcnt lgkmcnt(0)
	s_barrier
	global_load_dwordx4 v[2:5], v[16:17], off
	v_add_u32_e32 v8, 0x100, v1
	v_ashrrev_i32_e32 v19, 4, v8
	v_lshlrev_b32_e32 v18, 2, v6
	v_add_u32_e32 v6, s7, v19
	v_mad_u64_u32 v[10:11], s[8:9], v7, s3, v[18:19]
	v_mad_i64_i32 v[6:7], s[8:9], v6, s6, v[14:15]
	v_lshl_add_u64 v[6:7], v[6:7], 0, s[4:5]
	v_lshl_add_u64 v[20:21], v[6:7], 0, v[34:35]
	ds_read_b128 v[6:9], v10
	ds_read_b128 v[10:13], v10 offset:16
	s_waitcnt vmcnt(0)
	v_lshlrev_b32_e32 v22, 16, v2
	v_and_b32_e32 v23, 0xffff0000, v2
	v_lshlrev_b32_e32 v2, 16, v3
	v_and_b32_e32 v3, 0xffff0000, v3
	v_lshlrev_b32_e32 v24, 16, v4
	v_and_b32_e32 v25, 0xffff0000, v4
	v_lshlrev_b32_e32 v4, 16, v5
	v_and_b32_e32 v5, 0xffff0000, v5
	s_waitcnt lgkmcnt(1)
	v_pk_add_f32 v[6:7], v[6:7], v[22:23]
	v_pk_add_f32 v[8:9], v[8:9], v[2:3]
	s_waitcnt lgkmcnt(0)
	v_pk_add_f32 v[10:11], v[10:11], v[24:25]
	v_pk_add_f32 v[12:13], v[12:13], v[4:5]
	v_cvt_pk_bf16_f32 v2, v6, v7
	v_cvt_pk_bf16_f32 v3, v8, v9
	v_cvt_pk_bf16_f32 v4, v10, v11
	v_cvt_pk_bf16_f32 v5, v12, v13
	global_store_dwordx4 v[16:17], v[2:5], off
	global_load_dwordx4 v[2:5], v[20:21], off
	v_add_u32_e32 v6, 0x200, v1
	v_ashrrev_i32_e32 v26, 4, v6
	v_add_u32_e32 v6, s7, v26
	v_mad_i64_i32 v[6:7], s[8:9], v6, s6, v[14:15]
	v_mad_u64_u32 v[10:11], s[8:9], v19, s3, v[18:19]
	v_lshl_add_u64 v[6:7], v[6:7], 0, s[4:5]
	v_lshl_add_u64 v[16:17], v[6:7], 0, v[34:35]
	ds_read_b128 v[6:9], v10
	ds_read_b128 v[10:13], v10 offset:16
	v_add_u32_e32 v1, 0x300, v1
	v_ashrrev_i32_e32 v1, 4, v1
	s_waitcnt vmcnt(0)
	v_lshlrev_b32_e32 v22, 16, v2
	v_and_b32_e32 v23, 0xffff0000, v2
	v_lshlrev_b32_e32 v2, 16, v3
	v_and_b32_e32 v3, 0xffff0000, v3
	v_lshlrev_b32_e32 v24, 16, v4
	v_and_b32_e32 v25, 0xffff0000, v4
	v_lshlrev_b32_e32 v4, 16, v5
	v_and_b32_e32 v5, 0xffff0000, v5
	s_waitcnt lgkmcnt(1)
	v_pk_add_f32 v[6:7], v[6:7], v[22:23]
	v_pk_add_f32 v[8:9], v[8:9], v[2:3]
	s_waitcnt lgkmcnt(0)
	v_pk_add_f32 v[10:11], v[10:11], v[24:25]
	v_pk_add_f32 v[12:13], v[12:13], v[4:5]
	v_cvt_pk_bf16_f32 v2, v6, v7
	v_cvt_pk_bf16_f32 v3, v8, v9
	v_cvt_pk_bf16_f32 v4, v10, v11
	v_cvt_pk_bf16_f32 v5, v12, v13
	global_store_dwordx4 v[20:21], v[2:5], off
	global_load_dwordx4 v[2:5], v[16:17], off
	v_add_u32_e32 v6, s7, v1
	v_mad_i64_i32 v[6:7], s[6:7], v6, s6, v[14:15]
	v_mad_u64_u32 v[10:11], s[8:9], v26, s3, v[18:19]
	v_lshl_add_u64 v[6:7], v[6:7], 0, s[4:5]
	v_lshl_add_u64 v[14:15], v[6:7], 0, v[34:35]
	ds_read_b128 v[6:9], v10
	ds_read_b128 v[10:13], v10 offset:16
	s_waitcnt vmcnt(0)
	v_lshlrev_b32_e32 v20, 16, v2
	v_and_b32_e32 v21, 0xffff0000, v2
	v_lshlrev_b32_e32 v2, 16, v3
	v_and_b32_e32 v3, 0xffff0000, v3
	v_lshlrev_b32_e32 v22, 16, v4
	v_and_b32_e32 v23, 0xffff0000, v4
	v_lshlrev_b32_e32 v4, 16, v5
	v_and_b32_e32 v5, 0xffff0000, v5
	s_waitcnt lgkmcnt(1)
	v_pk_add_f32 v[6:7], v[6:7], v[20:21]
	v_pk_add_f32 v[8:9], v[8:9], v[2:3]
	s_waitcnt lgkmcnt(0)
	v_pk_add_f32 v[10:11], v[10:11], v[22:23]
	v_pk_add_f32 v[12:13], v[12:13], v[4:5]
	v_cvt_pk_bf16_f32 v2, v6, v7
	v_cvt_pk_bf16_f32 v3, v8, v9
	v_cvt_pk_bf16_f32 v4, v10, v11
	v_cvt_pk_bf16_f32 v5, v12, v13
	global_store_dwordx4 v[16:17], v[2:5], off
	global_load_dwordx4 v[2:5], v[14:15], off
	v_mad_u64_u32 v[10:11], s[4:5], v1, s3, v[18:19]
	ds_read_b128 v[6:9], v10
	ds_read_b128 v[10:13], v10 offset:16
	s_waitcnt vmcnt(0)
	v_lshlrev_b32_e32 v16, 16, v2
	v_and_b32_e32 v17, 0xffff0000, v2
	v_lshlrev_b32_e32 v2, 16, v3
	v_and_b32_e32 v3, 0xffff0000, v3
	v_lshlrev_b32_e32 v18, 16, v4
	v_and_b32_e32 v19, 0xffff0000, v4
	v_lshlrev_b32_e32 v4, 16, v5
	v_and_b32_e32 v5, 0xffff0000, v5
	s_waitcnt lgkmcnt(1)
	v_pk_add_f32 v[6:7], v[6:7], v[16:17]
	v_pk_add_f32 v[8:9], v[8:9], v[2:3]
	s_waitcnt lgkmcnt(0)
	v_pk_add_f32 v[10:11], v[10:11], v[18:19]
	v_pk_add_f32 v[12:13], v[12:13], v[4:5]
	v_cvt_pk_bf16_f32 v2, v6, v7
	v_cvt_pk_bf16_f32 v3, v8, v9
	v_cvt_pk_bf16_f32 v4, v10, v11
	v_cvt_pk_bf16_f32 v5, v12, v13
	global_store_dwordx4 v[14:15], v[2:5], off
	s_barrier

;   DI void operator()(const float* Ct, int ldc, int m0, int n0, int tid, int bm) const {
;     ...
;     for (int it = 0; it < bm / 16; it++) {
;       int id = tid + 256 * it; int row = id >> 4, c8 = (id & 15) * 8;
;       int m = m0 + row;
;       const float* c = Ct + row * ldc + c8;
;       float4 a = *(const float4*)c, b = *(const float4*)(c + 4);
;       float x[8];
;       if (srcb != nullptr) {
;         unpack8(*(const uint4*)(srcb + (size_t)m * LDA + n0 + c8), x);
;       } else {
;         const float* sp = (m < NP ? src0 + (size_t)m * 1024 : src1 + (size_t)(m - NP) * 1024) + n0 + c8;
;         float4 sa = *(const float4*)sp, sb = *(const float4*)(sp + 4);
;         x[0] = sa.x; x[1] = sa.y; x[2] = sa.z; x[3] = sa.w; x[4] = sb.x; x[5] = sb.y; x[6] = sb.z; x[7] = sb.w;
;       }
;       x[0] += a.x; x[1] += a.y; x[2] += a.z; x[3] += a.w; x[4] += b.x; x[5] += b.y; x[6] += b.z; x[7] += b.w;
;       if (dstf != nullptr) {
;         float* o = dstf + (size_t)m * 1024 + n0 + c8;
;         *(float4*)o = make_float4(x[0], x[1], x[2], x[3]); *(float4*)(o + 4) = make_float4(x[4], x[5], x[6], x[7]);
;       } else {
;         *(uint4*)(dstb + (size_t)m * LDA + n0 + c8) = pack8(x);
;       }
.LBB0_2619:
	v_add_u32_e32 v3, s14, v66
	v_ashrrev_i32_e32 v10, 4, v3
	v_add_u32_e32 v6, s36, v10
	v_mad_i64_i32 v[18:19], s[38:39], v6, s18, v[4:5]
	v_add_u32_e32 v11, 0x100, v3
	v_mad_u64_u32 v[14:15], s[38:39], v10, s30, v[2:3]
	v_ashrrev_i32_e32 v26, 4, v11
	ds_read_b128 v[10:13], v14
	ds_read_b128 v[14:17], v14 offset:16
	v_add_u32_e32 v20, s36, v26
	v_mad_i64_i32 v[20:21], s[38:39], v20, s18, v[4:5]
	s_addk_i32 s14, 0x400
	s_cmpk_lg_i32 s14, 0x800
	s_waitcnt vmcnt(7)
	v_mov_b64_e32 v[6:7], v[150:151]
	v_mov_b64_e32 v[8:9], v[152:153]
	v_lshlrev_b32_e32 v22, 16, v6
	v_and_b32_e32 v23, 0xffff0000, v6
	v_lshlrev_b32_e32 v6, 16, v7
	v_and_b32_e32 v7, 0xffff0000, v7
	v_lshlrev_b32_e32 v24, 16, v8
	v_and_b32_e32 v25, 0xffff0000, v8
	v_lshlrev_b32_e32 v8, 16, v9
	v_and_b32_e32 v9, 0xffff0000, v9
	s_waitcnt lgkmcnt(1)
	v_pk_add_f32 v[10:11], v[10:11], v[22:23]
	v_pk_add_f32 v[12:13], v[12:13], v[6:7]
	s_waitcnt lgkmcnt(0)
	v_pk_add_f32 v[14:15], v[14:15], v[24:25]
	v_pk_add_f32 v[16:17], v[16:17], v[8:9]
	v_cvt_pk_bf16_f32 v6, v10, v11
	v_cvt_pk_bf16_f32 v7, v12, v13
	v_cvt_pk_bf16_f32 v8, v14, v15
	v_cvt_pk_bf16_f32 v9, v16, v17
	global_store_dwordx4 v[18:19], v[6:9], off
	v_add_u32_e32 v10, 0x200, v3
	v_mad_u64_u32 v[14:15], s[38:39], v26, s30, v[2:3]
	v_ashrrev_i32_e32 v27, 4, v10
	ds_read_b128 v[10:13], v14
	ds_read_b128 v[14:17], v14 offset:16
	v_add_u32_e32 v18, s36, v27
	v_mad_i64_i32 v[18:19], s[38:39], v18, s18, v[4:5]
	v_add_u32_e32 v3, 0x300, v3
	v_ashrrev_i32_e32 v3, 4, v3
	s_waitcnt vmcnt(7)
	v_mov_b64_e32 v[6:7], v[154:155]
	v_mov_b64_e32 v[8:9], v[156:157]
	v_lshlrev_b32_e32 v22, 16, v6
	v_and_b32_e32 v23, 0xffff0000, v6
	v_lshlrev_b32_e32 v6, 16, v7
	v_and_b32_e32 v7, 0xffff0000, v7
	v_lshlrev_b32_e32 v24, 16, v8
	v_and_b32_e32 v25, 0xffff0000, v8
	v_lshlrev_b32_e32 v8, 16, v9
	v_and_b32_e32 v9, 0xffff0000, v9
	s_waitcnt lgkmcnt(1)
	v_pk_add_f32 v[10:11], v[10:11], v[22:23]
	v_pk_add_f32 v[12:13], v[12:13], v[6:7]
	s_waitcnt lgkmcnt(0)
	v_pk_add_f32 v[14:15], v[14:15], v[24:25]
	v_pk_add_f32 v[16:17], v[16:17], v[8:9]
	v_cvt_pk_bf16_f32 v6, v10, v11
	v_cvt_pk_bf16_f32 v7, v12, v13
	v_cvt_pk_bf16_f32 v8, v14, v15
	v_cvt_pk_bf16_f32 v9, v16, v17
	global_store_dwordx4 v[20:21], v[6:9], off
	v_mad_u64_u32 v[14:15], s[38:39], v27, s30, v[2:3]
	ds_read_b128 v[10:13], v14
	ds_read_b128 v[14:17], v14 offset:16
	v_add_u32_e32 v20, s36, v3
	v_mad_i64_i32 v[20:21], s[38:39], v20, s18, v[4:5]
	s_waitcnt vmcnt(7)
	v_mov_b64_e32 v[6:7], v[158:159]
	v_mov_b64_e32 v[8:9], v[160:161]
	v_lshlrev_b32_e32 v22, 16, v6
	v_and_b32_e32 v23, 0xffff0000, v6
	v_lshlrev_b32_e32 v6, 16, v7
	v_and_b32_e32 v7, 0xffff0000, v7
	v_lshlrev_b32_e32 v24, 16, v8
	v_and_b32_e32 v25, 0xffff0000, v8
	v_lshlrev_b32_e32 v8, 16, v9
	v_and_b32_e32 v9, 0xffff0000, v9
	s_waitcnt lgkmcnt(1)
	v_pk_add_f32 v[10:11], v[10:11], v[22:23]
	v_pk_add_f32 v[12:13], v[12:13], v[6:7]
	s_waitcnt lgkmcnt(0)
	v_pk_add_f32 v[14:15], v[14:15], v[24:25]
	v_pk_add_f32 v[16:17], v[16:17], v[8:9]
	v_cvt_pk_bf16_f32 v6, v10, v11
	v_cvt_pk_bf16_f32 v7, v12, v13
	v_cvt_pk_bf16_f32 v8, v14, v15
	v_cvt_pk_bf16_f32 v9, v16, v17
	global_store_dwordx4 v[18:19], v[6:9], off
	v_mad_u64_u32 v[14:15], s[38:39], v3, s30, v[2:3]
	ds_read_b128 v[10:13], v14
	ds_read_b128 v[14:17], v14 offset:16
	s_waitcnt vmcnt(7)
	v_mov_b64_e32 v[6:7], v[162:163]
	v_mov_b64_e32 v[8:9], v[164:165]
	v_lshlrev_b32_e32 v18, 16, v6
	v_and_b32_e32 v19, 0xffff0000, v6
	v_lshlrev_b32_e32 v6, 16, v7
	v_and_b32_e32 v7, 0xffff0000, v7
	v_lshlrev_b32_e32 v22, 16, v8
	v_and_b32_e32 v23, 0xffff0000, v8
	v_lshlrev_b32_e32 v8, 16, v9
	v_and_b32_e32 v9, 0xffff0000, v9
	s_waitcnt lgkmcnt(1)
	v_pk_add_f32 v[10:11], v[10:11], v[18:19]
	v_pk_add_f32 v[12:13], v[12:13], v[6:7]
	s_waitcnt lgkmcnt(0)
	v_pk_add_f32 v[14:15], v[14:15], v[22:23]
	v_pk_add_f32 v[16:17], v[16:17], v[8:9]
	v_cvt_pk_bf16_f32 v6, v10, v11
	v_cvt_pk_bf16_f32 v7, v12, v13
	v_cvt_pk_bf16_f32 v8, v14, v15
	v_cvt_pk_bf16_f32 v9, v16, v17
	global_store_dwordx4 v[20:21], v[6:9], off
	v_add_u32_e32 v3, s14, v66
	v_ashrrev_i32_e32 v10, 4, v3
	v_add_u32_e32 v6, s36, v10
	v_mad_i64_i32 v[18:19], s[38:39], v6, s18, v[4:5]
	v_add_u32_e32 v11, 0x100, v3
	v_mad_u64_u32 v[14:15], s[38:39], v10, s30, v[2:3]
	v_ashrrev_i32_e32 v26, 4, v11
	ds_read_b128 v[10:13], v14
	ds_read_b128 v[14:17], v14 offset:16
	v_add_u32_e32 v20, s36, v26
	v_mad_i64_i32 v[20:21], s[38:39], v20, s18, v[4:5]
	s_addk_i32 s14, 0x400
	s_cmpk_lg_i32 s14, 0x800
	s_waitcnt vmcnt(7)
	v_mov_b64_e32 v[6:7], v[166:167]
	v_mov_b64_e32 v[8:9], v[168:169]
	v_lshlrev_b32_e32 v22, 16, v6
	v_and_b32_e32 v23, 0xffff0000, v6
	v_lshlrev_b32_e32 v6, 16, v7
	v_and_b32_e32 v7, 0xffff0000, v7
	v_lshlrev_b32_e32 v24, 16, v8
	v_and_b32_e32 v25, 0xffff0000, v8
	v_lshlrev_b32_e32 v8, 16, v9
	v_and_b32_e32 v9, 0xffff0000, v9
	s_waitcnt lgkmcnt(1)
	v_pk_add_f32 v[10:11], v[10:11], v[22:23]
	v_pk_add_f32 v[12:13], v[12:13], v[6:7]
	s_waitcnt lgkmcnt(0)
	v_pk_add_f32 v[14:15], v[14:15], v[24:25]
	v_pk_add_f32 v[16:17], v[16:17], v[8:9]
	v_cvt_pk_bf16_f32 v6, v10, v11
	v_cvt_pk_bf16_f32 v7, v12, v13
	v_cvt_pk_bf16_f32 v8, v14, v15
	v_cvt_pk_bf16_f32 v9, v16, v17
	global_store_dwordx4 v[18:19], v[6:9], off
	v_add_u32_e32 v10, 0x200, v3
	v_mad_u64_u32 v[14:15], s[38:39], v26, s30, v[2:3]
	v_ashrrev_i32_e32 v27, 4, v10
	ds_read_b128 v[10:13], v14
	ds_read_b128 v[14:17], v14 offset:16
	v_add_u32_e32 v18, s36, v27
	v_mad_i64_i32 v[18:19], s[38:39], v18, s18, v[4:5]
	v_add_u32_e32 v3, 0x300, v3
	v_ashrrev_i32_e32 v3, 4, v3
	s_waitcnt vmcnt(7)
; template <int TM, int TN>
; DI void gemm_mainloop(const u16* __restrict__ A, long lda, const u16* __restrict__ Bt, long ldb, int K, char* smem,
;                       f32x16 (&acc)[TM][TN]) {
;     ...
;   const int lrow = tid >> 3, lch = (tid & 7) * 8;
;   const u16* gA = A + (long)lrow * lda + lch;
;   const u16* gB = Bt + (long)lrow * ldb + lch;
;   const int soff = lrow * LD + lch;
;     ...
;   GEMM_GLOAD(0)
;   __syncthreads();
;   GEMM_SSTORE(0)
;   if (nk > 1) GEMM_GLOAD(64)
;   __syncthreads();
;   DI void operator()(const float* Ct, int ldc, int m0, int n0, int tid, int bm) const {
;     ...
;     for (int it = 0; it < bm / 16; it++) {
;       int id = tid + 256 * it; int row = id >> 4, c8 = (id & 15) * 8;
;       int m = m0 + row;
;       const float* c = Ct + row * ldc + c8;
;       float4 a = *(const float4*)c, b = *(const float4*)(c + 4);
;       float x[8];
;       if (srcb != nullptr) {
;         unpack8(*(const uint4*)(srcb + (size_t)m * LDA + n0 + c8), x);
;       } else {
;         const float* sp = (m < NP ? src0 + (size_t)m * 1024 : src1 + (size_t)(m - NP) * 1024) + n0 + c8;
;         float4 sa = *(const float4*)sp, sb = *(const float4*)(sp + 4);
;         x[0] = sa.x; x[1] = sa.y; x[2] = sa.z; x[3] = sa.w; x[4] = sb.x; x[5] = sb.y; x[6] = sb.z; x[7] = sb.w;
;       }
;       x[0] += a.x; x[1] += a.y; x[2] += a.z; x[3] += a.w; x[4] += b.x; x[5] += b.y; x[6] += b.z; x[7] += b.w;
;       if (dstf != nullptr) {
;         float* o = dstf + (size_t)m * 1024 + n0 + c8;
;         *(float4*)o = make_float4(x[0], x[1], x[2], x[3]); *(float4*)(o + 4) = make_float4(x[4], x[5], x[6], x[7]);
;       } else {
;         *(uint4*)(dstb + (size_t)m * LDA + n0 + c8) = pack8(x);
;       }
	v_mov_b64_e32 v[6:7], v[170:171]
	v_mov_b64_e32 v[8:9], v[172:173]
	v_lshlrev_b32_e32 v22, 16, v6
	v_and_b32_e32 v23, 0xffff0000, v6
	v_lshlrev_b32_e32 v6, 16, v7
	v_and_b32_e32 v7, 0xffff0000, v7
	v_lshlrev_b32_e32 v24, 16, v8
	v_and_b32_e32 v25, 0xffff0000, v8
	v_lshlrev_b32_e32 v8, 16, v9
	v_and_b32_e32 v9, 0xffff0000, v9
	s_waitcnt lgkmcnt(1)
	v_pk_add_f32 v[10:11], v[10:11], v[22:23]
	v_pk_add_f32 v[12:13], v[12:13], v[6:7]
	s_waitcnt lgkmcnt(0)
	v_pk_add_f32 v[14:15], v[14:15], v[24:25]
	v_pk_add_f32 v[16:17], v[16:17], v[8:9]
	v_cvt_pk_bf16_f32 v6, v10, v11
	v_cvt_pk_bf16_f32 v7, v12, v13
	v_cvt_pk_bf16_f32 v8, v14, v15
	v_cvt_pk_bf16_f32 v9, v16, v17
	global_store_dwordx4 v[20:21], v[6:9], off
	v_mad_u64_u32 v[14:15], s[38:39], v27, s30, v[2:3]
	ds_read_b128 v[10:13], v14
	ds_read_b128 v[14:17], v14 offset:16
	v_add_u32_e32 v20, s36, v3
	v_mad_i64_i32 v[20:21], s[38:39], v20, s18, v[4:5]
	s_waitcnt vmcnt(7)
	v_mov_b64_e32 v[6:7], v[174:175]
	v_mov_b64_e32 v[8:9], v[176:177]
	v_lshlrev_b32_e32 v22, 16, v6
	v_and_b32_e32 v23, 0xffff0000, v6
	v_lshlrev_b32_e32 v6, 16, v7
	v_and_b32_e32 v7, 0xffff0000, v7
	v_lshlrev_b32_e32 v24, 16, v8
	v_and_b32_e32 v25, 0xffff0000, v8
	v_lshlrev_b32_e32 v8, 16, v9
	v_and_b32_e32 v9, 0xffff0000, v9
	s_waitcnt lgkmcnt(1)
	v_pk_add_f32 v[10:11], v[10:11], v[22:23]
	v_pk_add_f32 v[12:13], v[12:13], v[6:7]
	s_waitcnt lgkmcnt(0)
	v_pk_add_f32 v[14:15], v[14:15], v[24:25]
	v_pk_add_f32 v[16:17], v[16:17], v[8:9]
	v_cvt_pk_bf16_f32 v6, v10, v11
	v_cvt_pk_bf16_f32 v7, v12, v13
	v_cvt_pk_bf16_f32 v8, v14, v15
	v_cvt_pk_bf16_f32 v9, v16, v17
	global_store_dwordx4 v[18:19], v[6:9], off
	v_mad_u64_u32 v[14:15], s[38:39], v3, s30, v[2:3]
	ds_read_b128 v[10:13], v14
	ds_read_b128 v[14:17], v14 offset:16
	s_waitcnt vmcnt(7)
	v_mov_b64_e32 v[6:7], v[178:179]
	v_mov_b64_e32 v[8:9], v[180:181]
	v_lshlrev_b32_e32 v18, 16, v6
	v_and_b32_e32 v19, 0xffff0000, v6
	v_lshlrev_b32_e32 v6, 16, v7
	v_and_b32_e32 v7, 0xffff0000, v7
	v_lshlrev_b32_e32 v22, 16, v8
	v_and_b32_e32 v23, 0xffff0000, v8
	v_lshlrev_b32_e32 v8, 16, v9
	v_and_b32_e32 v9, 0xffff0000, v9
	s_waitcnt lgkmcnt(1)
	v_pk_add_f32 v[10:11], v[10:11], v[18:19]
	v_pk_add_f32 v[12:13], v[12:13], v[6:7]
	s_waitcnt lgkmcnt(0)
	v_pk_add_f32 v[14:15], v[14:15], v[22:23]
	v_pk_add_f32 v[16:17], v[16:17], v[8:9]
	v_cvt_pk_bf16_f32 v6, v10, v11
	v_cvt_pk_bf16_f32 v7, v12, v13
	v_cvt_pk_bf16_f32 v8, v14, v15
	v_cvt_pk_bf16_f32 v9, v16, v17
	global_store_dwordx4 v[20:21], v[6:9], off
	s_add_i32 s14, s31, 8
	s_addk_i32 s19, 0x2000
	s_cmp_lt_u32 s31, 24
	s_mov_b32 s31, s14
	s_barrier
	s_cbranch_scc1 .LBB0_2616
	s_lshl_b32 s6, s79, 6
	s_add_i32 s6, s80, s6
	s_cmpk_gt_i32 s6, 0xff
	s_cbranch_scc1 .LBB0_2623
	s_lshl_b32 s6, s6, 3
	s_lshl_b32 s10, s80, 6
	s_and_b32 s6, s6, 0xffffff80
	s_and_b32 s7, s10, 64
	s_or_b32 s7, s6, s7
	s_add_i32 s7, s7, 0x8000
	s_and_b32 s10, s10, 0x380
	s_mul_i32 s14, s7, 0x880
	s_mul_hi_i32 s11, s7, 0x880
	s_add_u32 s4, s4, s14
	v_mov_b32_e32 v1, v0
	s_addc_u32 s5, s5, s11
	s_mul_i32 s11, s10, 0x880
	s_movk_i32 s6, 0x880
	v_lshlrev_b32_e32 v2, 3, v1
	s_add_u32 s14, s3, s11
	v_ashrrev_i32_e32 v36, 3, v1
	v_and_b32_e32 v37, 56, v2
	v_mov_b64_e32 v[2:3], s[4:5]
	s_addc_u32 s15, s16, 0
	v_mad_i64_i32 v[2:3], s[4:5], v36, s6, v[2:3]
	v_lshlrev_b32_e32 v34, 1, v37
	v_mov_b32_e32 v35, 0
	v_lshl_add_u64 v[40:41], v[2:3], 0, v[34:35]
	v_mov_b64_e32 v[2:3], s[14:15]
	s_mov_b32 s3, 0x11000
	v_mad_i64_i32 v[10:11], s[4:5], v36, s6, v[2:3]
	v_add_co_u32_e32 v38, vcc, s3, v40
	v_lshl_add_u64 v[42:43], v[10:11], 0, v[34:35]
	s_nop 0
	v_addc_co_u32_e32 v39, vcc, 0, v41, vcc
	v_add_co_u32_e32 v44, vcc, s3, v42
	s_mov_b32 s3, 0x22000
	s_nop 0
	v_addc_co_u32_e32 v45, vcc, 0, v43, vcc
	v_add_co_u32_e32 v46, vcc, s3, v42
	s_mov_b32 s3, 0x33000
	s_nop 0
	v_addc_co_u32_e32 v47, vcc, 0, v43, vcc
	v_add_co_u32_e32 v48, vcc, s3, v42
	global_load_dwordx4 v[2:5], v[40:41], off
	s_nop 0
	v_addc_co_u32_e32 v49, vcc, 0, v43, vcc
	global_load_dwordx4 v[6:9], v[38:39], off
	global_load_dwordx4 v[10:13], v[42:43], off
	global_load_dwordx4 v[14:17], v[44:45], off
	global_load_dwordx4 v[18:21], v[46:47], off
	global_load_dwordx4 v[22:25], v[48:49], off
	s_barrier
	global_load_dwordx4 v[26:29], v[40:41], off offset:128
	global_load_dwordx4 v[30:33], v[38:39], off offset:128
	global_load_dwordx4 v[50:53], v[42:43], off offset:128
	global_load_dwordx4 v[54:57], v[44:45], off offset:128
	global_load_dwordx4 v[58:61], v[46:47], off offset:128
	global_load_dwordx4 v[62:65], v[48:49], off offset:128
	s_movk_i32 s4, 0x48
	s_mov_b32 s3, 0xfffffe0
	v_and_b32_e32 v34, 31, v1
	v_lshrrev_b32_e32 v66, 2, v1
	v_lshrrev_b32_e32 v67, 1, v1
	s_movk_i32 s11, 0x90
	v_and_b32_e32 v1, 0x5f, v1
	v_mul_lo_u32 v36, v36, s4
	v_and_or_b32 v68, v66, s3, v34
	v_and_b32_e32 v66, 16, v67
	v_add_lshl_u32 v34, v36, v37, 1
	v_mad_u64_u32 v[36:37], s[14:15], v68, s11, v[66:67]
	v_mad_u32_u24 v1, v1, s11, v66
	s_mov_b32 s5, 0
	s_waitcnt vmcnt(11)
	ds_write_b128 v34, v[2:5]
	s_waitcnt vmcnt(10)
	ds_write_b128 v34, v[6:9] offset:4608
	s_waitcnt vmcnt(9)
	ds_write_b128 v34, v[10:13] offset:18432
	s_waitcnt vmcnt(8)
	ds_write_b128 v34, v[14:17] offset:23040
	s_waitcnt vmcnt(7)
	ds_write_b128 v34, v[18:21] offset:27648
	s_waitcnt vmcnt(6)
	ds_write_b128 v34, v[22:25] offset:32256
	s_waitcnt lgkmcnt(0)
	s_barrier
; #define MFMA(a, b, c) __builtin_amdgcn_mfma_f32_32x32x16_bf16((a), (b), (c), 0, 0, 0)
; template <int TM, int TN>
; DI void gemm_mainloop(const u16* __restrict__ A, long lda, const u16* __restrict__ Bt, long ldb, int K, char* smem,
;                       f32x16 (&acc)[TM][TN]) {
;     ...
;   for (int kt = 0; kt < nk; kt++) {
;     const int buf = kt & 1;
;     const u16* cA = sA + buf * BM * LD + (wm * 32 * TM + r) * LD + h * 8;
;     const u16* cB = sB + buf * BN * LD + (wn * 32 * TN + r) * LD + h * 8;
;     bf16x8 af[TM], bfr[TN];
; #pragma unroll
;     for (int tm = 0; tm < TM; tm++) af[tm] = *(const bf16x8*)(cA + tm * 32 * LD);
; #pragma unroll
;     for (int tn = 0; tn < TN; tn++) bfr[tn] = *(const bf16x8*)(cB + tn * 32 * LD);
;     if (kt + 1 < nk) GEMM_SSTORE(buf ^ 1)
;     __builtin_amdgcn_sched_barrier(0);
;     __builtin_amdgcn_s_setprio(1);
; #pragma unroll
;     for (int tm = 0; tm < TM; tm++)
; #pragma unroll
;       for (int tn = 0; tn < TN; tn++) acc[tm][tn] = MFMA(af[tm], bfr[tn], acc[tm][tn]);
; #pragma unroll
;     for (int tm = 0; tm < TM; tm++) af[tm] = *(const bf16x8*)(cA + tm * 32 * LD + 16);
; #pragma unroll
;     for (int tn = 0; tn < TN; tn++) bfr[tn] = *(const bf16x8*)(cB + tn * 32 * LD + 16);
; #pragma unroll
;     for (int tm = 0; tm < TM; tm++)
; #pragma unroll
;       for (int tn = 0; tn < TN; tn++) acc[tm][tn] = MFMA(af[tm], bfr[tn], acc[tm][tn]);
;     __builtin_amdgcn_sched_group_barrier(0x8, 4, 0);
;     if (kt + 2 < nk) GEMM_GLOAD((kt + 2) * 64)
; #pragma unroll
;     for (int ks = 2; ks < 4; ks++) {
; #pragma unroll
;       for (int tm = 0; tm < TM; tm++) af[tm] = *(const bf16x8*)(cA + tm * 32 * LD + ks * 16);
; #pragma unroll
;       for (int tn = 0; tn < TN; tn++) bfr[tn] = *(const bf16x8*)(cB + tn * 32 * LD + ks * 16);
; #pragma unroll
;       for (int tm = 0; tm < TM; tm++)
; #pragma unroll
;         for (int tn = 0; tn < TN; tn++) acc[tm][tn] = MFMA(af[tm], bfr[tn], acc[tm][tn]);
;     }
;     __builtin_amdgcn_s_setprio(0);
;     __syncthreads();
;   }
	ds_read_b128 v[18:21], v36
	ds_read_b128 v[2:5], v1 offset:18432
	ds_read_b128 v[22:25], v1 offset:23040
	s_waitcnt vmcnt(5)
	ds_write_b128 v34, v[26:29] offset:9216
	s_waitcnt vmcnt(4)
	ds_write_b128 v34, v[30:33] offset:13824
	s_waitcnt vmcnt(3)
	ds_write_b128 v34, v[50:53] offset:36864
	s_waitcnt vmcnt(2)
	ds_write_b128 v34, v[54:57] offset:41472
	s_waitcnt vmcnt(1)
	ds_write_b128 v34, v[58:61] offset:46080
	s_waitcnt vmcnt(0)
	ds_write_b128 v34, v[62:65] offset:50688
	s_setprio 1
	ds_read_b128 v[50:53], v36 offset:32
	s_waitcnt lgkmcnt(8)
	v_mfma_f32_32x32x16_bf16 v[2:17], v[18:21], v[2:5], 0
	ds_read_b128 v[54:57], v1 offset:18464
	ds_read_b128 v[58:61], v1 offset:18528
	global_load_dwordx4 v[62:65], v[38:39], off offset:256
	global_load_dwordx4 v[66:69], v[42:43], off offset:256
	global_load_dwordx4 v[70:73], v[44:45], off offset:256
	global_load_dwordx4 v[74:77], v[46:47], off offset:256
	global_load_dwordx4 v[140:143], v[40:41], off offset:256
	global_load_dwordx4 v[144:147], v[48:49], off offset:256
	ds_read_b128 v[78:81], v1 offset:23136
	s_waitcnt lgkmcnt(10)
	v_mfma_f32_32x32x16_bf16 v[18:33], v[18:21], v[22:25], 0
	s_waitcnt lgkmcnt(2)
	v_mfma_f32_32x32x16_bf16 v[2:17], v[50:53], v[54:57], v[2:17]
	ds_read_b128 v[54:57], v1 offset:23072
	s_waitcnt lgkmcnt(0)
	v_mfma_f32_32x32x16_bf16 v[18:33], v[50:53], v[54:57], v[18:33]
	ds_read_b128 v[50:53], v36 offset:64
	ds_read_b128 v[54:57], v1 offset:18496
	s_waitcnt lgkmcnt(0)
	v_mfma_f32_32x32x16_bf16 v[2:17], v[50:53], v[54:57], v[2:17]
	ds_read_b128 v[54:57], v1 offset:23104
	s_waitcnt lgkmcnt(0)
	v_mfma_f32_32x32x16_bf16 v[18:33], v[50:53], v[54:57], v[18:33]
	ds_read_b128 v[50:53], v36 offset:96
	s_waitcnt lgkmcnt(0)
	v_mfma_f32_32x32x16_bf16 v[2:17], v[50:53], v[58:61], v[2:17]
	v_mfma_f32_32x32x16_bf16 v[18:33], v[50:53], v[78:81], v[18:33]
	s_setprio 0
	s_barrier
	ds_read_b128 v[50:53], v36 offset:9216
	ds_read_b128 v[78:81], v1 offset:36864
	ds_read_b128 v[82:85], v1 offset:41472
	s_waitcnt vmcnt(1)
	ds_write_b128 v34, v[140:143]
	ds_write_b128 v34, v[62:65] offset:4608
	ds_write_b128 v34, v[66:69] offset:18432
	ds_write_b128 v34, v[70:73] offset:23040
	ds_write_b128 v34, v[74:77] offset:27648
	s_waitcnt vmcnt(0)
	ds_write_b128 v34, v[144:147] offset:32256
	s_setprio 1
	s_waitcnt lgkmcnt(7)
	v_mfma_f32_32x32x16_bf16 v[2:17], v[50:53], v[78:81], v[2:17]
	ds_read_b128 v[54:57], v1 offset:36896
	ds_read_b128 v[58:61], v1 offset:36960
	global_load_dwordx4 v[62:65], v[38:39], off offset:384
	global_load_dwordx4 v[66:69], v[42:43], off offset:384
	global_load_dwordx4 v[70:73], v[44:45], off offset:384
	global_load_dwordx4 v[74:77], v[46:47], off offset:384
	global_load_dwordx4 v[140:143], v[40:41], off offset:384
	global_load_dwordx4 v[144:147], v[48:49], off offset:384
	ds_read_b128 v[78:81], v1 offset:41568
	s_waitcnt lgkmcnt(9)
	v_mfma_f32_32x32x16_bf16 v[18:33], v[50:53], v[82:85], v[18:33]
	ds_read_b128 v[50:53], v36 offset:9248
	s_waitcnt lgkmcnt(0)
	v_mfma_f32_32x32x16_bf16 v[2:17], v[50:53], v[54:57], v[2:17]
	ds_read_b128 v[54:57], v1 offset:41504
	s_waitcnt lgkmcnt(0)
	v_mfma_f32_32x32x16_bf16 v[18:33], v[50:53], v[54:57], v[18:33]
	ds_read_b128 v[50:53], v36 offset:9280
	ds_read_b128 v[54:57], v1 offset:36928
	s_waitcnt lgkmcnt(0)
	v_mfma_f32_32x32x16_bf16 v[2:17], v[50:53], v[54:57], v[2:17]
	ds_read_b128 v[54:57], v1 offset:41536
	s_waitcnt lgkmcnt(0)
	v_mfma_f32_32x32x16_bf16 v[18:33], v[50:53], v[54:57], v[18:33]
	ds_read_b128 v[50:53], v36 offset:9312
	s_waitcnt lgkmcnt(0)
	v_mfma_f32_32x32x16_bf16 v[2:17], v[50:53], v[58:61], v[2:17]
	v_mfma_f32_32x32x16_bf16 v[18:33], v[50:53], v[78:81], v[18:33]
	s_setprio 0
	s_barrier
	ds_read_b128 v[50:53], v36
	ds_read_b128 v[78:81], v1 offset:18432
	ds_read_b128 v[82:85], v1 offset:23040
	s_waitcnt vmcnt(1)
	ds_write_b128 v34, v[140:143] offset:9216
	ds_write_b128 v34, v[62:65] offset:13824
	ds_write_b128 v34, v[66:69] offset:36864
	ds_write_b128 v34, v[70:73] offset:41472
	ds_write_b128 v34, v[74:77] offset:46080
	s_waitcnt vmcnt(0)
	ds_write_b128 v34, v[144:147] offset:50688
	s_setprio 1
	s_waitcnt lgkmcnt(7)
	v_mfma_f32_32x32x16_bf16 v[2:17], v[50:53], v[78:81], v[2:17]
	ds_read_b128 v[54:57], v1 offset:18464
	ds_read_b128 v[58:61], v1 offset:18528
	global_load_dwordx4 v[62:65], v[38:39], off offset:512
	global_load_dwordx4 v[66:69], v[42:43], off offset:512
	global_load_dwordx4 v[70:73], v[44:45], off offset:512
	global_load_dwordx4 v[74:77], v[46:47], off offset:512
	global_load_dwordx4 v[140:143], v[40:41], off offset:512
	global_load_dwordx4 v[144:147], v[48:49], off offset:512
	ds_read_b128 v[78:81], v1 offset:23136
	s_waitcnt lgkmcnt(9)
	v_mfma_f32_32x32x16_bf16 v[18:33], v[50:53], v[82:85], v[18:33]
	ds_read_b128 v[50:53], v36 offset:32
	s_waitcnt lgkmcnt(0)
	v_mfma_f32_32x32x16_bf16 v[2:17], v[50:53], v[54:57], v[2:17]
	ds_read_b128 v[54:57], v1 offset:23072
	s_waitcnt lgkmcnt(0)
	v_mfma_f32_32x32x16_bf16 v[18:33], v[50:53], v[54:57], v[18:33]
	ds_read_b128 v[50:53], v36 offset:64
	ds_read_b128 v[54:57], v1 offset:18496
	s_waitcnt lgkmcnt(0)
	v_mfma_f32_32x32x16_bf16 v[2:17], v[50:53], v[54:57], v[2:17]
	ds_read_b128 v[54:57], v1 offset:23104
	s_waitcnt lgkmcnt(0)
	v_mfma_f32_32x32x16_bf16 v[18:33], v[50:53], v[54:57], v[18:33]
	ds_read_b128 v[50:53], v36 offset:96
	s_waitcnt lgkmcnt(0)
	v_mfma_f32_32x32x16_bf16 v[2:17], v[50:53], v[58:61], v[2:17]
	v_mfma_f32_32x32x16_bf16 v[18:33], v[50:53], v[78:81], v[18:33]
	s_setprio 0
	s_barrier
; #define MFMA(a, b, c) __builtin_amdgcn_mfma_f32_32x32x16_bf16((a), (b), (c), 0, 0, 0)
; template <int TM, int TN>
; DI void gemm_mainloop(const u16* __restrict__ A, long lda, const u16* __restrict__ Bt, long ldb, int K, char* smem,
;                       f32x16 (&acc)[TM][TN]) {
;     ...
;   for (int kt = 0; kt < nk; kt++) {
;     const int buf = kt & 1;
;     const u16* cA = sA + buf * BM * LD + (wm * 32 * TM + r) * LD + h * 8;
;     const u16* cB = sB + buf * BN * LD + (wn * 32 * TN + r) * LD + h * 8;
;     bf16x8 af[TM], bfr[TN];
; #pragma unroll
;     for (int tm = 0; tm < TM; tm++) af[tm] = *(const bf16x8*)(cA + tm * 32 * LD);
; #pragma unroll
;     for (int tn = 0; tn < TN; tn++) bfr[tn] = *(const bf16x8*)(cB + tn * 32 * LD);
;     if (kt + 1 < nk) GEMM_SSTORE(buf ^ 1)
;     __builtin_amdgcn_sched_barrier(0);
;     __builtin_amdgcn_s_setprio(1);
; #pragma unroll
;     for (int tm = 0; tm < TM; tm++)
; #pragma unroll
;       for (int tn = 0; tn < TN; tn++) acc[tm][tn] = MFMA(af[tm], bfr[tn], acc[tm][tn]);
; #pragma unroll
;     for (int tm = 0; tm < TM; tm++) af[tm] = *(const bf16x8*)(cA + tm * 32 * LD + 16);
; #pragma unroll
;     for (int tn = 0; tn < TN; tn++) bfr[tn] = *(const bf16x8*)(cB + tn * 32 * LD + 16);
; #pragma unroll
;     for (int tm = 0; tm < TM; tm++)
; #pragma unroll
;       for (int tn = 0; tn < TN; tn++) acc[tm][tn] = MFMA(af[tm], bfr[tn], acc[tm][tn]);
;     __builtin_amdgcn_sched_group_barrier(0x8, 4, 0);
;     if (kt + 2 < nk) GEMM_GLOAD((kt + 2) * 64)
; #pragma unroll
;     for (int ks = 2; ks < 4; ks++) {
; #pragma unroll
;       for (int tm = 0; tm < TM; tm++) af[tm] = *(const bf16x8*)(cA + tm * 32 * LD + ks * 16);
; #pragma unroll
;       for (int tn = 0; tn < TN; tn++) bfr[tn] = *(const bf16x8*)(cB + tn * 32 * LD + ks * 16);
; #pragma unroll
;       for (int tm = 0; tm < TM; tm++)
; #pragma unroll
;         for (int tn = 0; tn < TN; tn++) acc[tm][tn] = MFMA(af[tm], bfr[tn], acc[tm][tn]);
;     }
;     __builtin_amdgcn_s_setprio(0);
;     __syncthreads();
;   }
	ds_read_b128 v[50:53], v36 offset:9216
	ds_read_b128 v[78:81], v1 offset:36864
	ds_read_b128 v[82:85], v1 offset:41472
	s_waitcnt vmcnt(1)
	ds_write_b128 v34, v[140:143]
	ds_write_b128 v34, v[62:65] offset:4608
	ds_write_b128 v34, v[66:69] offset:18432
	ds_write_b128 v34, v[70:73] offset:23040
	ds_write_b128 v34, v[74:77] offset:27648
	s_waitcnt vmcnt(0)
	ds_write_b128 v34, v[144:147] offset:32256
	s_setprio 1
	s_waitcnt lgkmcnt(7)
	v_mfma_f32_32x32x16_bf16 v[2:17], v[50:53], v[78:81], v[2:17]
	ds_read_b128 v[54:57], v1 offset:36896
	ds_read_b128 v[58:61], v1 offset:36960
	global_load_dwordx4 v[62:65], v[38:39], off offset:640
	global_load_dwordx4 v[66:69], v[42:43], off offset:640
	global_load_dwordx4 v[70:73], v[44:45], off offset:640
	global_load_dwordx4 v[74:77], v[46:47], off offset:640
	global_load_dwordx4 v[140:143], v[40:41], off offset:640
	global_load_dwordx4 v[144:147], v[48:49], off offset:640
	ds_read_b128 v[78:81], v1 offset:41568
	s_waitcnt lgkmcnt(9)
	v_mfma_f32_32x32x16_bf16 v[18:33], v[50:53], v[82:85], v[18:33]
	ds_read_b128 v[50:53], v36 offset:9248
	s_waitcnt lgkmcnt(0)
	v_mfma_f32_32x32x16_bf16 v[2:17], v[50:53], v[54:57], v[2:17]
	ds_read_b128 v[54:57], v1 offset:41504
	s_waitcnt lgkmcnt(0)
	v_mfma_f32_32x32x16_bf16 v[18:33], v[50:53], v[54:57], v[18:33]
	ds_read_b128 v[50:53], v36 offset:9280
	ds_read_b128 v[54:57], v1 offset:36928
	s_waitcnt lgkmcnt(0)
	v_mfma_f32_32x32x16_bf16 v[2:17], v[50:53], v[54:57], v[2:17]
	ds_read_b128 v[54:57], v1 offset:41536
	s_waitcnt lgkmcnt(0)
	v_mfma_f32_32x32x16_bf16 v[18:33], v[50:53], v[54:57], v[18:33]
	ds_read_b128 v[50:53], v36 offset:9312
	s_waitcnt lgkmcnt(0)
	v_mfma_f32_32x32x16_bf16 v[2:17], v[50:53], v[58:61], v[2:17]
	v_mfma_f32_32x32x16_bf16 v[18:33], v[50:53], v[78:81], v[18:33]
	s_setprio 0
	s_barrier
	ds_read_b128 v[50:53], v36
	ds_read_b128 v[78:81], v1 offset:18432
	ds_read_b128 v[82:85], v1 offset:23040
	s_waitcnt vmcnt(1)
	ds_write_b128 v34, v[140:143] offset:9216
	ds_write_b128 v34, v[62:65] offset:13824
	ds_write_b128 v34, v[66:69] offset:36864
	ds_write_b128 v34, v[70:73] offset:41472
	ds_write_b128 v34, v[74:77] offset:46080
	s_waitcnt vmcnt(0)
	ds_write_b128 v34, v[144:147] offset:50688
	s_setprio 1
	s_waitcnt lgkmcnt(7)
	v_mfma_f32_32x32x16_bf16 v[2:17], v[50:53], v[78:81], v[2:17]
	ds_read_b128 v[54:57], v1 offset:18464
	ds_read_b128 v[58:61], v1 offset:18528
	global_load_dwordx4 v[62:65], v[38:39], off offset:768
	global_load_dwordx4 v[66:69], v[42:43], off offset:768
	global_load_dwordx4 v[70:73], v[44:45], off offset:768
	global_load_dwordx4 v[74:77], v[46:47], off offset:768
	global_load_dwordx4 v[140:143], v[40:41], off offset:768
	global_load_dwordx4 v[144:147], v[48:49], off offset:768
	ds_read_b128 v[78:81], v1 offset:23136
	s_waitcnt lgkmcnt(9)
	v_mfma_f32_32x32x16_bf16 v[18:33], v[50:53], v[82:85], v[18:33]
	ds_read_b128 v[50:53], v36 offset:32
	s_waitcnt lgkmcnt(0)
	v_mfma_f32_32x32x16_bf16 v[2:17], v[50:53], v[54:57], v[2:17]
	ds_read_b128 v[54:57], v1 offset:23072
	s_waitcnt lgkmcnt(0)
	v_mfma_f32_32x32x16_bf16 v[18:33], v[50:53], v[54:57], v[18:33]
	ds_read_b128 v[50:53], v36 offset:64
	ds_read_b128 v[54:57], v1 offset:18496
	s_waitcnt lgkmcnt(0)
	v_mfma_f32_32x32x16_bf16 v[2:17], v[50:53], v[54:57], v[2:17]
	ds_read_b128 v[54:57], v1 offset:23104
	s_waitcnt lgkmcnt(0)
	v_mfma_f32_32x32x16_bf16 v[18:33], v[50:53], v[54:57], v[18:33]
	ds_read_b128 v[50:53], v36 offset:96
	s_waitcnt lgkmcnt(0)
	v_mfma_f32_32x32x16_bf16 v[2:17], v[50:53], v[58:61], v[2:17]
	v_mfma_f32_32x32x16_bf16 v[18:33], v[50:53], v[78:81], v[18:33]
	s_setprio 0
	s_barrier
	ds_read_b128 v[50:53], v36 offset:9216
	ds_read_b128 v[78:81], v1 offset:36864
	ds_read_b128 v[82:85], v1 offset:41472
	s_waitcnt vmcnt(1)
	ds_write_b128 v34, v[140:143]
	ds_write_b128 v34, v[62:65] offset:4608
	ds_write_b128 v34, v[66:69] offset:18432
	ds_write_b128 v34, v[70:73] offset:23040
	ds_write_b128 v34, v[74:77] offset:27648
	s_waitcnt vmcnt(0)
	ds_write_b128 v34, v[144:147] offset:32256
	s_setprio 1
	s_waitcnt lgkmcnt(7)
	v_mfma_f32_32x32x16_bf16 v[2:17], v[50:53], v[78:81], v[2:17]
	ds_read_b128 v[54:57], v1 offset:36896
	ds_read_b128 v[58:61], v1 offset:36960
	global_load_dwordx4 v[62:65], v[38:39], off offset:896
	global_load_dwordx4 v[66:69], v[42:43], off offset:896
	global_load_dwordx4 v[70:73], v[44:45], off offset:896
	global_load_dwordx4 v[74:77], v[46:47], off offset:896
	global_load_dwordx4 v[140:143], v[40:41], off offset:896
	global_load_dwordx4 v[144:147], v[48:49], off offset:896
	ds_read_b128 v[78:81], v1 offset:41568
	s_waitcnt lgkmcnt(9)
	v_mfma_f32_32x32x16_bf16 v[18:33], v[50:53], v[82:85], v[18:33]
	ds_read_b128 v[50:53], v36 offset:9248
	s_waitcnt lgkmcnt(0)
	v_mfma_f32_32x32x16_bf16 v[2:17], v[50:53], v[54:57], v[2:17]
	ds_read_b128 v[54:57], v1 offset:41504
	s_waitcnt lgkmcnt(0)
	v_mfma_f32_32x32x16_bf16 v[18:33], v[50:53], v[54:57], v[18:33]
	ds_read_b128 v[50:53], v36 offset:9280
	ds_read_b128 v[54:57], v1 offset:36928
	s_waitcnt lgkmcnt(0)
	v_mfma_f32_32x32x16_bf16 v[2:17], v[50:53], v[54:57], v[2:17]
	ds_read_b128 v[54:57], v1 offset:41536
	s_waitcnt lgkmcnt(0)
	v_mfma_f32_32x32x16_bf16 v[18:33], v[50:53], v[54:57], v[18:33]
	ds_read_b128 v[50:53], v36 offset:9312
	s_waitcnt lgkmcnt(0)
	v_mfma_f32_32x32x16_bf16 v[2:17], v[50:53], v[58:61], v[2:17]
	v_mfma_f32_32x32x16_bf16 v[18:33], v[50:53], v[78:81], v[18:33]
	s_setprio 0
	s_barrier
; #define MFMA(a, b, c) __builtin_amdgcn_mfma_f32_32x32x16_bf16((a), (b), (c), 0, 0, 0)
; template <int TM, int TN>
; DI void gemm_mainloop(const u16* __restrict__ A, long lda, const u16* __restrict__ Bt, long ldb, int K, char* smem,
;                       f32x16 (&acc)[TM][TN]) {
;     ...
;   for (int kt = 0; kt < nk; kt++) {
;     const int buf = kt & 1;
;     const u16* cA = sA + buf * BM * LD + (wm * 32 * TM + r) * LD + h * 8;
;     const u16* cB = sB + buf * BN * LD + (wn * 32 * TN + r) * LD + h * 8;
;     bf16x8 af[TM], bfr[TN];
; #pragma unroll
;     for (int tm = 0; tm < TM; tm++) af[tm] = *(const bf16x8*)(cA + tm * 32 * LD);
; #pragma unroll
;     for (int tn = 0; tn < TN; tn++) bfr[tn] = *(const bf16x8*)(cB + tn * 32 * LD);
;     if (kt + 1 < nk) GEMM_SSTORE(buf ^ 1)
;     __builtin_amdgcn_sched_barrier(0);
;     __builtin_amdgcn_s_setprio(1);
; #pragma unroll
;     for (int tm = 0; tm < TM; tm++)
; #pragma unroll
;       for (int tn = 0; tn < TN; tn++) acc[tm][tn] = MFMA(af[tm], bfr[tn], acc[tm][tn]);
; #pragma unroll
;     for (int tm = 0; tm < TM; tm++) af[tm] = *(const bf16x8*)(cA + tm * 32 * LD + 16);
; #pragma unroll
;     for (int tn = 0; tn < TN; tn++) bfr[tn] = *(const bf16x8*)(cB + tn * 32 * LD + 16);
; #pragma unroll
;     for (int tm = 0; tm < TM; tm++)
; #pragma unroll
;       for (int tn = 0; tn < TN; tn++) acc[tm][tn] = MFMA(af[tm], bfr[tn], acc[tm][tn]);
;     __builtin_amdgcn_sched_group_barrier(0x8, 4, 0);
;     if (kt + 2 < nk) GEMM_GLOAD((kt + 2) * 64)
; #pragma unroll
;     for (int ks = 2; ks < 4; ks++) {
; #pragma unroll
;       for (int tm = 0; tm < TM; tm++) af[tm] = *(const bf16x8*)(cA + tm * 32 * LD + ks * 16);
; #pragma unroll
;       for (int tn = 0; tn < TN; tn++) bfr[tn] = *(const bf16x8*)(cB + tn * 32 * LD + ks * 16);
; #pragma unroll
;       for (int tm = 0; tm < TM; tm++)
; #pragma unroll
;         for (int tn = 0; tn < TN; tn++) acc[tm][tn] = MFMA(af[tm], bfr[tn], acc[tm][tn]);
;     }
;     __builtin_amdgcn_s_setprio(0);
;     __syncthreads();
;   }
	ds_read_b128 v[50:53], v36
	ds_read_b128 v[78:81], v1 offset:18432
	ds_read_b128 v[82:85], v1 offset:23040
	s_waitcnt vmcnt(1)
	ds_write_b128 v34, v[140:143] offset:9216
	ds_write_b128 v34, v[62:65] offset:13824
	ds_write_b128 v34, v[66:69] offset:36864
	ds_write_b128 v34, v[70:73] offset:41472
	ds_write_b128 v34, v[74:77] offset:46080
	s_waitcnt vmcnt(0)
	ds_write_b128 v34, v[144:147] offset:50688
	s_setprio 1
	s_waitcnt lgkmcnt(7)
	v_mfma_f32_32x32x16_bf16 v[2:17], v[50:53], v[78:81], v[2:17]
	ds_read_b128 v[54:57], v1 offset:18464
	ds_read_b128 v[58:61], v1 offset:18528
	global_load_dwordx4 v[62:65], v[38:39], off offset:1024
	global_load_dwordx4 v[66:69], v[42:43], off offset:1024
	global_load_dwordx4 v[70:73], v[44:45], off offset:1024
	global_load_dwordx4 v[74:77], v[46:47], off offset:1024
	global_load_dwordx4 v[140:143], v[40:41], off offset:1024
	global_load_dwordx4 v[144:147], v[48:49], off offset:1024
	ds_read_b128 v[78:81], v1 offset:23136
	s_waitcnt lgkmcnt(9)
	v_mfma_f32_32x32x16_bf16 v[18:33], v[50:53], v[82:85], v[18:33]
	ds_read_b128 v[50:53], v36 offset:32
	s_waitcnt lgkmcnt(0)
	v_mfma_f32_32x32x16_bf16 v[2:17], v[50:53], v[54:57], v[2:17]
	ds_read_b128 v[54:57], v1 offset:23072
	s_waitcnt lgkmcnt(0)
	v_mfma_f32_32x32x16_bf16 v[18:33], v[50:53], v[54:57], v[18:33]
	ds_read_b128 v[50:53], v36 offset:64
	ds_read_b128 v[54:57], v1 offset:18496
	s_waitcnt lgkmcnt(0)
	v_mfma_f32_32x32x16_bf16 v[2:17], v[50:53], v[54:57], v[2:17]
	ds_read_b128 v[54:57], v1 offset:23104
	s_waitcnt lgkmcnt(0)
	v_mfma_f32_32x32x16_bf16 v[18:33], v[50:53], v[54:57], v[18:33]
	ds_read_b128 v[50:53], v36 offset:96
	s_waitcnt lgkmcnt(0)
	v_mfma_f32_32x32x16_bf16 v[2:17], v[50:53], v[58:61], v[2:17]
	v_mfma_f32_32x32x16_bf16 v[18:33], v[50:53], v[78:81], v[18:33]
	s_setprio 0
	s_barrier
	ds_read_b128 v[50:53], v36 offset:9216
	ds_read_b128 v[78:81], v1 offset:36864
	ds_read_b128 v[82:85], v1 offset:41472
	s_waitcnt vmcnt(1)
	ds_write_b128 v34, v[140:143]
	ds_write_b128 v34, v[62:65] offset:4608
	ds_write_b128 v34, v[66:69] offset:18432
	ds_write_b128 v34, v[70:73] offset:23040
	ds_write_b128 v34, v[74:77] offset:27648
	s_waitcnt vmcnt(0)
	ds_write_b128 v34, v[144:147] offset:32256
	s_setprio 1
	s_waitcnt lgkmcnt(7)
	v_mfma_f32_32x32x16_bf16 v[2:17], v[50:53], v[78:81], v[2:17]
	ds_read_b128 v[54:57], v1 offset:36896
	ds_read_b128 v[58:61], v1 offset:36960
	global_load_dwordx4 v[62:65], v[38:39], off offset:1152
	global_load_dwordx4 v[66:69], v[42:43], off offset:1152
	global_load_dwordx4 v[70:73], v[44:45], off offset:1152
	global_load_dwordx4 v[74:77], v[46:47], off offset:1152
	global_load_dwordx4 v[140:143], v[40:41], off offset:1152
	global_load_dwordx4 v[144:147], v[48:49], off offset:1152
	ds_read_b128 v[78:81], v1 offset:41568
	s_waitcnt lgkmcnt(9)
	v_mfma_f32_32x32x16_bf16 v[18:33], v[50:53], v[82:85], v[18:33]
	ds_read_b128 v[50:53], v36 offset:9248
	s_waitcnt lgkmcnt(0)
	v_mfma_f32_32x32x16_bf16 v[2:17], v[50:53], v[54:57], v[2:17]
	ds_read_b128 v[54:57], v1 offset:41504
	s_waitcnt lgkmcnt(0)
	v_mfma_f32_32x32x16_bf16 v[18:33], v[50:53], v[54:57], v[18:33]
	ds_read_b128 v[50:53], v36 offset:9280
	ds_read_b128 v[54:57], v1 offset:36928
	s_waitcnt lgkmcnt(0)
	v_mfma_f32_32x32x16_bf16 v[2:17], v[50:53], v[54:57], v[2:17]
	ds_read_b128 v[54:57], v1 offset:41536
	s_waitcnt lgkmcnt(0)
	v_mfma_f32_32x32x16_bf16 v[18:33], v[50:53], v[54:57], v[18:33]
	ds_read_b128 v[50:53], v36 offset:9312
	s_waitcnt lgkmcnt(0)
	v_mfma_f32_32x32x16_bf16 v[2:17], v[50:53], v[58:61], v[2:17]
	v_mfma_f32_32x32x16_bf16 v[18:33], v[50:53], v[78:81], v[18:33]
	s_setprio 0
	s_barrier
	ds_read_b128 v[50:53], v36
	ds_read_b128 v[78:81], v1 offset:18432
	ds_read_b128 v[82:85], v1 offset:23040
	s_waitcnt vmcnt(1)
	ds_write_b128 v34, v[140:143] offset:9216
	ds_write_b128 v34, v[62:65] offset:13824
	ds_write_b128 v34, v[66:69] offset:36864
	ds_write_b128 v34, v[70:73] offset:41472
	ds_write_b128 v34, v[74:77] offset:46080
	s_waitcnt vmcnt(0)
	ds_write_b128 v34, v[144:147] offset:50688
	s_setprio 1
	s_waitcnt lgkmcnt(7)
	v_mfma_f32_32x32x16_bf16 v[2:17], v[50:53], v[78:81], v[2:17]
	ds_read_b128 v[54:57], v1 offset:18464
	ds_read_b128 v[58:61], v1 offset:18528
	global_load_dwordx4 v[62:65], v[38:39], off offset:1280
	global_load_dwordx4 v[66:69], v[42:43], off offset:1280
	global_load_dwordx4 v[70:73], v[44:45], off offset:1280
	global_load_dwordx4 v[74:77], v[46:47], off offset:1280
	global_load_dwordx4 v[140:143], v[40:41], off offset:1280
	global_load_dwordx4 v[144:147], v[48:49], off offset:1280
	ds_read_b128 v[78:81], v1 offset:23136
	s_waitcnt lgkmcnt(9)
	v_mfma_f32_32x32x16_bf16 v[18:33], v[50:53], v[82:85], v[18:33]
	ds_read_b128 v[50:53], v36 offset:32
	s_waitcnt lgkmcnt(0)
	v_mfma_f32_32x32x16_bf16 v[2:17], v[50:53], v[54:57], v[2:17]
	ds_read_b128 v[54:57], v1 offset:23072
	s_waitcnt lgkmcnt(0)
	v_mfma_f32_32x32x16_bf16 v[18:33], v[50:53], v[54:57], v[18:33]
	ds_read_b128 v[50:53], v36 offset:64
	ds_read_b128 v[54:57], v1 offset:18496
	s_waitcnt lgkmcnt(0)
	v_mfma_f32_32x32x16_bf16 v[2:17], v[50:53], v[54:57], v[2:17]
	ds_read_b128 v[54:57], v1 offset:23104
	s_waitcnt lgkmcnt(0)
	v_mfma_f32_32x32x16_bf16 v[18:33], v[50:53], v[54:57], v[18:33]
	ds_read_b128 v[50:53], v36 offset:96
	s_waitcnt lgkmcnt(0)
	v_mfma_f32_32x32x16_bf16 v[2:17], v[50:53], v[58:61], v[2:17]
	v_mfma_f32_32x32x16_bf16 v[18:33], v[50:53], v[78:81], v[18:33]
	s_setprio 0
	s_barrier
; #define MFMA(a, b, c) __builtin_amdgcn_mfma_f32_32x32x16_bf16((a), (b), (c), 0, 0, 0)
; template <int TM, int TN>
; DI void gemm_mainloop(const u16* __restrict__ A, long lda, const u16* __restrict__ Bt, long ldb, int K, char* smem,
;                       f32x16 (&acc)[TM][TN]) {
;     ...
;   for (int kt = 0; kt < nk; kt++) {
;     const int buf = kt & 1;
;     const u16* cA = sA + buf * BM * LD + (wm * 32 * TM + r) * LD + h * 8;
;     const u16* cB = sB + buf * BN * LD + (wn * 32 * TN + r) * LD + h * 8;
;     bf16x8 af[TM], bfr[TN];
; #pragma unroll
;     for (int tm = 0; tm < TM; tm++) af[tm] = *(const bf16x8*)(cA + tm * 32 * LD);
; #pragma unroll
;     for (int tn = 0; tn < TN; tn++) bfr[tn] = *(const bf16x8*)(cB + tn * 32 * LD);
;     if (kt + 1 < nk) GEMM_SSTORE(buf ^ 1)
;     __builtin_amdgcn_sched_barrier(0);
;     __builtin_amdgcn_s_setprio(1);
; #pragma unroll
;     for (int tm = 0; tm < TM; tm++)
; #pragma unroll
;       for (int tn = 0; tn < TN; tn++) acc[tm][tn] = MFMA(af[tm], bfr[tn], acc[tm][tn]);
; #pragma unroll
;     for (int tm = 0; tm < TM; tm++) af[tm] = *(const bf16x8*)(cA + tm * 32 * LD + 16);
; #pragma unroll
;     for (int tn = 0; tn < TN; tn++) bfr[tn] = *(const bf16x8*)(cB + tn * 32 * LD + 16);
; #pragma unroll
;     for (int tm = 0; tm < TM; tm++)
; #pragma unroll
;       for (int tn = 0; tn < TN; tn++) acc[tm][tn] = MFMA(af[tm], bfr[tn], acc[tm][tn]);
;     __builtin_amdgcn_sched_group_barrier(0x8, 4, 0);
;     if (kt + 2 < nk) GEMM_GLOAD((kt + 2) * 64)
; #pragma unroll
;     for (int ks = 2; ks < 4; ks++) {
; #pragma unroll
;       for (int tm = 0; tm < TM; tm++) af[tm] = *(const bf16x8*)(cA + tm * 32 * LD + ks * 16);
; #pragma unroll
;       for (int tn = 0; tn < TN; tn++) bfr[tn] = *(const bf16x8*)(cB + tn * 32 * LD + ks * 16);
; #pragma unroll
;       for (int tm = 0; tm < TM; tm++)
; #pragma unroll
;         for (int tn = 0; tn < TN; tn++) acc[tm][tn] = MFMA(af[tm], bfr[tn], acc[tm][tn]);
;     }
;     __builtin_amdgcn_s_setprio(0);
;     __syncthreads();
;   }
	ds_read_b128 v[50:53], v36 offset:9216
	ds_read_b128 v[78:81], v1 offset:36864
	ds_read_b128 v[82:85], v1 offset:41472
	s_waitcnt vmcnt(1)
	ds_write_b128 v34, v[140:143]
	ds_write_b128 v34, v[62:65] offset:4608
	ds_write_b128 v34, v[66:69] offset:18432
	ds_write_b128 v34, v[70:73] offset:23040
	ds_write_b128 v34, v[74:77] offset:27648
	s_waitcnt vmcnt(0)
	ds_write_b128 v34, v[144:147] offset:32256
	s_setprio 1
	s_waitcnt lgkmcnt(7)
	v_mfma_f32_32x32x16_bf16 v[2:17], v[50:53], v[78:81], v[2:17]
	ds_read_b128 v[54:57], v1 offset:36896
	ds_read_b128 v[58:61], v1 offset:36960
	global_load_dwordx4 v[62:65], v[38:39], off offset:1408
	global_load_dwordx4 v[66:69], v[42:43], off offset:1408
	global_load_dwordx4 v[70:73], v[44:45], off offset:1408
	global_load_dwordx4 v[74:77], v[46:47], off offset:1408
	global_load_dwordx4 v[140:143], v[40:41], off offset:1408
	global_load_dwordx4 v[144:147], v[48:49], off offset:1408
	ds_read_b128 v[78:81], v1 offset:41568
	s_waitcnt lgkmcnt(9)
	v_mfma_f32_32x32x16_bf16 v[18:33], v[50:53], v[82:85], v[18:33]
	ds_read_b128 v[50:53], v36 offset:9248
	s_waitcnt lgkmcnt(0)
	v_mfma_f32_32x32x16_bf16 v[2:17], v[50:53], v[54:57], v[2:17]
	ds_read_b128 v[54:57], v1 offset:41504
	s_waitcnt lgkmcnt(0)
	v_mfma_f32_32x32x16_bf16 v[18:33], v[50:53], v[54:57], v[18:33]
	ds_read_b128 v[50:53], v36 offset:9280
	ds_read_b128 v[54:57], v1 offset:36928
	s_waitcnt lgkmcnt(0)
	v_mfma_f32_32x32x16_bf16 v[2:17], v[50:53], v[54:57], v[2:17]
	ds_read_b128 v[54:57], v1 offset:41536
	s_waitcnt lgkmcnt(0)
	v_mfma_f32_32x32x16_bf16 v[18:33], v[50:53], v[54:57], v[18:33]
	ds_read_b128 v[50:53], v36 offset:9312
	s_waitcnt lgkmcnt(0)
	v_mfma_f32_32x32x16_bf16 v[2:17], v[50:53], v[58:61], v[2:17]
	v_mfma_f32_32x32x16_bf16 v[18:33], v[50:53], v[78:81], v[18:33]
	s_setprio 0
	s_barrier
	ds_read_b128 v[50:53], v36
	ds_read_b128 v[78:81], v1 offset:18432
	ds_read_b128 v[82:85], v1 offset:23040
	s_waitcnt vmcnt(1)
	ds_write_b128 v34, v[140:143] offset:9216
	ds_write_b128 v34, v[62:65] offset:13824
	ds_write_b128 v34, v[66:69] offset:36864
	ds_write_b128 v34, v[70:73] offset:41472
	ds_write_b128 v34, v[74:77] offset:46080
	s_waitcnt vmcnt(0)
	ds_write_b128 v34, v[144:147] offset:50688
	s_setprio 1
	s_waitcnt lgkmcnt(7)
	v_mfma_f32_32x32x16_bf16 v[2:17], v[50:53], v[78:81], v[2:17]
	ds_read_b128 v[54:57], v1 offset:18464
	ds_read_b128 v[58:61], v1 offset:18528
	global_load_dwordx4 v[62:65], v[38:39], off offset:1536
	global_load_dwordx4 v[66:69], v[42:43], off offset:1536
	global_load_dwordx4 v[70:73], v[44:45], off offset:1536
	global_load_dwordx4 v[74:77], v[46:47], off offset:1536
	global_load_dwordx4 v[140:143], v[40:41], off offset:1536
	global_load_dwordx4 v[144:147], v[48:49], off offset:1536
	ds_read_b128 v[78:81], v1 offset:23136
	s_waitcnt lgkmcnt(9)
	v_mfma_f32_32x32x16_bf16 v[18:33], v[50:53], v[82:85], v[18:33]
	ds_read_b128 v[50:53], v36 offset:32
	s_waitcnt lgkmcnt(0)
	v_mfma_f32_32x32x16_bf16 v[2:17], v[50:53], v[54:57], v[2:17]
	ds_read_b128 v[54:57], v1 offset:23072
	s_waitcnt lgkmcnt(0)
	v_mfma_f32_32x32x16_bf16 v[18:33], v[50:53], v[54:57], v[18:33]
	ds_read_b128 v[50:53], v36 offset:64
	ds_read_b128 v[54:57], v1 offset:18496
	s_waitcnt lgkmcnt(0)
	v_mfma_f32_32x32x16_bf16 v[2:17], v[50:53], v[54:57], v[2:17]
	ds_read_b128 v[54:57], v1 offset:23104
	s_waitcnt lgkmcnt(0)
	v_mfma_f32_32x32x16_bf16 v[18:33], v[50:53], v[54:57], v[18:33]
	ds_read_b128 v[50:53], v36 offset:96
	s_waitcnt lgkmcnt(0)
	v_mfma_f32_32x32x16_bf16 v[2:17], v[50:53], v[58:61], v[2:17]
	v_mfma_f32_32x32x16_bf16 v[18:33], v[50:53], v[78:81], v[18:33]
	s_setprio 0
	s_barrier
	ds_read_b128 v[50:53], v36 offset:9216
	ds_read_b128 v[78:81], v1 offset:36864
	ds_read_b128 v[82:85], v1 offset:41472
	s_waitcnt vmcnt(1)
	ds_write_b128 v34, v[140:143]
	ds_write_b128 v34, v[62:65] offset:4608
	ds_write_b128 v34, v[66:69] offset:18432
	ds_write_b128 v34, v[70:73] offset:23040
	ds_write_b128 v34, v[74:77] offset:27648
	s_waitcnt vmcnt(0)
	ds_write_b128 v34, v[144:147] offset:32256
	s_setprio 1
	s_waitcnt lgkmcnt(7)
	v_mfma_f32_32x32x16_bf16 v[2:17], v[50:53], v[78:81], v[2:17]
	ds_read_b128 v[54:57], v1 offset:36896
	ds_read_b128 v[58:61], v1 offset:36960
	global_load_dwordx4 v[62:65], v[38:39], off offset:1664
	global_load_dwordx4 v[66:69], v[42:43], off offset:1664
	global_load_dwordx4 v[70:73], v[44:45], off offset:1664
	global_load_dwordx4 v[74:77], v[46:47], off offset:1664
	global_load_dwordx4 v[140:143], v[40:41], off offset:1664
	global_load_dwordx4 v[144:147], v[48:49], off offset:1664
	ds_read_b128 v[78:81], v1 offset:41568
	s_waitcnt lgkmcnt(9)
	v_mfma_f32_32x32x16_bf16 v[18:33], v[50:53], v[82:85], v[18:33]
	ds_read_b128 v[50:53], v36 offset:9248
	s_waitcnt lgkmcnt(0)
	v_mfma_f32_32x32x16_bf16 v[2:17], v[50:53], v[54:57], v[2:17]
	ds_read_b128 v[54:57], v1 offset:41504
	s_waitcnt lgkmcnt(0)
	v_mfma_f32_32x32x16_bf16 v[18:33], v[50:53], v[54:57], v[18:33]
	ds_read_b128 v[50:53], v36 offset:9280
	ds_read_b128 v[54:57], v1 offset:36928
	s_waitcnt lgkmcnt(0)
	v_mfma_f32_32x32x16_bf16 v[2:17], v[50:53], v[54:57], v[2:17]
	ds_read_b128 v[54:57], v1 offset:41536
	s_waitcnt lgkmcnt(0)
	v_mfma_f32_32x32x16_bf16 v[18:33], v[50:53], v[54:57], v[18:33]
	ds_read_b128 v[50:53], v36 offset:9312
	s_waitcnt lgkmcnt(0)
	v_mfma_f32_32x32x16_bf16 v[2:17], v[50:53], v[58:61], v[2:17]
	v_mfma_f32_32x32x16_bf16 v[18:33], v[50:53], v[78:81], v[18:33]
	s_setprio 0
	s_barrier
; #define MFMA(a, b, c) __builtin_amdgcn_mfma_f32_32x32x16_bf16((a), (b), (c), 0, 0, 0)
; template <int TM, int TN>
; DI void gemm_mainloop(const u16* __restrict__ A, long lda, const u16* __restrict__ Bt, long ldb, int K, char* smem,
;                       f32x16 (&acc)[TM][TN]) {
;     ...
;   for (int kt = 0; kt < nk; kt++) {
;     const int buf = kt & 1;
;     const u16* cA = sA + buf * BM * LD + (wm * 32 * TM + r) * LD + h * 8;
;     const u16* cB = sB + buf * BN * LD + (wn * 32 * TN + r) * LD + h * 8;
;     bf16x8 af[TM], bfr[TN];
; #pragma unroll
;     for (int tm = 0; tm < TM; tm++) af[tm] = *(const bf16x8*)(cA + tm * 32 * LD);
; #pragma unroll
;     for (int tn = 0; tn < TN; tn++) bfr[tn] = *(const bf16x8*)(cB + tn * 32 * LD);
;     if (kt + 1 < nk) GEMM_SSTORE(buf ^ 1)
;     __builtin_amdgcn_sched_barrier(0);
;     __builtin_amdgcn_s_setprio(1);
; #pragma unroll
;     for (int tm = 0; tm < TM; tm++)
; #pragma unroll
;       for (int tn = 0; tn < TN; tn++) acc[tm][tn] = MFMA(af[tm], bfr[tn], acc[tm][tn]);
; #pragma unroll
;     for (int tm = 0; tm < TM; tm++) af[tm] = *(const bf16x8*)(cA + tm * 32 * LD + 16);
; #pragma unroll
;     for (int tn = 0; tn < TN; tn++) bfr[tn] = *(const bf16x8*)(cB + tn * 32 * LD + 16);
; #pragma unroll
;     for (int tm = 0; tm < TM; tm++)
; #pragma unroll
;       for (int tn = 0; tn < TN; tn++) acc[tm][tn] = MFMA(af[tm], bfr[tn], acc[tm][tn]);
;     __builtin_amdgcn_sched_group_barrier(0x8, 4, 0);
;     if (kt + 2 < nk) GEMM_GLOAD((kt + 2) * 64)
; #pragma unroll
;     for (int ks = 2; ks < 4; ks++) {
; #pragma unroll
;       for (int tm = 0; tm < TM; tm++) af[tm] = *(const bf16x8*)(cA + tm * 32 * LD + ks * 16);
; #pragma unroll
;       for (int tn = 0; tn < TN; tn++) bfr[tn] = *(const bf16x8*)(cB + tn * 32 * LD + ks * 16);
; #pragma unroll
;       for (int tm = 0; tm < TM; tm++)
; #pragma unroll
;         for (int tn = 0; tn < TN; tn++) acc[tm][tn] = MFMA(af[tm], bfr[tn], acc[tm][tn]);
;     }
;     __builtin_amdgcn_s_setprio(0);
;     __syncthreads();
;   }
	ds_read_b128 v[50:53], v36
	ds_read_b128 v[78:81], v1 offset:18432
	ds_read_b128 v[82:85], v1 offset:23040
	s_waitcnt vmcnt(1)
	ds_write_b128 v34, v[140:143] offset:9216
	ds_write_b128 v34, v[62:65] offset:13824
	ds_write_b128 v34, v[66:69] offset:36864
	ds_write_b128 v34, v[70:73] offset:41472
	ds_write_b128 v34, v[74:77] offset:46080
	s_waitcnt vmcnt(0)
	ds_write_b128 v34, v[144:147] offset:50688
	s_setprio 1
	s_waitcnt lgkmcnt(7)
	v_mfma_f32_32x32x16_bf16 v[2:17], v[50:53], v[78:81], v[2:17]
	ds_read_b128 v[54:57], v1 offset:18464
	ds_read_b128 v[58:61], v1 offset:18528
	global_load_dwordx4 v[62:65], v[38:39], off offset:1792
	global_load_dwordx4 v[66:69], v[42:43], off offset:1792
	global_load_dwordx4 v[70:73], v[44:45], off offset:1792
	global_load_dwordx4 v[74:77], v[46:47], off offset:1792
	global_load_dwordx4 v[140:143], v[40:41], off offset:1792
	global_load_dwordx4 v[144:147], v[48:49], off offset:1792
	ds_read_b128 v[78:81], v1 offset:23136
	s_waitcnt lgkmcnt(9)
	v_mfma_f32_32x32x16_bf16 v[18:33], v[50:53], v[82:85], v[18:33]
	ds_read_b128 v[50:53], v36 offset:32
	s_waitcnt lgkmcnt(0)
	v_mfma_f32_32x32x16_bf16 v[2:17], v[50:53], v[54:57], v[2:17]
	ds_read_b128 v[54:57], v1 offset:23072
	s_waitcnt lgkmcnt(0)
	v_mfma_f32_32x32x16_bf16 v[18:33], v[50:53], v[54:57], v[18:33]
	ds_read_b128 v[50:53], v36 offset:64
	ds_read_b128 v[54:57], v1 offset:18496
	s_waitcnt lgkmcnt(0)
	v_mfma_f32_32x32x16_bf16 v[2:17], v[50:53], v[54:57], v[2:17]
	ds_read_b128 v[54:57], v1 offset:23104
	s_waitcnt lgkmcnt(0)
	v_mfma_f32_32x32x16_bf16 v[18:33], v[50:53], v[54:57], v[18:33]
	ds_read_b128 v[50:53], v36 offset:96
	s_waitcnt lgkmcnt(0)
	v_mfma_f32_32x32x16_bf16 v[2:17], v[50:53], v[58:61], v[2:17]
	v_mfma_f32_32x32x16_bf16 v[18:33], v[50:53], v[78:81], v[18:33]
	s_setprio 0
	s_barrier
	ds_read_b128 v[50:53], v36 offset:9216
	ds_read_b128 v[78:81], v1 offset:36864
	ds_read_b128 v[82:85], v1 offset:41472
	s_waitcnt vmcnt(1)
	ds_write_b128 v34, v[140:143]
	ds_write_b128 v34, v[62:65] offset:4608
	ds_write_b128 v34, v[66:69] offset:18432
	ds_write_b128 v34, v[70:73] offset:23040
	ds_write_b128 v34, v[74:77] offset:27648
	s_waitcnt vmcnt(0)
	ds_write_b128 v34, v[144:147] offset:32256
	s_setprio 1
	s_waitcnt lgkmcnt(7)
	v_mfma_f32_32x32x16_bf16 v[2:17], v[50:53], v[78:81], v[2:17]
	ds_read_b128 v[54:57], v1 offset:36896
	global_load_dwordx4 v[62:65], v[38:39], off offset:1920
	global_load_dwordx4 v[66:69], v[42:43], off offset:1920
	global_load_dwordx4 v[70:73], v[44:45], off offset:1920
	global_load_dwordx4 v[74:77], v[46:47], off offset:1920
	global_load_dwordx4 v[140:143], v[40:41], off offset:1920
	global_load_dwordx4 v[144:147], v[48:49], off offset:1920
	ds_read_b128 v[58:61], v1 offset:36960
	ds_read_b128 v[42:45], v1 offset:41568
	s_waitcnt lgkmcnt(9)
	v_mfma_f32_32x32x16_bf16 v[18:33], v[50:53], v[82:85], v[18:33]
	ds_read_b128 v[50:53], v36 offset:9248
	s_waitcnt lgkmcnt(0)
	v_mfma_f32_32x32x16_bf16 v[2:17], v[50:53], v[54:57], v[2:17]
	ds_read_b128 v[54:57], v1 offset:41504
	s_waitcnt lgkmcnt(0)
	v_mfma_f32_32x32x16_bf16 v[18:33], v[50:53], v[54:57], v[18:33]
	ds_read_b128 v[50:53], v36 offset:9280
	ds_read_b128 v[54:57], v1 offset:36928
	s_waitcnt lgkmcnt(0)
	v_mfma_f32_32x32x16_bf16 v[2:17], v[50:53], v[54:57], v[2:17]
	ds_read_b128 v[54:57], v1 offset:41536
	s_waitcnt lgkmcnt(0)
	v_mfma_f32_32x32x16_bf16 v[18:33], v[50:53], v[54:57], v[18:33]
	ds_read_b128 v[50:53], v36 offset:9312
	s_waitcnt lgkmcnt(0)
	v_mfma_f32_32x32x16_bf16 v[2:17], v[50:53], v[58:61], v[2:17]
	v_mfma_f32_32x32x16_bf16 v[18:33], v[50:53], v[42:45], v[18:33]
	s_setprio 0
	s_barrier
	ds_read_b128 v[42:45], v36
	ds_read_b128 v[46:49], v1 offset:18432
	ds_read_b128 v[50:53], v1 offset:23040
	s_waitcnt vmcnt(1)
	ds_write_b128 v34, v[140:143] offset:9216
	ds_write_b128 v34, v[62:65] offset:13824
	ds_write_b128 v34, v[66:69] offset:36864
	ds_write_b128 v34, v[70:73] offset:41472
	ds_write_b128 v34, v[74:77] offset:46080
	s_waitcnt vmcnt(0)
	ds_write_b128 v34, v[144:147] offset:50688
	s_setprio 1
	ds_read_b128 v[38:41], v36 offset:32
	s_waitcnt lgkmcnt(8)
	v_mfma_f32_32x32x16_bf16 v[2:17], v[42:45], v[46:49], v[2:17]
	s_waitcnt lgkmcnt(7)
	v_mfma_f32_32x32x16_bf16 v[18:33], v[42:45], v[50:53], v[18:33]
	ds_read_b128 v[42:45], v1 offset:18464
	s_waitcnt lgkmcnt(0)
	v_mfma_f32_32x32x16_bf16 v[2:17], v[38:41], v[42:45], v[2:17]
	ds_read_b128 v[42:45], v1 offset:23072
	s_waitcnt lgkmcnt(0)
	v_mfma_f32_32x32x16_bf16 v[18:33], v[38:41], v[42:45], v[18:33]
	ds_read_b128 v[38:41], v36 offset:64
	ds_read_b128 v[42:45], v1 offset:18496
	s_waitcnt lgkmcnt(0)
	v_mfma_f32_32x32x16_bf16 v[2:17], v[38:41], v[42:45], v[2:17]
	ds_read_b128 v[42:45], v1 offset:23104
	s_waitcnt lgkmcnt(0)
	v_mfma_f32_32x32x16_bf16 v[18:33], v[38:41], v[42:45], v[18:33]
	ds_read_b128 v[38:41], v36 offset:96
	ds_read_b128 v[42:45], v1 offset:18528
	s_waitcnt lgkmcnt(0)
	v_mfma_f32_32x32x16_bf16 v[2:17], v[38:41], v[42:45], v[2:17]
	ds_read_b128 v[42:45], v1 offset:23136
	s_waitcnt lgkmcnt(0)
	v_mfma_f32_32x32x16_bf16 v[18:33], v[38:41], v[42:45], v[18:33]
	s_setprio 0
	s_barrier
; DI int crow(int i, int h) { return (i & 3) + 8 * (i >> 2) + 4 * h; }
; template <int TM, int TN, class Epi>
; DI void gemm_tile(const u16* A, long lda, const u16* Bt, long ldb, int K, int m0, int n0, char* smem, const Epi& epi) {
;     ...
; #pragma unroll
;   for (int tm = 0; tm < TM; tm++)
; #pragma unroll
;     for (int tn = 0; tn < TN; tn++)
; #pragma unroll
;       for (int i = 0; i < 16; i++)
;         Ct[(wm * 32 * TM + tm * 32 + crow(i, h)) * LDC + wn * 32 * TN + tn * 32 + r] = acc[tm][tn][i];
;   __syncthreads();
;   DI void operator()(const float* Ct, int ldc, int m0, int n0, int tid, int bm) const {
;     ...
;     for (int it = 0; it < bm / 16; it++) {
;       int id = tid + 256 * it; int row = id >> 4, c8 = (id & 15) * 8;
;       int m = m0 + row;
;       const float* c = Ct + row * ldc + c8;
;       float4 a = *(const float4*)c, b = *(const float4*)(c + 4);
;       float x[8];
;       if (srcb != nullptr) {
;         unpack8(*(const uint4*)(srcb + (size_t)m * LDA + n0 + c8), x);
;       } else {
;         const float* sp = (m < NP ? src0 + (size_t)m * 1024 : src1 + (size_t)(m - NP) * 1024) + n0 + c8;
;         float4 sa = *(const float4*)sp, sb = *(const float4*)(sp + 4);
;         x[0] = sa.x; x[1] = sa.y; x[2] = sa.z; x[3] = sa.w; x[4] = sb.x; x[5] = sb.y; x[6] = sb.z; x[7] = sb.w;
;       }
;       x[0] += a.x; x[1] += a.y; x[2] += a.z; x[3] += a.w; x[4] += b.x; x[5] += b.y; x[6] += b.z; x[7] += b.w;
;       if (dstf != nullptr) {
;         float* o = dstf + (size_t)m * 1024 + n0 + c8;
;         *(float4*)o = make_float4(x[0], x[1], x[2], x[3]); *(float4*)(o + 4) = make_float4(x[4], x[5], x[6], x[7]);
;       } else {
;         *(uint4*)(dstb + (size_t)m * LDA + n0 + c8) = pack8(x);
;       }
	ds_read_b128 v[38:41], v36 offset:9216
	ds_read_b128 v[42:45], v1 offset:36864
	ds_read_b128 v[46:49], v1 offset:41472
	s_setprio 1
	s_waitcnt lgkmcnt(1)
	v_mfma_f32_32x32x16_bf16 v[2:17], v[38:41], v[42:45], v[2:17]
	ds_read_b128 v[42:45], v1 offset:36896
	s_waitcnt lgkmcnt(1)
	v_mfma_f32_32x32x16_bf16 v[18:33], v[38:41], v[46:49], v[18:33]
	ds_read_b128 v[38:41], v36 offset:9248
	s_waitcnt lgkmcnt(0)
	v_mfma_f32_32x32x16_bf16 v[2:17], v[38:41], v[42:45], v[2:17]
	ds_read_b128 v[42:45], v1 offset:41504
	s_waitcnt lgkmcnt(0)
	v_mfma_f32_32x32x16_bf16 v[18:33], v[38:41], v[42:45], v[18:33]
	ds_read_b128 v[38:41], v36 offset:9280
	ds_read_b128 v[42:45], v1 offset:36928
	s_waitcnt lgkmcnt(0)
	v_mfma_f32_32x32x16_bf16 v[2:17], v[38:41], v[42:45], v[2:17]
	ds_read_b128 v[42:45], v1 offset:41536
	s_waitcnt lgkmcnt(0)
	v_mfma_f32_32x32x16_bf16 v[18:33], v[38:41], v[42:45], v[18:33]
	ds_read_b128 v[36:39], v36 offset:9312
	ds_read_b128 v[40:43], v1 offset:36960
	s_waitcnt lgkmcnt(0)
	v_mfma_f32_32x32x16_bf16 v[2:17], v[36:39], v[40:43], v[2:17]
	ds_read_b128 v[40:43], v1 offset:41568
	s_waitcnt lgkmcnt(0)
	v_mfma_f32_32x32x16_bf16 v[18:33], v[36:39], v[40:43], v[18:33]
	s_setprio 0
	v_mov_b32_e32 v1, v0
	s_barrier
	s_lshl_b32 s4, s10, 1
	v_lshrrev_b32_e32 v36, 3, v1
	v_lshrrev_b32_e32 v34, 2, v1
	v_and_b32_e32 v36, 4, v36
	v_and_or_b32 v34, v34, s3, v36
	s_movk_i32 s3, 0x210
	v_and_b32_e32 v36, 0x5f, v1
	v_mul_lo_u32 v34, v34, s3
	v_lshl_add_u32 v34, v36, 2, v34
	ds_write2_b32 v34, v2, v18 offset1:32
	v_add_u32_e32 v2, 0x400, v34
	ds_write2_b32 v2, v4, v20 offset0:8 offset1:40
	ds_write2_b32 v2, v5, v21 offset0:140 offset1:172
	v_add_u32_e32 v2, 0x1000, v34
	ds_write2_b32 v2, v6, v22 offset0:32 offset1:64
	ds_write2_b32 v2, v7, v23 offset0:164 offset1:196
	v_add_u32_e32 v2, 0x1400, v34
	ds_write2_b32 v2, v8, v24 offset0:40 offset1:72
	ds_write2_b32 v2, v9, v25 offset0:172 offset1:204
	v_add_u32_e32 v2, 0x2000, v34
	ds_write2_b32 v2, v10, v26 offset0:64 offset1:96
	ds_write2_b32 v2, v11, v27 offset0:196 offset1:228
	v_add_u32_e32 v2, 0x2400, v34
	ds_write2_b32 v2, v12, v28 offset0:72 offset1:104
	ds_write2_b32 v2, v13, v29 offset0:204 offset1:236
	v_add_u32_e32 v2, 0x3000, v34
	ds_write2_b32 v2, v14, v30 offset0:96 offset1:128
	v_add_u32_e32 v2, 0x3200, v34
	ds_write2_b32 v2, v15, v31 offset0:100 offset1:132
	v_add_u32_e32 v2, 0x3400, v34
	ds_write2_b32 v2, v16, v32 offset0:104 offset1:136
	v_add_u32_e32 v2, 0x3600, v34
	ds_write2_b32 v2, v17, v33 offset0:108 offset1:140
	v_lshlrev_b32_e32 v2, 3, v1
	v_ashrrev_i32_e32 v7, 4, v1
	v_and_b32_e32 v6, 0x78, v2
	v_add_u32_e32 v2, s7, v7
	v_mov_b64_e32 v[14:15], s[8:9]
	ds_write2_b32 v34, v3, v19 offset0:132 offset1:164
	v_mad_i64_i32 v[2:3], s[8:9], v2, s6, v[14:15]
	v_lshl_add_u64 v[2:3], v[2:3], 0, s[4:5]
	v_lshlrev_b32_e32 v34, 1, v6
	v_lshl_add_u64 v[16:17], v[2:3], 0, v[34:35]
	s_waitcnt lgkmcnt(0)
	s_barrier
	global_load_dwordx4 v[2:5], v[16:17], off
	v_add_u32_e32 v8, 0x100, v1
	v_ashrrev_i32_e32 v19, 4, v8
	v_lshlrev_b32_e32 v18, 2, v6
	v_add_u32_e32 v6, s7, v19
	v_mad_u64_u32 v[10:11], s[8:9], v7, s3, v[18:19]
	v_mad_i64_i32 v[6:7], s[8:9], v6, s6, v[14:15]
	v_lshl_add_u64 v[6:7], v[6:7], 0, s[4:5]
	v_lshl_add_u64 v[20:21], v[6:7], 0, v[34:35]
	ds_read_b128 v[6:9], v10
	ds_read_b128 v[10:13], v10 offset:16
	s_waitcnt vmcnt(0)
	v_lshlrev_b32_e32 v22, 16, v2
	v_and_b32_e32 v23, 0xffff0000, v2
	v_lshlrev_b32_e32 v2, 16, v3
	v_and_b32_e32 v3, 0xffff0000, v3
	v_lshlrev_b32_e32 v24, 16, v4
	v_and_b32_e32 v25, 0xffff0000, v4
	v_lshlrev_b32_e32 v4, 16, v5
	v_and_b32_e32 v5, 0xffff0000, v5
	s_waitcnt lgkmcnt(1)
	v_pk_add_f32 v[6:7], v[6:7], v[22:23]
	v_pk_add_f32 v[8:9], v[8:9], v[2:3]
	s_waitcnt lgkmcnt(0)
	v_pk_add_f32 v[10:11], v[10:11], v[24:25]
	v_pk_add_f32 v[12:13], v[12:13], v[4:5]
	v_cvt_pk_bf16_f32 v2, v6, v7
	v_cvt_pk_bf16_f32 v3, v8, v9
	v_cvt_pk_bf16_f32 v4, v10, v11
	v_cvt_pk_bf16_f32 v5, v12, v13
	global_store_dwordx4 v[16:17], v[2:5], off
	global_load_dwordx4 v[2:5], v[20:21], off
	v_add_u32_e32 v6, 0x200, v1
	v_ashrrev_i32_e32 v26, 4, v6
	v_add_u32_e32 v6, s7, v26
	v_mad_i64_i32 v[6:7], s[8:9], v6, s6, v[14:15]
	v_mad_u64_u32 v[10:11], s[8:9], v19, s3, v[18:19]
	v_lshl_add_u64 v[6:7], v[6:7], 0, s[4:5]
	v_lshl_add_u64 v[16:17], v[6:7], 0, v[34:35]
	ds_read_b128 v[6:9], v10
	ds_read_b128 v[10:13], v10 offset:16
	v_add_u32_e32 v1, 0x300, v1
	v_ashrrev_i32_e32 v1, 4, v1
	s_waitcnt vmcnt(0)
	v_lshlrev_b32_e32 v22, 16, v2
	v_and_b32_e32 v23, 0xffff0000, v2
	v_lshlrev_b32_e32 v2, 16, v3
	v_and_b32_e32 v3, 0xffff0000, v3
	v_lshlrev_b32_e32 v24, 16, v4
	v_and_b32_e32 v25, 0xffff0000, v4
	v_lshlrev_b32_e32 v4, 16, v5
	v_and_b32_e32 v5, 0xffff0000, v5
	s_waitcnt lgkmcnt(1)
	v_pk_add_f32 v[6:7], v[6:7], v[22:23]
	v_pk_add_f32 v[8:9], v[8:9], v[2:3]
	s_waitcnt lgkmcnt(0)
	v_pk_add_f32 v[10:11], v[10:11], v[24:25]
	v_pk_add_f32 v[12:13], v[12:13], v[4:5]
	v_cvt_pk_bf16_f32 v2, v6, v7
	v_cvt_pk_bf16_f32 v3, v8, v9
	v_cvt_pk_bf16_f32 v4, v10, v11
	v_cvt_pk_bf16_f32 v5, v12, v13
	global_store_dwordx4 v[20:21], v[2:5], off
	global_load_dwordx4 v[2:5], v[16:17], off
	v_add_u32_e32 v6, s7, v1
	v_mad_i64_i32 v[6:7], s[6:7], v6, s6, v[14:15]
	v_mad_u64_u32 v[10:11], s[8:9], v26, s3, v[18:19]
	v_lshl_add_u64 v[6:7], v[6:7], 0, s[4:5]
	v_lshl_add_u64 v[14:15], v[6:7], 0, v[34:35]
	ds_read_b128 v[6:9], v10
	ds_read_b128 v[10:13], v10 offset:16
	s_waitcnt vmcnt(0)
	v_lshlrev_b32_e32 v20, 16, v2
	v_and_b32_e32 v21, 0xffff0000, v2
	v_lshlrev_b32_e32 v2, 16, v3
	v_and_b32_e32 v3, 0xffff0000, v3
	v_lshlrev_b32_e32 v22, 16, v4
	v_and_b32_e32 v23, 0xffff0000, v4
	v_lshlrev_b32_e32 v4, 16, v5
	v_and_b32_e32 v5, 0xffff0000, v5
	s_waitcnt lgkmcnt(1)
	v_pk_add_f32 v[6:7], v[6:7], v[20:21]
	v_pk_add_f32 v[8:9], v[8:9], v[2:3]
	s_waitcnt lgkmcnt(0)
	v_pk_add_f32 v[10:11], v[10:11], v[22:23]
	v_pk_add_f32 v[12:13], v[12:13], v[4:5]
	v_cvt_pk_bf16_f32 v2, v6, v7
	v_cvt_pk_bf16_f32 v3, v8, v9
	v_cvt_pk_bf16_f32 v4, v10, v11
	v_cvt_pk_bf16_f32 v5, v12, v13
	global_store_dwordx4 v[16:17], v[2:5], off
	global_load_dwordx4 v[2:5], v[14:15], off
	v_mad_u64_u32 v[10:11], s[4:5], v1, s3, v[18:19]
	ds_read_b128 v[6:9], v10
	ds_read_b128 v[10:13], v10 offset:16
	s_waitcnt vmcnt(0)
	v_lshlrev_b32_e32 v16, 16, v2
	v_and_b32_e32 v17, 0xffff0000, v2
	v_lshlrev_b32_e32 v2, 16, v3
	v_and_b32_e32 v3, 0xffff0000, v3
	v_lshlrev_b32_e32 v18, 16, v4
	v_and_b32_e32 v19, 0xffff0000, v4
	v_lshlrev_b32_e32 v4, 16, v5
	v_and_b32_e32 v5, 0xffff0000, v5
	s_waitcnt lgkmcnt(1)
	v_pk_add_f32 v[6:7], v[6:7], v[16:17]
	v_pk_add_f32 v[8:9], v[8:9], v[2:3]
	s_waitcnt lgkmcnt(0)
	v_pk_add_f32 v[10:11], v[10:11], v[18:19]
	v_pk_add_f32 v[12:13], v[12:13], v[4:5]
	v_cvt_pk_bf16_f32 v2, v6, v7
	v_cvt_pk_bf16_f32 v3, v8, v9
	v_cvt_pk_bf16_f32 v4, v10, v11
	v_cvt_pk_bf16_f32 v5, v12, v13
	global_store_dwordx4 v[14:15], v[2:5], off
	s_barrier

; #define MFMA(a, b, c) __builtin_amdgcn_mfma_f32_32x32x16_bf16((a), (b), (c), 0, 0, 0)
; template <int TM, int TN>
; DI void gemm_mainloop(const u16* __restrict__ A, long lda, const u16* __restrict__ Bt, long ldb, int K, char* smem,
;                       f32x16 (&acc)[TM][TN]) {
;     ...
;   for (int kt = 0; kt < nk; kt++) {
;     const int buf = kt & 1;
;     const u16* cA = sA + buf * BM * LD + (wm * 32 * TM + r) * LD + h * 8;
;     const u16* cB = sB + buf * BN * LD + (wn * 32 * TN + r) * LD + h * 8;
;     bf16x8 af[TM], bfr[TN];
; #pragma unroll
;     for (int tm = 0; tm < TM; tm++) af[tm] = *(const bf16x8*)(cA + tm * 32 * LD);
; #pragma unroll
;     for (int tn = 0; tn < TN; tn++) bfr[tn] = *(const bf16x8*)(cB + tn * 32 * LD);
;     if (kt + 1 < nk) GEMM_SSTORE(buf ^ 1)
;     __builtin_amdgcn_sched_barrier(0);
;     __builtin_amdgcn_s_setprio(1);
; #pragma unroll
;     for (int tm = 0; tm < TM; tm++)
; #pragma unroll
;       for (int tn = 0; tn < TN; tn++) acc[tm][tn] = MFMA(af[tm], bfr[tn], acc[tm][tn]);
; #pragma unroll
;     for (int tm = 0; tm < TM; tm++) af[tm] = *(const bf16x8*)(cA + tm * 32 * LD + 16);
; #pragma unroll
;     for (int tn = 0; tn < TN; tn++) bfr[tn] = *(const bf16x8*)(cB + tn * 32 * LD + 16);
; #pragma unroll
;     for (int tm = 0; tm < TM; tm++)
; #pragma unroll
;       for (int tn = 0; tn < TN; tn++) acc[tm][tn] = MFMA(af[tm], bfr[tn], acc[tm][tn]);
;     __builtin_amdgcn_sched_group_barrier(0x8, 4, 0);
;     if (kt + 2 < nk) GEMM_GLOAD((kt + 2) * 64)
; #pragma unroll
;     for (int ks = 2; ks < 4; ks++) {
; #pragma unroll
;       for (int tm = 0; tm < TM; tm++) af[tm] = *(const bf16x8*)(cA + tm * 32 * LD + ks * 16);
; #pragma unroll
;       for (int tn = 0; tn < TN; tn++) bfr[tn] = *(const bf16x8*)(cB + tn * 32 * LD + ks * 16);
; #pragma unroll
;       for (int tm = 0; tm < TM; tm++)
; #pragma unroll
;         for (int tn = 0; tn < TN; tn++) acc[tm][tn] = MFMA(af[tm], bfr[tn], acc[tm][tn]);
;     }
;     __builtin_amdgcn_s_setprio(0);
;     __syncthreads();
;   }
.LBB0_2832:
	s_and_b32 s19, s18, 1
	s_mul_i32 s51, s19, 0x4800
	v_add_u32_e32 v109, s51, v102
	v_add_u32_e32 v126, s51, v98
	s_lshl_b32 s19, s19, 7
	ds_read_b128 v[110:113], v109
	ds_read_b128 v[114:117], v109 offset:4608
	ds_read_b128 v[118:121], v126 offset:36864
	ds_read_b128 v[122:125], v126 offset:41472
	s_xor_b32 s19, s19, 0x80
	s_mulk_i32 s19, 0x90
	s_add_i32 s18, s18, 1
	v_add_u32_e32 v127, s19, v108
	s_waitcnt vmcnt(7)
	ds_write_b128 v127, v[70:73]
	s_waitcnt vmcnt(6)
	ds_write_b128 v127, v[74:77] offset:4608
	s_waitcnt vmcnt(5)
	ds_write_b128 v127, v[66:69] offset:9216
	s_waitcnt vmcnt(4)
	ds_write_b128 v127, v[78:81] offset:13824
	s_waitcnt vmcnt(3)
	ds_write_b128 v127, v[82:85] offset:36864
	s_waitcnt vmcnt(2)
	ds_write_b128 v127, v[86:89] offset:41472
	s_waitcnt vmcnt(1)
	ds_write_b128 v127, v[90:93] offset:46080
	s_waitcnt vmcnt(0)
	ds_write_b128 v127, v[94:97] offset:50688
	s_setprio 1
	ds_read_b128 v[66:69], v109 offset:32
	s_waitcnt lgkmcnt(10)
	v_mfma_f32_32x32x16_bf16 v[50:65], v[110:113], v[118:121], v[50:65]
	ds_read_b128 v[70:73], v126 offset:36896
	ds_read_b128 v[74:77], v126 offset:41504
	ds_read_b128 v[86:89], v109 offset:4672
	ds_read_b128 v[78:81], v126 offset:36928
	v_lshl_add_u64 v[90:91], v[106:107], 0, s[0:1]
	ds_read_b128 v[82:85], v126 offset:41536
	ds_read_b128 v[94:97], v126 offset:36960
	s_waitcnt lgkmcnt(14)
	v_mfma_f32_32x32x16_bf16 v[34:49], v[110:113], v[122:125], v[34:49]
	ds_read_b128 v[110:113], v126 offset:41568
	s_waitcnt lgkmcnt(6)
	v_mfma_f32_32x32x16_bf16 v[50:65], v[66:69], v[70:73], v[50:65]
	s_waitcnt lgkmcnt(5)
	v_mfma_f32_32x32x16_bf16 v[34:49], v[66:69], v[74:77], v[34:49]
	ds_read_b128 v[66:69], v109 offset:4640
	v_mfma_f32_32x32x16_bf16 v[18:33], v[114:117], v[118:121], v[18:33]
	v_lshl_add_u64 v[118:119], v[104:105], 0, s[0:1]
	v_mfma_f32_32x32x16_bf16 v[2:17], v[114:117], v[122:125], v[2:17]
	ds_read_b128 v[114:117], v109 offset:4704
	s_waitcnt lgkmcnt(1)
	v_mfma_f32_32x32x16_bf16 v[18:33], v[66:69], v[70:73], v[18:33]
	v_add_co_u32_e32 v70, vcc, s37, v90
	s_nop 1
	v_addc_co_u32_e32 v71, vcc, 0, v91, vcc
	global_load_dwordx4 v[70:73], v[70:71], off offset:2304
	v_mfma_f32_32x32x16_bf16 v[2:17], v[66:69], v[74:77], v[2:17]
	ds_read_b128 v[66:69], v109 offset:64
	v_add_co_u32_e32 v74, vcc, s38, v90
	s_nop 1
	v_addc_co_u32_e32 v75, vcc, 0, v91, vcc
	global_load_dwordx4 v[74:77], v[74:75], off offset:2304
	s_waitcnt lgkmcnt(0)
	v_mfma_f32_32x32x16_bf16 v[50:65], v[66:69], v[78:81], v[50:65]
	v_mfma_f32_32x32x16_bf16 v[34:49], v[66:69], v[82:85], v[34:49]
	v_add_co_u32_e32 v66, vcc, s39, v90
	s_nop 1
	v_addc_co_u32_e32 v67, vcc, 0, v91, vcc
	global_load_dwordx4 v[66:69], v[66:67], off offset:2304
	v_mfma_f32_32x32x16_bf16 v[18:33], v[86:89], v[78:81], v[18:33]
	v_add_co_u32_e32 v78, vcc, s40, v90
	s_nop 1
	v_addc_co_u32_e32 v79, vcc, 0, v91, vcc
	ds_read_b128 v[90:93], v109 offset:96
	global_load_dwordx4 v[78:81], v[78:79], off offset:2304
	v_mfma_f32_32x32x16_bf16 v[2:17], v[86:89], v[82:85], v[2:17]
	v_add_co_u32_e32 v82, vcc, s41, v118
	s_nop 1
	v_addc_co_u32_e32 v83, vcc, 0, v119, vcc
	v_add_co_u32_e32 v86, vcc, s42, v118
	global_load_dwordx4 v[82:85], v[82:83], off offset:256
	s_nop 0
	v_addc_co_u32_e32 v87, vcc, 0, v119, vcc
	v_add_co_u32_e32 v120, vcc, s43, v118
	s_waitcnt lgkmcnt(0)
	v_mfma_f32_32x32x16_bf16 v[50:65], v[90:93], v[94:97], v[50:65]
	v_addc_co_u32_e32 v121, vcc, 0, v119, vcc
	v_add_co_u32_e32 v118, vcc, s44, v118
	global_load_dwordx4 v[86:89], v[86:87], off offset:256
	s_nop 0
	v_addc_co_u32_e32 v119, vcc, 0, v119, vcc
	v_mfma_f32_32x32x16_bf16 v[34:49], v[90:93], v[110:113], v[34:49]
	global_load_dwordx4 v[90:93], v[120:121], off offset:256
	v_mfma_f32_32x32x16_bf16 v[18:33], v[114:117], v[94:97], v[18:33]
	global_load_dwordx4 v[94:97], v[118:119], off offset:256
	v_mfma_f32_32x32x16_bf16 v[2:17], v[114:117], v[110:113], v[2:17]
	s_setprio 0
	s_add_u32 s0, s0, 0x80
	s_addc_u32 s1, s1, 0
	s_cmpk_eq_i32 s0, 0x1f00
	s_barrier
	s_cbranch_scc0 .LBB0_2832
	ds_read_b128 v[104:107], v102
	ds_read_b128 v[110:113], v102 offset:4608
	ds_read_b128 v[114:117], v98 offset:36864
	ds_read_b128 v[118:121], v98 offset:41472
	s_waitcnt vmcnt(7)
	ds_write_b128 v108, v[70:73] offset:18432
	s_waitcnt vmcnt(6)
	ds_write_b128 v108, v[74:77] offset:23040
	s_waitcnt vmcnt(5)
	ds_write_b128 v108, v[66:69] offset:27648
	s_waitcnt vmcnt(4)
	ds_write_b128 v108, v[78:81] offset:32256
	s_waitcnt vmcnt(3)
	ds_write_b128 v108, v[82:85] offset:55296
	s_waitcnt vmcnt(2)
	ds_write_b128 v108, v[86:89] offset:59904
	s_waitcnt vmcnt(1)
	ds_write_b128 v108, v[90:93] offset:64512
	s_waitcnt vmcnt(0)
	ds_write_b128 v103, v[94:97] offset:32256
	s_setprio 1
	ds_read_b128 v[66:69], v102 offset:32
	s_waitcnt lgkmcnt(10)
	v_mfma_f32_32x32x16_bf16 v[50:65], v[104:107], v[114:117], v[50:65]
	ds_read_b128 v[70:73], v98 offset:36896
	ds_read_b128 v[74:77], v98 offset:41504
	s_waitcnt lgkmcnt(11)
	v_mfma_f32_32x32x16_bf16 v[34:49], v[104:107], v[118:121], v[34:49]
	s_waitcnt lgkmcnt(1)
	v_mfma_f32_32x32x16_bf16 v[50:65], v[66:69], v[70:73], v[50:65]
	s_waitcnt lgkmcnt(0)
	v_mfma_f32_32x32x16_bf16 v[34:49], v[66:69], v[74:77], v[34:49]
	ds_read_b128 v[66:69], v102 offset:4640
	v_mfma_f32_32x32x16_bf16 v[18:33], v[110:113], v[114:117], v[18:33]
	v_mfma_f32_32x32x16_bf16 v[2:17], v[110:113], v[118:121], v[2:17]
	s_waitcnt lgkmcnt(0)
	v_mfma_f32_32x32x16_bf16 v[18:33], v[66:69], v[70:73], v[18:33]
	ds_read_b128 v[70:73], v98 offset:36928
	v_mfma_f32_32x32x16_bf16 v[2:17], v[66:69], v[74:77], v[2:17]
	ds_read_b128 v[66:69], v102 offset:64
	ds_read_b128 v[74:77], v98 offset:41536
	s_waitcnt lgkmcnt(1)
	v_mfma_f32_32x32x16_bf16 v[50:65], v[66:69], v[70:73], v[50:65]
	s_waitcnt lgkmcnt(0)
	v_mfma_f32_32x32x16_bf16 v[34:49], v[66:69], v[74:77], v[34:49]
	ds_read_b128 v[66:69], v102 offset:4672
	s_waitcnt lgkmcnt(0)
	v_mfma_f32_32x32x16_bf16 v[18:33], v[66:69], v[70:73], v[18:33]
	ds_read_b128 v[70:73], v98 offset:36960
	v_mfma_f32_32x32x16_bf16 v[2:17], v[66:69], v[74:77], v[2:17]
	ds_read_b128 v[66:69], v102 offset:96
	ds_read_b128 v[74:77], v98 offset:41568
	s_waitcnt lgkmcnt(1)
	v_mfma_f32_32x32x16_bf16 v[50:65], v[66:69], v[70:73], v[50:65]
	s_waitcnt lgkmcnt(0)
	v_mfma_f32_32x32x16_bf16 v[34:49], v[66:69], v[74:77], v[34:49]
	ds_read_b128 v[66:69], v102 offset:4704
	s_waitcnt lgkmcnt(0)
	v_mfma_f32_32x32x16_bf16 v[2:17], v[66:69], v[74:77], v[2:17]
	v_mfma_f32_32x32x16_bf16 v[18:33], v[66:69], v[70:73], v[18:33]
	s_setprio 0
	s_barrier
; DI int crow(int i, int h) { return (i & 3) + 8 * (i >> 2) + 4 * h; }
; template <int TM, int TN, class Epi>
; DI void gemm_tile(const u16* A, long lda, const u16* Bt, long ldb, int K, int m0, int n0, char* smem, const Epi& epi) {
;     ...
; #pragma unroll
;   for (int tm = 0; tm < TM; tm++)
; #pragma unroll
;     for (int tn = 0; tn < TN; tn++)
; #pragma unroll
;       for (int i = 0; i < 16; i++)
;         Ct[(wm * 32 * TM + tm * 32 + crow(i, h)) * LDC + wn * 32 * TN + tn * 32 + r] = acc[tm][tn][i];
;   __syncthreads();
;   DI void operator()(const float* Ct, int ldc, int m0, int n0, int tid, int bm) const {
;     ...
;     for (int it = 0; it < bm / 16; it++) {
;       int id = tid + 256 * it; int row = id >> 4, c8 = (id & 15) * 8;
;       int m = m0 + row;
;       const float* c = Ct + row * ldc + c8;
;       float4 a = *(const float4*)c, b = *(const float4*)(c + 4);
;       float x[8];
;       if (srcb != nullptr) {
;         unpack8(*(const uint4*)(srcb + (size_t)m * LDA + n0 + c8), x);
	ds_read_b128 v[66:69], v102 offset:18432
	ds_read_b128 v[70:73], v102 offset:23040
	ds_read_b128 v[74:77], v98 offset:55296
	ds_read_b128 v[78:81], v98 offset:59904
	s_setprio 1
	s_waitcnt lgkmcnt(1)
	v_mfma_f32_32x32x16_bf16 v[50:65], v[66:69], v[74:77], v[50:65]
	s_waitcnt lgkmcnt(0)
	v_mfma_f32_32x32x16_bf16 v[34:49], v[66:69], v[78:81], v[34:49]
	ds_read_b128 v[66:69], v102 offset:18464
	v_mfma_f32_32x32x16_bf16 v[18:33], v[70:73], v[74:77], v[18:33]
	ds_read_b128 v[74:77], v98 offset:59936
	v_mfma_f32_32x32x16_bf16 v[2:17], v[70:73], v[78:81], v[2:17]
	ds_read_b128 v[70:73], v98 offset:55328
	s_waitcnt lgkmcnt(0)
	v_mfma_f32_32x32x16_bf16 v[50:65], v[66:69], v[70:73], v[50:65]
	v_mfma_f32_32x32x16_bf16 v[34:49], v[66:69], v[74:77], v[34:49]
	ds_read_b128 v[66:69], v102 offset:23072
	s_waitcnt lgkmcnt(0)
	v_mfma_f32_32x32x16_bf16 v[18:33], v[66:69], v[70:73], v[18:33]
	ds_read_b128 v[70:73], v98 offset:55360
	v_mfma_f32_32x32x16_bf16 v[2:17], v[66:69], v[74:77], v[2:17]
	ds_read_b128 v[66:69], v102 offset:18496
	ds_read_b128 v[74:77], v98 offset:59968
	s_waitcnt lgkmcnt(1)
	v_mfma_f32_32x32x16_bf16 v[50:65], v[66:69], v[70:73], v[50:65]
	s_waitcnt lgkmcnt(0)
	v_mfma_f32_32x32x16_bf16 v[34:49], v[66:69], v[74:77], v[34:49]
	ds_read_b128 v[66:69], v102 offset:23104
	s_waitcnt lgkmcnt(0)
	v_mfma_f32_32x32x16_bf16 v[18:33], v[66:69], v[70:73], v[18:33]
	ds_read_b128 v[70:73], v98 offset:55392
	v_mfma_f32_32x32x16_bf16 v[2:17], v[66:69], v[74:77], v[2:17]
	ds_read_b128 v[66:69], v102 offset:18528
	ds_read_b128 v[74:77], v98 offset:60000
	s_waitcnt lgkmcnt(1)
	v_mfma_f32_32x32x16_bf16 v[50:65], v[66:69], v[70:73], v[50:65]
	s_waitcnt lgkmcnt(0)
	v_mfma_f32_32x32x16_bf16 v[34:49], v[66:69], v[74:77], v[34:49]
	ds_read_b128 v[66:69], v102 offset:23136
	s_waitcnt lgkmcnt(0)
	v_mfma_f32_32x32x16_bf16 v[2:17], v[66:69], v[74:77], v[2:17]
	v_mfma_f32_32x32x16_bf16 v[18:33], v[66:69], v[70:73], v[18:33]
	s_setprio 0
	v_mov_b32_e32 v66, v0
	s_barrier
	s_mov_b32 s51, 0
	v_lshrrev_b32_e32 v67, 1, v66
	v_and_b32_e32 v67, 0xfffffc0, v67
	v_lshrrev_b32_e32 v68, 3, v66
	v_and_or_b32 v67, v68, 4, v67
	v_and_b32_e32 v68, 0x5f, v66
	v_mul_lo_u32 v67, v67, s45
	v_lshl_add_u32 v67, v68, 2, v67
	ds_write2_b32 v67, v50, v34 offset1:32
	v_add_u32_e32 v34, 0x400, v67
	ds_write2_b32 v34, v52, v36 offset0:8 offset1:40
	ds_write2_b32 v34, v53, v37 offset0:140 offset1:172
	v_add_u32_e32 v34, 0x1000, v67
	ds_write2_b32 v34, v54, v38 offset0:32 offset1:64
	ds_write2_b32 v34, v55, v39 offset0:164 offset1:196
	v_add_u32_e32 v34, 0x1400, v67
	ds_write2_b32 v34, v56, v40 offset0:40 offset1:72
	ds_write2_b32 v34, v57, v41 offset0:172 offset1:204
	v_add_u32_e32 v34, 0x2000, v67
	ds_write2_b32 v34, v58, v42 offset0:64 offset1:96
	ds_write2_b32 v34, v59, v43 offset0:196 offset1:228
	v_add_u32_e32 v34, 0x2400, v67
	ds_write2_b32 v34, v60, v44 offset0:72 offset1:104
	ds_write2_b32 v34, v61, v45 offset0:204 offset1:236
	v_add_u32_e32 v34, 0x3000, v67
	ds_write2_b32 v34, v62, v46 offset0:96 offset1:128
	v_add_u32_e32 v34, 0x3200, v67
	ds_write2_b32 v34, v63, v47 offset0:100 offset1:132
	v_add_u32_e32 v34, 0x3400, v67
	ds_write2_b32 v34, v64, v48 offset0:104 offset1:136
	v_add_u32_e32 v34, 0x3600, v67
	ds_write2_b32 v34, v65, v49 offset0:108 offset1:140
	v_add_u32_e32 v34, 0x4000, v67
	ds_write2_b32 v34, v18, v2 offset0:128 offset1:160
	v_add_u32_e32 v2, 0x4400, v67
	ds_write2_b32 v2, v19, v3 offset0:4 offset1:36
	ds_write2_b32 v2, v20, v4 offset0:136 offset1:168
	v_add_u32_e32 v2, 0x4800, v67
	ds_write2_b32 v2, v21, v5 offset0:12 offset1:44
	v_add_u32_e32 v2, 0x5000, v67
	ds_write2_b32 v2, v22, v6 offset0:160 offset1:192
	v_add_u32_e32 v2, 0x5400, v67
	ds_write2_b32 v2, v23, v7 offset0:36 offset1:68
	ds_write2_b32 v2, v24, v8 offset0:168 offset1:200
	v_add_u32_e32 v2, 0x5800, v67
	ds_write2_b32 v2, v25, v9 offset0:44 offset1:76
	v_add_u32_e32 v2, 0x6000, v67
	ds_write2_b32 v2, v26, v10 offset0:192 offset1:224
	v_add_u32_e32 v2, 0x6400, v67
	ds_write2_b32 v2, v27, v11 offset0:68 offset1:100
	ds_write2_b32 v2, v28, v12 offset0:200 offset1:232
	v_add_u32_e32 v2, 0x6800, v67
	ds_write2_b32 v2, v29, v13 offset0:76 offset1:108
	v_add_u32_e32 v2, 0x7200, v67
	ds_write2_b32 v2, v30, v14 offset0:96 offset1:128
	v_add_u32_e32 v2, 0x7400, v67
	ds_write2_b32 v2, v31, v15 offset0:100 offset1:132
	v_add_u32_e32 v2, 0x7600, v67
	ds_write2_b32 v2, v32, v16 offset0:104 offset1:136
	v_add_u32_e32 v2, 0x7800, v67
	ds_write2_b32 v2, v33, v17 offset0:108 offset1:140
	v_lshlrev_b32_e32 v2, 3, v66
	v_and_b32_e32 v2, 0x78, v2
	v_lshlrev_b32_e32 v10, 2, v2
	v_lshlrev_b32_e32 v98, 1, v2
	v_mov_b32_e32 v11, v99
	v_lshl_add_u64 v[12:13], s[10:11], 0, v[98:99]
	v_lshl_add_u64 v[14:15], s[14:15], 0, v[10:11]
	ds_write2_b32 v67, v51, v35 offset0:132 offset1:164
	v_ashrrev_i32_e32 v190, 4, v66
	v_add_u32_e32 v190, s50, v190
	v_add_u32_e32 v191, 0, v190
	v_mad_i64_i32 v[192:193], vcc, v191, s48, v[12:13]
	global_load_dwordx4 v[150:153], v[192:193], off
	v_add_u32_e32 v191, 16, v190
	v_mad_i64_i32 v[192:193], vcc, v191, s48, v[12:13]
	global_load_dwordx4 v[154:157], v[192:193], off
	v_add_u32_e32 v191, 32, v190
	v_mad_i64_i32 v[192:193], vcc, v191, s48, v[12:13]
	global_load_dwordx4 v[158:161], v[192:193], off
	v_add_u32_e32 v191, 48, v190
	v_mad_i64_i32 v[192:193], vcc, v191, s48, v[12:13]
	global_load_dwordx4 v[162:165], v[192:193], off
	v_add_u32_e32 v191, 64, v190
	v_mad_i64_i32 v[192:193], vcc, v191, s48, v[12:13]
	global_load_dwordx4 v[166:169], v[192:193], off
	v_add_u32_e32 v191, 80, v190
	v_mad_i64_i32 v[192:193], vcc, v191, s48, v[12:13]
	global_load_dwordx4 v[170:173], v[192:193], off
	v_add_u32_e32 v191, 96, v190
	v_mad_i64_i32 v[192:193], vcc, v191, s48, v[12:13]
	global_load_dwordx4 v[174:177], v[192:193], off
	v_add_u32_e32 v191, 112, v190
	v_mad_i64_i32 v[192:193], vcc, v191, s48, v[12:13]
	global_load_dwordx4 v[178:181], v[192:193], off
	s_waitcnt lgkmcnt(0)
	s_barrier
	s_branch .LBB0_2835
